# v13o plus loader segments of the 10 GEMM K loops reordered: loop-invariant-address LDS fragment reads issued first after the barrier, address math and LDS-DMA issue after
# speedup vs baseline: 1.0014x; 1.0014x over previous
.Lsp_skip0:
.LBB0_233:
	ds_read_b128 v[162:165], v155
	ds_read_b128 v[166:169], v155 offset:1024
	ds_read_b128 v[170:173], v155 offset:2048
	ds_read_b128 v[174:177], v155 offset:3072
	ds_read_b128 v[178:181], v158
	ds_read_b128 v[182:185], v158 offset:1024
	ds_read_b128 v[186:189], v158 offset:2048
	ds_read_b128 v[190:193], v158 offset:3072
	ds_read_b128 v[194:197], v159
	ds_read_b128 v[198:201], v159 offset:1024
	ds_read_b128 v[202:205], v159 offset:2048
	ds_read_b128 v[206:209], v159 offset:3072
	ds_read_b128 v[210:213], v159 offset:4096
	ds_read_b128 v[214:217], v159 offset:5120
	ds_read_b128 v[218:221], v159 offset:6144
	ds_read_b128 v[222:225], v159 offset:7168
	s_add_u32 s36, s34, 0xfff00080
	s_addc_u32 s37, s35, -1
	s_cmp_eq_u32 s68, 60
	s_cselect_b32 s39, s25, s37
	s_cselect_b32 s38, s64, s36
	s_cselect_b32 s37, s23, s67
	s_cselect_b32 s36, s65, s66
	v_lshl_add_u64 v[144:145], s[34:35], 0, v[138:139]
	s_add_i32 m0, s31, 0xc000
	s_nop 0
	global_load_lds_dwordx4 v[144:145], off
	v_lshl_add_u64 v[144:145], s[34:35], 0, v[136:137]
	s_add_i32 m0, s31, 0xe000
	s_nop 0
	global_load_lds_dwordx4 v[144:145], off
	s_waitcnt vmcnt(8)
	s_waitcnt lgkmcnt(0)
	s_barrier
	s_waitcnt lgkmcnt(0)
	v_mfma_f32_16x16x32_bf16 v[124:127], v[162:165], v[194:197], v[124:127]
	v_mfma_f32_16x16x32_bf16 v[120:123], v[170:173], v[194:197], v[120:123]
	v_mfma_f32_16x16x32_bf16 v[108:111], v[162:165], v[202:205], v[108:111]
	v_mfma_f32_16x16x32_bf16 v[104:107], v[170:173], v[202:205], v[104:107]
	v_mfma_f32_16x16x32_bf16 v[92:95], v[162:165], v[210:213], v[92:95]
	v_mfma_f32_16x16x32_bf16 v[88:91], v[170:173], v[210:213], v[88:91]
	v_mfma_f32_16x16x32_bf16 v[76:79], v[162:165], v[218:221], v[76:79]
	v_mfma_f32_16x16x32_bf16 v[72:75], v[170:173], v[218:221], v[72:75]
	v_mfma_f32_16x16x32_bf16 v[124:127], v[166:169], v[198:201], v[124:127]
	v_mfma_f32_16x16x32_bf16 v[120:123], v[174:177], v[198:201], v[120:123]
	v_mfma_f32_16x16x32_bf16 v[108:111], v[166:169], v[206:209], v[108:111]
	v_mfma_f32_16x16x32_bf16 v[104:107], v[174:177], v[206:209], v[104:107]
	v_mfma_f32_16x16x32_bf16 v[92:95], v[166:169], v[214:217], v[92:95]
	v_mfma_f32_16x16x32_bf16 v[88:91], v[174:177], v[214:217], v[88:91]
	v_mfma_f32_16x16x32_bf16 v[76:79], v[166:169], v[222:225], v[76:79]
	v_mfma_f32_16x16x32_bf16 v[72:75], v[174:177], v[222:225], v[72:75]
	v_mfma_f32_16x16x32_bf16 v[116:119], v[178:181], v[194:197], v[116:119]
	v_mfma_f32_16x16x32_bf16 v[112:115], v[186:189], v[194:197], v[112:115]
	v_mfma_f32_16x16x32_bf16 v[100:103], v[178:181], v[202:205], v[100:103]
	v_mfma_f32_16x16x32_bf16 v[96:99], v[186:189], v[202:205], v[96:99]
	v_mfma_f32_16x16x32_bf16 v[84:87], v[178:181], v[210:213], v[84:87]
	v_mfma_f32_16x16x32_bf16 v[80:83], v[186:189], v[210:213], v[80:83]
	v_mfma_f32_16x16x32_bf16 v[68:71], v[178:181], v[218:221], v[68:71]
	v_mfma_f32_16x16x32_bf16 v[64:67], v[186:189], v[218:221], v[64:67]
	v_mfma_f32_16x16x32_bf16 v[116:119], v[182:185], v[198:201], v[116:119]
	v_mfma_f32_16x16x32_bf16 v[112:115], v[190:193], v[198:201], v[112:115]
	v_mfma_f32_16x16x32_bf16 v[100:103], v[182:185], v[206:209], v[100:103]
	v_mfma_f32_16x16x32_bf16 v[96:99], v[190:193], v[206:209], v[96:99]
	v_mfma_f32_16x16x32_bf16 v[84:87], v[182:185], v[214:217], v[84:87]
	v_mfma_f32_16x16x32_bf16 v[80:83], v[190:193], v[214:217], v[80:83]
	v_mfma_f32_16x16x32_bf16 v[68:71], v[182:185], v[222:225], v[68:71]
	v_mfma_f32_16x16x32_bf16 v[64:67], v[190:193], v[222:225], v[64:67]
	s_barrier
	ds_read_b128 v[194:197], v159 offset:16384
	ds_read_b128 v[198:201], v159 offset:17408
	ds_read_b128 v[202:205], v159 offset:18432
	ds_read_b128 v[206:209], v159 offset:19456
	ds_read_b128 v[210:213], v159 offset:20480
	ds_read_b128 v[214:217], v159 offset:21504
	ds_read_b128 v[218:221], v159 offset:22528
	ds_read_b128 v[222:225], v159 offset:23552
	s_add_i32 s69, s57, s40
	v_lshl_add_u64 v[144:145], s[36:37], 0, v[130:131]
	s_mov_b32 m0, s69
	s_nop 0
	global_load_lds_dwordx4 v[144:145], off
	s_add_i32 m0, s69, 0x2000
	s_add_u32 s70, s36, 0x100000
	v_lshl_add_u64 v[150:151], s[36:37], 0, v[134:135]
	s_addc_u32 s71, s37, 0
	s_add_i32 s69, s58, s40
	global_load_lds_dwordx4 v[150:151], off
	v_lshl_add_u64 v[156:157], s[70:71], 0, v[130:131]
	s_mov_b32 m0, s69
	v_lshl_add_u64 v[226:227], s[38:39], 0, v[132:133]
	global_load_lds_dwordx4 v[156:157], off
	v_lshl_add_u64 v[156:157], s[70:71], 0, v[134:135]
	s_add_i32 m0, s69, 0x2000
	s_nop 0
	global_load_lds_dwordx4 v[156:157], off
	v_lshl_add_u64 v[156:157], s[38:39], 0, v[128:129]
	s_mov_b32 m0, s31
	s_nop 0
	global_load_lds_dwordx4 v[156:157], off
	s_mov_b32 m0, s50
	s_nop 0
	global_load_lds_dwordx4 v[226:227], off
	s_waitcnt vmcnt(8)
	s_waitcnt lgkmcnt(0)
	s_barrier
	s_waitcnt lgkmcnt(0)
	v_mfma_f32_16x16x32_bf16 v[60:63], v[162:165], v[194:197], v[60:63]
	v_mfma_f32_16x16x32_bf16 v[56:59], v[170:173], v[194:197], v[56:59]
	v_mfma_f32_16x16x32_bf16 v[48:51], v[162:165], v[202:205], v[48:51]
	v_mfma_f32_16x16x32_bf16 v[40:43], v[170:173], v[202:205], v[40:43]
	v_mfma_f32_16x16x32_bf16 v[32:35], v[162:165], v[210:213], v[32:35]
	v_mfma_f32_16x16x32_bf16 v[24:27], v[170:173], v[210:213], v[24:27]
	v_mfma_f32_16x16x32_bf16 v[16:19], v[162:165], v[218:221], v[16:19]
	v_mfma_f32_16x16x32_bf16 v[8:11], v[170:173], v[218:221], v[8:11]
	v_mfma_f32_16x16x32_bf16 v[60:63], v[166:169], v[198:201], v[60:63]
	v_mfma_f32_16x16x32_bf16 v[56:59], v[174:177], v[198:201], v[56:59]
	v_mfma_f32_16x16x32_bf16 v[48:51], v[166:169], v[206:209], v[48:51]
	v_mfma_f32_16x16x32_bf16 v[40:43], v[174:177], v[206:209], v[40:43]
	v_mfma_f32_16x16x32_bf16 v[32:35], v[166:169], v[214:217], v[32:35]
	v_mfma_f32_16x16x32_bf16 v[24:27], v[174:177], v[214:217], v[24:27]
	v_mfma_f32_16x16x32_bf16 v[16:19], v[166:169], v[222:225], v[16:19]
	v_mfma_f32_16x16x32_bf16 v[8:11], v[174:177], v[222:225], v[8:11]
	v_mfma_f32_16x16x32_bf16 v[52:55], v[178:181], v[194:197], v[52:55]
	v_mfma_f32_16x16x32_bf16 v[44:47], v[186:189], v[194:197], v[44:47]
	v_mfma_f32_16x16x32_bf16 v[36:39], v[178:181], v[202:205], v[36:39]
	v_mfma_f32_16x16x32_bf16 v[28:31], v[186:189], v[202:205], v[28:31]
	v_mfma_f32_16x16x32_bf16 v[20:23], v[178:181], v[210:213], v[20:23]
	v_mfma_f32_16x16x32_bf16 v[12:15], v[186:189], v[210:213], v[12:15]
	v_mfma_f32_16x16x32_bf16 v[4:7], v[178:181], v[218:221], v[4:7]
	v_mfma_f32_16x16x32_bf16 v[0:3], v[186:189], v[218:221], v[0:3]
	v_mfma_f32_16x16x32_bf16 v[52:55], v[182:185], v[198:201], v[52:55]
	v_mfma_f32_16x16x32_bf16 v[44:47], v[190:193], v[198:201], v[44:47]
	v_mfma_f32_16x16x32_bf16 v[36:39], v[182:185], v[206:209], v[36:39]
	v_mfma_f32_16x16x32_bf16 v[28:31], v[190:193], v[206:209], v[28:31]
	v_mfma_f32_16x16x32_bf16 v[20:23], v[182:185], v[214:217], v[20:23]
	v_mfma_f32_16x16x32_bf16 v[12:15], v[190:193], v[214:217], v[12:15]
	v_mfma_f32_16x16x32_bf16 v[4:7], v[182:185], v[222:225], v[4:7]
	v_mfma_f32_16x16x32_bf16 v[0:3], v[190:193], v[222:225], v[0:3]
	s_barrier
	ds_read_b128 v[194:197], v159 offset:32768
	ds_read_b128 v[198:201], v159 offset:33792
	ds_read_b128 v[202:205], v159 offset:34816
	ds_read_b128 v[206:209], v159 offset:35840
	ds_read_b128 v[210:213], v159 offset:36864
	ds_read_b128 v[214:217], v159 offset:37888
	ds_read_b128 v[218:221], v159 offset:38912
	ds_read_b128 v[222:225], v159 offset:39936
	s_add_i32 s69, 0, 0x18000
	v_add_u32_e32 v146, s69, v149
	s_add_i32 s70, 0, 0x1c000
	ds_read_b128 v[162:165], v146
	ds_read_b128 v[166:169], v146 offset:1024
	ds_read_b128 v[170:173], v146 offset:2048
	ds_read_b128 v[174:177], v146 offset:3072
	v_add_u32_e32 v146, s70, v149
	ds_read_b128 v[178:181], v146
	ds_read_b128 v[182:185], v146 offset:1024
	ds_read_b128 v[186:189], v146 offset:2048
	ds_read_b128 v[190:193], v146 offset:3072
	s_add_u32 s38, s38, 0x100000
	s_addc_u32 s39, s39, 0
	s_mov_b32 m0, s51
	v_lshl_add_u64 v[228:229], s[38:39], 0, v[128:129]
	global_load_lds_dwordx4 v[228:229], off
	v_lshl_add_u64 v[228:229], s[38:39], 0, v[132:133]
	s_mov_b32 m0, s52
	s_nop 0
	global_load_lds_dwordx4 v[228:229], off
	s_waitcnt vmcnt(8)
	s_waitcnt lgkmcnt(0)
	s_barrier
	s_waitcnt lgkmcnt(0)
	v_mfma_f32_16x16x32_bf16 v[124:127], v[162:165], v[194:197], v[124:127]
	v_mfma_f32_16x16x32_bf16 v[120:123], v[170:173], v[194:197], v[120:123]
	v_mfma_f32_16x16x32_bf16 v[108:111], v[162:165], v[202:205], v[108:111]
	v_mfma_f32_16x16x32_bf16 v[104:107], v[170:173], v[202:205], v[104:107]
	v_mfma_f32_16x16x32_bf16 v[92:95], v[162:165], v[210:213], v[92:95]
	v_mfma_f32_16x16x32_bf16 v[88:91], v[170:173], v[210:213], v[88:91]
	v_mfma_f32_16x16x32_bf16 v[76:79], v[162:165], v[218:221], v[76:79]
	v_mfma_f32_16x16x32_bf16 v[72:75], v[170:173], v[218:221], v[72:75]
	v_mfma_f32_16x16x32_bf16 v[124:127], v[166:169], v[198:201], v[124:127]
	v_mfma_f32_16x16x32_bf16 v[120:123], v[174:177], v[198:201], v[120:123]
	v_mfma_f32_16x16x32_bf16 v[108:111], v[166:169], v[206:209], v[108:111]
	v_mfma_f32_16x16x32_bf16 v[104:107], v[174:177], v[206:209], v[104:107]
	v_mfma_f32_16x16x32_bf16 v[92:95], v[166:169], v[214:217], v[92:95]
	v_mfma_f32_16x16x32_bf16 v[88:91], v[174:177], v[214:217], v[88:91]
	v_mfma_f32_16x16x32_bf16 v[76:79], v[166:169], v[222:225], v[76:79]
	v_mfma_f32_16x16x32_bf16 v[72:75], v[174:177], v[222:225], v[72:75]
	v_mfma_f32_16x16x32_bf16 v[116:119], v[178:181], v[194:197], v[116:119]
	v_mfma_f32_16x16x32_bf16 v[112:115], v[186:189], v[194:197], v[112:115]
	v_mfma_f32_16x16x32_bf16 v[100:103], v[178:181], v[202:205], v[100:103]
	v_mfma_f32_16x16x32_bf16 v[96:99], v[186:189], v[202:205], v[96:99]
	v_mfma_f32_16x16x32_bf16 v[84:87], v[178:181], v[210:213], v[84:87]
	v_mfma_f32_16x16x32_bf16 v[80:83], v[186:189], v[210:213], v[80:83]
	v_mfma_f32_16x16x32_bf16 v[68:71], v[178:181], v[218:221], v[68:71]
	v_mfma_f32_16x16x32_bf16 v[64:67], v[186:189], v[218:221], v[64:67]
	v_mfma_f32_16x16x32_bf16 v[116:119], v[182:185], v[198:201], v[116:119]
	v_mfma_f32_16x16x32_bf16 v[112:115], v[190:193], v[198:201], v[112:115]
	v_mfma_f32_16x16x32_bf16 v[100:103], v[182:185], v[206:209], v[100:103]
	v_mfma_f32_16x16x32_bf16 v[96:99], v[190:193], v[206:209], v[96:99]
	v_mfma_f32_16x16x32_bf16 v[84:87], v[182:185], v[214:217], v[84:87]
	v_mfma_f32_16x16x32_bf16 v[80:83], v[190:193], v[214:217], v[80:83]
	v_mfma_f32_16x16x32_bf16 v[68:71], v[182:185], v[222:225], v[68:71]
	v_mfma_f32_16x16x32_bf16 v[64:67], v[190:193], v[222:225], v[64:67]
	s_barrier
	ds_read_b128 v[194:197], v159 offset:49152
	ds_read_b128 v[198:201], v159 offset:50176
	ds_read_b128 v[202:205], v159 offset:51200
	ds_read_b128 v[206:209], v159 offset:52224
	ds_read_b128 v[210:213], v159 offset:53248
	ds_read_b128 v[214:217], v159 offset:54272
	ds_read_b128 v[218:221], v159 offset:55296
	ds_read_b128 v[222:225], v159 offset:56320
	s_add_i32 s38, s69, s40
	v_lshl_add_u64 v[144:145], v[144:145], 0, s[12:13]
	s_mov_b32 m0, s38
	s_nop 0
	global_load_lds_dwordx4 v[144:145], off
	s_add_i32 m0, s38, 0x2000
	s_add_u32 s36, s36, 0x100080
	v_lshl_add_u64 v[144:145], v[150:151], 0, s[12:13]
	s_addc_u32 s37, s37, 0
	s_add_i32 s38, s70, s40
	global_load_lds_dwordx4 v[144:145], off
	v_lshl_add_u64 v[144:145], s[36:37], 0, v[130:131]
	s_mov_b32 m0, s38
	s_nop 0
	global_load_lds_dwordx4 v[144:145], off
	v_lshl_add_u64 v[144:145], s[36:37], 0, v[134:135]
	s_add_i32 m0, s38, 0x2000
	s_nop 0
	global_load_lds_dwordx4 v[144:145], off
	v_lshl_add_u64 v[144:145], v[156:157], 0, s[12:13]
	s_mov_b32 m0, s54
	s_nop 0
	global_load_lds_dwordx4 v[144:145], off
	v_lshl_add_u64 v[144:145], v[226:227], 0, s[12:13]
	s_mov_b32 m0, s55
	s_nop 0
	global_load_lds_dwordx4 v[144:145], off
	s_waitcnt vmcnt(8)
	s_waitcnt lgkmcnt(0)
	s_barrier
	s_waitcnt lgkmcnt(0)
	v_mfma_f32_16x16x32_bf16 v[60:63], v[162:165], v[194:197], v[60:63]
	v_mfma_f32_16x16x32_bf16 v[56:59], v[170:173], v[194:197], v[56:59]
	v_mfma_f32_16x16x32_bf16 v[48:51], v[162:165], v[202:205], v[48:51]
	v_mfma_f32_16x16x32_bf16 v[40:43], v[170:173], v[202:205], v[40:43]
	v_mfma_f32_16x16x32_bf16 v[32:35], v[162:165], v[210:213], v[32:35]
	v_mfma_f32_16x16x32_bf16 v[24:27], v[170:173], v[210:213], v[24:27]
	v_mfma_f32_16x16x32_bf16 v[16:19], v[162:165], v[218:221], v[16:19]
	v_mfma_f32_16x16x32_bf16 v[8:11], v[170:173], v[218:221], v[8:11]
	v_mfma_f32_16x16x32_bf16 v[60:63], v[166:169], v[198:201], v[60:63]
	v_mfma_f32_16x16x32_bf16 v[56:59], v[174:177], v[198:201], v[56:59]
	v_mfma_f32_16x16x32_bf16 v[48:51], v[166:169], v[206:209], v[48:51]
	v_mfma_f32_16x16x32_bf16 v[40:43], v[174:177], v[206:209], v[40:43]
	v_mfma_f32_16x16x32_bf16 v[32:35], v[166:169], v[214:217], v[32:35]
	v_mfma_f32_16x16x32_bf16 v[24:27], v[174:177], v[214:217], v[24:27]
	v_mfma_f32_16x16x32_bf16 v[16:19], v[166:169], v[222:225], v[16:19]
	v_mfma_f32_16x16x32_bf16 v[8:11], v[174:177], v[222:225], v[8:11]
	v_mfma_f32_16x16x32_bf16 v[52:55], v[178:181], v[194:197], v[52:55]
	v_mfma_f32_16x16x32_bf16 v[44:47], v[186:189], v[194:197], v[44:47]
	v_mfma_f32_16x16x32_bf16 v[36:39], v[178:181], v[202:205], v[36:39]
	v_mfma_f32_16x16x32_bf16 v[28:31], v[186:189], v[202:205], v[28:31]
	v_mfma_f32_16x16x32_bf16 v[20:23], v[178:181], v[210:213], v[20:23]
	v_mfma_f32_16x16x32_bf16 v[12:15], v[186:189], v[210:213], v[12:15]
	v_mfma_f32_16x16x32_bf16 v[4:7], v[178:181], v[218:221], v[4:7]
	v_mfma_f32_16x16x32_bf16 v[0:3], v[186:189], v[218:221], v[0:3]
	v_mfma_f32_16x16x32_bf16 v[52:55], v[182:185], v[198:201], v[52:55]
	v_mfma_f32_16x16x32_bf16 v[44:47], v[190:193], v[198:201], v[44:47]
	v_mfma_f32_16x16x32_bf16 v[36:39], v[182:185], v[206:209], v[36:39]
	v_mfma_f32_16x16x32_bf16 v[28:31], v[190:193], v[206:209], v[28:31]
	v_mfma_f32_16x16x32_bf16 v[20:23], v[182:185], v[214:217], v[20:23]
	v_mfma_f32_16x16x32_bf16 v[12:15], v[190:193], v[214:217], v[12:15]
	v_mfma_f32_16x16x32_bf16 v[4:7], v[182:185], v[222:225], v[4:7]
	v_mfma_f32_16x16x32_bf16 v[0:3], v[190:193], v[222:225], v[0:3]
	s_barrier
	s_add_i32 s68, s68, 2
	s_add_u32 s66, s66, 0x100
	s_addc_u32 s67, s67, 0
	s_add_u32 s34, s34, 0x100
	s_addc_u32 s35, s35, 0
	s_cmp_gt_u32 s68, 61
	s_cbranch_scc0 .LBB0_233
	s_setprio 0
	s_and_b64 vcc, exec, s[14:15]
	s_cbranch_vccz .LBB0_236
	s_barrier

.Lsp_skip1:
.LBB0_254:
	ds_read_b128 v[152:155], v149
	ds_read_b128 v[156:159], v149 offset:1024
	ds_read_b128 v[160:163], v149 offset:2048
	ds_read_b128 v[164:167], v149 offset:3072
	ds_read_b128 v[168:171], v150
	ds_read_b128 v[172:175], v150 offset:1024
	ds_read_b128 v[176:179], v150 offset:2048
	ds_read_b128 v[180:183], v150 offset:3072
	ds_read_b128 v[184:187], v151
	ds_read_b128 v[188:191], v151 offset:1024
	ds_read_b128 v[192:195], v151 offset:2048
	ds_read_b128 v[196:199], v151 offset:3072
	ds_read_b128 v[200:203], v151 offset:4096
	ds_read_b128 v[204:207], v151 offset:5120
	ds_read_b128 v[208:211], v151 offset:6144
	ds_read_b128 v[212:215], v151 offset:7168
	s_add_u32 s26, s24, 0x100
	s_addc_u32 s27, s25, 0
	s_cmp_eq_u32 s67, 8
	s_cselect_b32 s31, s1, s27
	s_cselect_b32 s30, s0, s26
	s_cselect_b32 s29, s23, s66
	s_cselect_b32 s28, s22, s65
	v_lshl_add_u64 v[144:145], s[24:25], 0, v[138:139]
	s_add_i32 m0, s46, 0xc000
	s_nop 0
	global_load_lds_dwordx4 v[144:145], off
	v_lshl_add_u64 v[144:145], s[24:25], 0, v[136:137]
	s_add_i32 m0, s46, 0xe000
	s_nop 0
	global_load_lds_dwordx4 v[144:145], off
	s_waitcnt vmcnt(8)
	s_waitcnt lgkmcnt(0)
	s_barrier
	s_waitcnt lgkmcnt(0)
	v_mfma_f32_16x16x32_bf16 v[124:127], v[152:155], v[184:187], v[124:127]
	v_mfma_f32_16x16x32_bf16 v[120:123], v[160:163], v[184:187], v[120:123]
	v_mfma_f32_16x16x32_bf16 v[116:119], v[152:155], v[192:195], v[116:119]
	v_mfma_f32_16x16x32_bf16 v[108:111], v[160:163], v[192:195], v[108:111]
	v_mfma_f32_16x16x32_bf16 v[100:103], v[152:155], v[200:203], v[100:103]
	v_mfma_f32_16x16x32_bf16 v[92:95], v[160:163], v[200:203], v[92:95]
	v_mfma_f32_16x16x32_bf16 v[84:87], v[152:155], v[208:211], v[84:87]
	v_mfma_f32_16x16x32_bf16 v[76:79], v[160:163], v[208:211], v[76:79]
	v_mfma_f32_16x16x32_bf16 v[124:127], v[156:159], v[188:191], v[124:127]
	v_mfma_f32_16x16x32_bf16 v[120:123], v[164:167], v[188:191], v[120:123]
	v_mfma_f32_16x16x32_bf16 v[116:119], v[156:159], v[196:199], v[116:119]
	v_mfma_f32_16x16x32_bf16 v[108:111], v[164:167], v[196:199], v[108:111]
	v_mfma_f32_16x16x32_bf16 v[100:103], v[156:159], v[204:207], v[100:103]
	v_mfma_f32_16x16x32_bf16 v[92:95], v[164:167], v[204:207], v[92:95]
	v_mfma_f32_16x16x32_bf16 v[84:87], v[156:159], v[212:215], v[84:87]
	v_mfma_f32_16x16x32_bf16 v[76:79], v[164:167], v[212:215], v[76:79]
	v_mfma_f32_16x16x32_bf16 v[112:115], v[168:171], v[184:187], v[112:115]
	v_mfma_f32_16x16x32_bf16 v[104:107], v[176:179], v[184:187], v[104:107]
	v_mfma_f32_16x16x32_bf16 v[96:99], v[168:171], v[192:195], v[96:99]
	v_mfma_f32_16x16x32_bf16 v[88:91], v[176:179], v[192:195], v[88:91]
	v_mfma_f32_16x16x32_bf16 v[80:83], v[168:171], v[200:203], v[80:83]
	v_mfma_f32_16x16x32_bf16 v[72:75], v[176:179], v[200:203], v[72:75]
	v_mfma_f32_16x16x32_bf16 v[68:71], v[168:171], v[208:211], v[68:71]
	v_mfma_f32_16x16x32_bf16 v[64:67], v[176:179], v[208:211], v[64:67]
	v_mfma_f32_16x16x32_bf16 v[112:115], v[172:175], v[188:191], v[112:115]
	v_mfma_f32_16x16x32_bf16 v[104:107], v[180:183], v[188:191], v[104:107]
	v_mfma_f32_16x16x32_bf16 v[96:99], v[172:175], v[196:199], v[96:99]
	v_mfma_f32_16x16x32_bf16 v[88:91], v[180:183], v[196:199], v[88:91]
	v_mfma_f32_16x16x32_bf16 v[80:83], v[172:175], v[204:207], v[80:83]
	v_mfma_f32_16x16x32_bf16 v[72:75], v[180:183], v[204:207], v[72:75]
	v_mfma_f32_16x16x32_bf16 v[68:71], v[172:175], v[212:215], v[68:71]
	v_mfma_f32_16x16x32_bf16 v[64:67], v[180:183], v[212:215], v[64:67]
	s_barrier
	ds_read_b128 v[184:187], v151 offset:16384
	ds_read_b128 v[188:191], v151 offset:17408
	ds_read_b128 v[192:195], v151 offset:18432
	ds_read_b128 v[196:199], v151 offset:19456
	ds_read_b128 v[200:203], v151 offset:20480
	ds_read_b128 v[204:207], v151 offset:21504
	ds_read_b128 v[208:211], v151 offset:22528
	ds_read_b128 v[212:215], v151 offset:23552
	s_add_i32 s24, s55, s40
	v_lshl_add_u64 v[144:145], s[28:29], 0, v[132:133]
	s_mov_b32 m0, s24
	s_nop 0
	global_load_lds_dwordx4 v[144:145], off
	s_add_i32 m0, s24, 0x2000
	s_add_u32 s24, s28, 0x30000
	v_lshl_add_u64 v[216:217], s[28:29], 0, v[128:129]
	s_addc_u32 s25, s29, 0
	s_add_i32 s68, s56, s40
	global_load_lds_dwordx4 v[216:217], off
	v_lshl_add_u64 v[218:219], s[24:25], 0, v[132:133]
	s_mov_b32 m0, s68
	v_lshl_add_u64 v[220:221], s[30:31], 0, v[130:131]
	global_load_lds_dwordx4 v[218:219], off
	v_lshl_add_u64 v[218:219], s[24:25], 0, v[128:129]
	s_add_i32 m0, s68, 0x2000
	s_nop 0
	global_load_lds_dwordx4 v[218:219], off
	v_lshl_add_u64 v[218:219], s[30:31], 0, v[134:135]
	s_mov_b32 m0, s46
	s_nop 0
	global_load_lds_dwordx4 v[218:219], off
	s_mov_b32 m0, s47
	s_nop 0
	global_load_lds_dwordx4 v[220:221], off
	s_waitcnt vmcnt(8)
	s_waitcnt lgkmcnt(0)
	s_barrier
	s_waitcnt lgkmcnt(0)
	v_mfma_f32_16x16x32_bf16 v[60:63], v[152:155], v[184:187], v[60:63]
	v_mfma_f32_16x16x32_bf16 v[56:59], v[160:163], v[184:187], v[56:59]
	v_mfma_f32_16x16x32_bf16 v[52:55], v[152:155], v[192:195], v[52:55]
	v_mfma_f32_16x16x32_bf16 v[44:47], v[160:163], v[192:195], v[44:47]
	v_mfma_f32_16x16x32_bf16 v[36:39], v[152:155], v[200:203], v[36:39]
	v_mfma_f32_16x16x32_bf16 v[28:31], v[160:163], v[200:203], v[28:31]
	v_mfma_f32_16x16x32_bf16 v[20:23], v[152:155], v[208:211], v[20:23]
	v_mfma_f32_16x16x32_bf16 v[12:15], v[160:163], v[208:211], v[12:15]
	v_mfma_f32_16x16x32_bf16 v[60:63], v[156:159], v[188:191], v[60:63]
	v_mfma_f32_16x16x32_bf16 v[56:59], v[164:167], v[188:191], v[56:59]
	v_mfma_f32_16x16x32_bf16 v[52:55], v[156:159], v[196:199], v[52:55]
	v_mfma_f32_16x16x32_bf16 v[44:47], v[164:167], v[196:199], v[44:47]
	v_mfma_f32_16x16x32_bf16 v[36:39], v[156:159], v[204:207], v[36:39]
	v_mfma_f32_16x16x32_bf16 v[28:31], v[164:167], v[204:207], v[28:31]
	v_mfma_f32_16x16x32_bf16 v[20:23], v[156:159], v[212:215], v[20:23]
	v_mfma_f32_16x16x32_bf16 v[12:15], v[164:167], v[212:215], v[12:15]
	v_mfma_f32_16x16x32_bf16 v[48:51], v[168:171], v[184:187], v[48:51]
	v_mfma_f32_16x16x32_bf16 v[40:43], v[176:179], v[184:187], v[40:43]
	v_mfma_f32_16x16x32_bf16 v[32:35], v[168:171], v[192:195], v[32:35]
	v_mfma_f32_16x16x32_bf16 v[24:27], v[176:179], v[192:195], v[24:27]
	v_mfma_f32_16x16x32_bf16 v[16:19], v[168:171], v[200:203], v[16:19]
	v_mfma_f32_16x16x32_bf16 v[8:11], v[176:179], v[200:203], v[8:11]
	v_mfma_f32_16x16x32_bf16 v[4:7], v[168:171], v[208:211], v[4:7]
	v_mfma_f32_16x16x32_bf16 v[0:3], v[176:179], v[208:211], v[0:3]
	v_mfma_f32_16x16x32_bf16 v[48:51], v[172:175], v[188:191], v[48:51]
	v_mfma_f32_16x16x32_bf16 v[40:43], v[180:183], v[188:191], v[40:43]
	v_mfma_f32_16x16x32_bf16 v[32:35], v[172:175], v[196:199], v[32:35]
	v_mfma_f32_16x16x32_bf16 v[24:27], v[180:183], v[196:199], v[24:27]
	v_mfma_f32_16x16x32_bf16 v[16:19], v[172:175], v[204:207], v[16:19]
	v_mfma_f32_16x16x32_bf16 v[8:11], v[180:183], v[204:207], v[8:11]
	v_mfma_f32_16x16x32_bf16 v[4:7], v[172:175], v[212:215], v[4:7]
	v_mfma_f32_16x16x32_bf16 v[0:3], v[180:183], v[212:215], v[0:3]
	s_barrier
	ds_read_b128 v[184:187], v151 offset:32768
	ds_read_b128 v[188:191], v151 offset:33792
	ds_read_b128 v[192:195], v151 offset:34816
	ds_read_b128 v[196:199], v151 offset:35840
	ds_read_b128 v[200:203], v151 offset:36864
	ds_read_b128 v[204:207], v151 offset:37888
	ds_read_b128 v[208:211], v151 offset:38912
	ds_read_b128 v[212:215], v151 offset:39936
	s_add_i32 s68, 0, 0x18000
	s_add_i32 s69, 0, 0x1c000
	v_add_u32_e32 v164, s68, v147
	v_add_u32_e32 v180, s69, v147
	ds_read_b128 v[152:155], v164
	ds_read_b128 v[156:159], v164 offset:1024
	ds_read_b128 v[160:163], v164 offset:2048
	ds_read_b128 v[164:167], v164 offset:3072
	ds_read_b128 v[168:171], v180
	ds_read_b128 v[172:175], v180 offset:1024
	ds_read_b128 v[176:179], v180 offset:2048
	ds_read_b128 v[180:183], v180 offset:3072
	s_add_u32 s24, s30, 0xc0000
	s_addc_u32 s25, s31, 0
	s_mov_b32 m0, s48
	v_lshl_add_u64 v[222:223], s[24:25], 0, v[134:135]
	global_load_lds_dwordx4 v[222:223], off
	v_lshl_add_u64 v[222:223], s[24:25], 0, v[130:131]
	s_mov_b32 m0, s49
	s_nop 0
	global_load_lds_dwordx4 v[222:223], off
	s_waitcnt vmcnt(8)
	s_waitcnt lgkmcnt(0)
	s_barrier
	s_waitcnt lgkmcnt(0)
	v_mfma_f32_16x16x32_bf16 v[124:127], v[152:155], v[184:187], v[124:127]
	v_mfma_f32_16x16x32_bf16 v[120:123], v[160:163], v[184:187], v[120:123]
	v_mfma_f32_16x16x32_bf16 v[116:119], v[152:155], v[192:195], v[116:119]
	v_mfma_f32_16x16x32_bf16 v[108:111], v[160:163], v[192:195], v[108:111]
	v_mfma_f32_16x16x32_bf16 v[100:103], v[152:155], v[200:203], v[100:103]
	v_mfma_f32_16x16x32_bf16 v[92:95], v[160:163], v[200:203], v[92:95]
	v_mfma_f32_16x16x32_bf16 v[84:87], v[152:155], v[208:211], v[84:87]
	v_mfma_f32_16x16x32_bf16 v[76:79], v[160:163], v[208:211], v[76:79]
	v_mfma_f32_16x16x32_bf16 v[124:127], v[156:159], v[188:191], v[124:127]
	v_mfma_f32_16x16x32_bf16 v[120:123], v[164:167], v[188:191], v[120:123]
	v_mfma_f32_16x16x32_bf16 v[116:119], v[156:159], v[196:199], v[116:119]
	v_mfma_f32_16x16x32_bf16 v[108:111], v[164:167], v[196:199], v[108:111]
	v_mfma_f32_16x16x32_bf16 v[100:103], v[156:159], v[204:207], v[100:103]
	v_mfma_f32_16x16x32_bf16 v[92:95], v[164:167], v[204:207], v[92:95]
	v_mfma_f32_16x16x32_bf16 v[84:87], v[156:159], v[212:215], v[84:87]
	v_mfma_f32_16x16x32_bf16 v[76:79], v[164:167], v[212:215], v[76:79]
	v_mfma_f32_16x16x32_bf16 v[112:115], v[168:171], v[184:187], v[112:115]
	v_mfma_f32_16x16x32_bf16 v[104:107], v[176:179], v[184:187], v[104:107]
	v_mfma_f32_16x16x32_bf16 v[96:99], v[168:171], v[192:195], v[96:99]
	v_mfma_f32_16x16x32_bf16 v[88:91], v[176:179], v[192:195], v[88:91]
	v_mfma_f32_16x16x32_bf16 v[80:83], v[168:171], v[200:203], v[80:83]
	v_mfma_f32_16x16x32_bf16 v[72:75], v[176:179], v[200:203], v[72:75]
	v_mfma_f32_16x16x32_bf16 v[68:71], v[168:171], v[208:211], v[68:71]
	v_mfma_f32_16x16x32_bf16 v[64:67], v[176:179], v[208:211], v[64:67]
	v_mfma_f32_16x16x32_bf16 v[112:115], v[172:175], v[188:191], v[112:115]
	v_mfma_f32_16x16x32_bf16 v[104:107], v[180:183], v[188:191], v[104:107]
	v_mfma_f32_16x16x32_bf16 v[96:99], v[172:175], v[196:199], v[96:99]
	v_mfma_f32_16x16x32_bf16 v[88:91], v[180:183], v[196:199], v[88:91]
	v_mfma_f32_16x16x32_bf16 v[80:83], v[172:175], v[204:207], v[80:83]
	v_mfma_f32_16x16x32_bf16 v[72:75], v[180:183], v[204:207], v[72:75]
	v_mfma_f32_16x16x32_bf16 v[68:71], v[172:175], v[212:215], v[68:71]
	v_mfma_f32_16x16x32_bf16 v[64:67], v[180:183], v[212:215], v[64:67]
	s_barrier
	ds_read_b128 v[184:187], v151 offset:49152
	ds_read_b128 v[188:191], v151 offset:50176
	ds_read_b128 v[192:195], v151 offset:51200
	ds_read_b128 v[196:199], v151 offset:52224
	ds_read_b128 v[200:203], v151 offset:53248
	ds_read_b128 v[204:207], v151 offset:54272
	ds_read_b128 v[208:211], v151 offset:55296
	ds_read_b128 v[212:215], v151 offset:56320
	s_add_i32 s24, s68, s40
	v_lshl_add_u64 v[144:145], v[144:145], 0, s[10:11]
	s_mov_b32 m0, s24
	s_nop 0
	global_load_lds_dwordx4 v[144:145], off
	s_add_i32 m0, s24, 0x2000
	s_add_u32 s24, s28, 0x30080
	v_lshl_add_u64 v[144:145], v[216:217], 0, s[10:11]
	s_addc_u32 s25, s29, 0
	s_add_i32 s28, s69, s40
	global_load_lds_dwordx4 v[144:145], off
	v_lshl_add_u64 v[144:145], s[24:25], 0, v[132:133]
	s_mov_b32 m0, s28
	s_nop 0
	global_load_lds_dwordx4 v[144:145], off
	v_lshl_add_u64 v[144:145], s[24:25], 0, v[128:129]
	s_add_i32 m0, s28, 0x2000
	s_nop 0
	global_load_lds_dwordx4 v[144:145], off
	v_lshl_add_u64 v[144:145], v[218:219], 0, s[10:11]
	s_mov_b32 m0, s52
	s_nop 0
	global_load_lds_dwordx4 v[144:145], off
	v_lshl_add_u64 v[144:145], v[220:221], 0, s[10:11]
	s_mov_b32 m0, s53
	s_nop 0
	global_load_lds_dwordx4 v[144:145], off
	s_waitcnt vmcnt(8)
	s_waitcnt lgkmcnt(0)
	s_barrier
	s_waitcnt lgkmcnt(0)
	v_mfma_f32_16x16x32_bf16 v[60:63], v[152:155], v[184:187], v[60:63]
	v_mfma_f32_16x16x32_bf16 v[56:59], v[160:163], v[184:187], v[56:59]
	v_mfma_f32_16x16x32_bf16 v[52:55], v[152:155], v[192:195], v[52:55]
	v_mfma_f32_16x16x32_bf16 v[44:47], v[160:163], v[192:195], v[44:47]
	v_mfma_f32_16x16x32_bf16 v[36:39], v[152:155], v[200:203], v[36:39]
	v_mfma_f32_16x16x32_bf16 v[28:31], v[160:163], v[200:203], v[28:31]
	v_mfma_f32_16x16x32_bf16 v[20:23], v[152:155], v[208:211], v[20:23]
	v_mfma_f32_16x16x32_bf16 v[12:15], v[160:163], v[208:211], v[12:15]
	v_mfma_f32_16x16x32_bf16 v[60:63], v[156:159], v[188:191], v[60:63]
	v_mfma_f32_16x16x32_bf16 v[56:59], v[164:167], v[188:191], v[56:59]
	v_mfma_f32_16x16x32_bf16 v[52:55], v[156:159], v[196:199], v[52:55]
	v_mfma_f32_16x16x32_bf16 v[44:47], v[164:167], v[196:199], v[44:47]
	v_mfma_f32_16x16x32_bf16 v[36:39], v[156:159], v[204:207], v[36:39]
	v_mfma_f32_16x16x32_bf16 v[28:31], v[164:167], v[204:207], v[28:31]
	v_mfma_f32_16x16x32_bf16 v[20:23], v[156:159], v[212:215], v[20:23]
	v_mfma_f32_16x16x32_bf16 v[12:15], v[164:167], v[212:215], v[12:15]
	v_mfma_f32_16x16x32_bf16 v[48:51], v[168:171], v[184:187], v[48:51]
	v_mfma_f32_16x16x32_bf16 v[40:43], v[176:179], v[184:187], v[40:43]
	v_mfma_f32_16x16x32_bf16 v[32:35], v[168:171], v[192:195], v[32:35]
	v_mfma_f32_16x16x32_bf16 v[24:27], v[176:179], v[192:195], v[24:27]
	v_mfma_f32_16x16x32_bf16 v[16:19], v[168:171], v[200:203], v[16:19]
	v_mfma_f32_16x16x32_bf16 v[8:11], v[176:179], v[200:203], v[8:11]
	v_mfma_f32_16x16x32_bf16 v[4:7], v[168:171], v[208:211], v[4:7]
	v_mfma_f32_16x16x32_bf16 v[0:3], v[176:179], v[208:211], v[0:3]
	v_mfma_f32_16x16x32_bf16 v[48:51], v[172:175], v[188:191], v[48:51]
	v_mfma_f32_16x16x32_bf16 v[40:43], v[180:183], v[188:191], v[40:43]
	v_mfma_f32_16x16x32_bf16 v[32:35], v[172:175], v[196:199], v[32:35]
	v_mfma_f32_16x16x32_bf16 v[24:27], v[180:183], v[196:199], v[24:27]
	v_mfma_f32_16x16x32_bf16 v[16:19], v[172:175], v[204:207], v[16:19]
	v_mfma_f32_16x16x32_bf16 v[8:11], v[180:183], v[204:207], v[8:11]
	v_mfma_f32_16x16x32_bf16 v[4:7], v[172:175], v[212:215], v[4:7]
	v_mfma_f32_16x16x32_bf16 v[0:3], v[180:183], v[212:215], v[0:3]
	s_barrier
	s_add_i32 s67, s67, 2
	s_add_u32 s65, s65, 0x100
	s_addc_u32 s66, s66, 0
	s_cmp_gt_u32 s67, 9
	s_mov_b64 s[24:25], s[26:27]
	s_cbranch_scc0 .LBB0_254
	s_setprio 0
	s_and_b64 vcc, exec, s[12:13]
	s_cbranch_vccz .LBB0_257
	s_barrier

.Lsp_skip2:
.LBB0_281:
	ds_read_b128 v[144:147], v153
	ds_read_b128 v[156:159], v153 offset:1024
	ds_read_b128 v[160:163], v153 offset:2048
	ds_read_b128 v[164:167], v153 offset:3072
	ds_read_b128 v[168:171], v154
	ds_read_b128 v[172:175], v154 offset:1024
	ds_read_b128 v[176:179], v154 offset:2048
	ds_read_b128 v[180:183], v154 offset:3072
	ds_read_b128 v[184:187], v155
	ds_read_b128 v[188:191], v155 offset:1024
	ds_read_b128 v[192:195], v155 offset:2048
	ds_read_b128 v[196:199], v155 offset:3072
	ds_read_b128 v[200:203], v155 offset:4096
	ds_read_b128 v[204:207], v155 offset:5120
	ds_read_b128 v[208:211], v155 offset:6144
	ds_read_b128 v[212:215], v155 offset:7168
	s_add_u32 s34, s30, 0xfff80080
	s_addc_u32 s35, s31, -1
	s_cmp_eq_u32 s61, 28
	s_cselect_b32 s37, s23, s35
	s_cselect_b32 s36, s57, s34
	s_cselect_b32 s35, s21, s60
	s_cselect_b32 s34, s58, s59
	v_lshl_add_u64 v[148:149], s[30:31], 0, v[138:139]
	s_add_i32 m0, s29, 0xc000
	s_nop 0
	global_load_lds_dwordx4 v[148:149], off
	v_lshl_add_u64 v[148:149], s[30:31], 0, v[136:137]
	s_add_i32 m0, s29, 0xe000
	s_nop 0
	global_load_lds_dwordx4 v[148:149], off
	s_waitcnt vmcnt(8)
	s_waitcnt lgkmcnt(0)
	s_barrier
	s_waitcnt lgkmcnt(0)
	v_mfma_i32_16x16x64_i8 v[124:127], v[144:147], v[184:187], v[124:127]
	v_mfma_i32_16x16x64_i8 v[120:123], v[160:163], v[184:187], v[120:123]
	v_mfma_i32_16x16x64_i8 v[108:111], v[144:147], v[192:195], v[108:111]
	v_mfma_i32_16x16x64_i8 v[104:107], v[160:163], v[192:195], v[104:107]
	v_mfma_i32_16x16x64_i8 v[92:95], v[144:147], v[200:203], v[92:95]
	v_mfma_i32_16x16x64_i8 v[88:91], v[160:163], v[200:203], v[88:91]
	v_mfma_i32_16x16x64_i8 v[76:79], v[144:147], v[208:211], v[76:79]
	v_mfma_i32_16x16x64_i8 v[72:75], v[160:163], v[208:211], v[72:75]
	v_mfma_i32_16x16x64_i8 v[124:127], v[156:159], v[188:191], v[124:127]
	v_mfma_i32_16x16x64_i8 v[120:123], v[164:167], v[188:191], v[120:123]
	v_mfma_i32_16x16x64_i8 v[108:111], v[156:159], v[196:199], v[108:111]
	v_mfma_i32_16x16x64_i8 v[104:107], v[164:167], v[196:199], v[104:107]
	v_mfma_i32_16x16x64_i8 v[92:95], v[156:159], v[204:207], v[92:95]
	v_mfma_i32_16x16x64_i8 v[88:91], v[164:167], v[204:207], v[88:91]
	v_mfma_i32_16x16x64_i8 v[76:79], v[156:159], v[212:215], v[76:79]
	v_mfma_i32_16x16x64_i8 v[72:75], v[164:167], v[212:215], v[72:75]
	v_mfma_i32_16x16x64_i8 v[116:119], v[168:171], v[184:187], v[116:119]
	v_mfma_i32_16x16x64_i8 v[112:115], v[176:179], v[184:187], v[112:115]
	v_mfma_i32_16x16x64_i8 v[100:103], v[168:171], v[192:195], v[100:103]
	v_mfma_i32_16x16x64_i8 v[96:99], v[176:179], v[192:195], v[96:99]
	v_mfma_i32_16x16x64_i8 v[84:87], v[168:171], v[200:203], v[84:87]
	v_mfma_i32_16x16x64_i8 v[80:83], v[176:179], v[200:203], v[80:83]
	v_mfma_i32_16x16x64_i8 v[68:71], v[168:171], v[208:211], v[68:71]
	v_mfma_i32_16x16x64_i8 v[64:67], v[176:179], v[208:211], v[64:67]
	v_mfma_i32_16x16x64_i8 v[116:119], v[172:175], v[188:191], v[116:119]
	v_mfma_i32_16x16x64_i8 v[112:115], v[180:183], v[188:191], v[112:115]
	v_mfma_i32_16x16x64_i8 v[100:103], v[172:175], v[196:199], v[100:103]
	v_mfma_i32_16x16x64_i8 v[96:99], v[180:183], v[196:199], v[96:99]
	v_mfma_i32_16x16x64_i8 v[84:87], v[172:175], v[204:207], v[84:87]
	v_mfma_i32_16x16x64_i8 v[80:83], v[180:183], v[204:207], v[80:83]
	v_mfma_i32_16x16x64_i8 v[68:71], v[172:175], v[212:215], v[68:71]
	v_mfma_i32_16x16x64_i8 v[64:67], v[180:183], v[212:215], v[64:67]
	s_barrier
	ds_read_b128 v[184:187], v155 offset:16384
	ds_read_b128 v[188:191], v155 offset:17408
	ds_read_b128 v[192:195], v155 offset:18432
	ds_read_b128 v[196:199], v155 offset:19456
	ds_read_b128 v[200:203], v155 offset:20480
	ds_read_b128 v[204:207], v155 offset:21504
	ds_read_b128 v[208:211], v155 offset:22528
	ds_read_b128 v[212:215], v155 offset:23552
	s_add_i32 s62, s41, s40
	v_lshl_add_u64 v[148:149], s[34:35], 0, v[130:131]
	s_mov_b32 m0, s62
	s_nop 0
	global_load_lds_dwordx4 v[148:149], off
	s_add_i32 m0, s62, 0x2000
	s_add_u32 s62, s34, 0x80000
	v_lshl_add_u64 v[216:217], s[34:35], 0, v[134:135]
	s_addc_u32 s63, s35, 0
	s_add_i32 s64, s42, s40
	global_load_lds_dwordx4 v[216:217], off
	v_lshl_add_u64 v[218:219], s[62:63], 0, v[130:131]
	s_mov_b32 m0, s64
	v_lshl_add_u64 v[220:221], s[36:37], 0, v[132:133]
	global_load_lds_dwordx4 v[218:219], off
	v_lshl_add_u64 v[218:219], s[62:63], 0, v[134:135]
	s_add_i32 m0, s64, 0x2000
	s_nop 0
	global_load_lds_dwordx4 v[218:219], off
	v_lshl_add_u64 v[218:219], s[36:37], 0, v[128:129]
	s_mov_b32 m0, s29
	s_nop 0
	global_load_lds_dwordx4 v[218:219], off
	s_mov_b32 m0, s48
	s_nop 0
	global_load_lds_dwordx4 v[220:221], off
	s_waitcnt vmcnt(8)
	s_waitcnt lgkmcnt(0)
	s_barrier
	s_waitcnt lgkmcnt(0)
	v_mfma_i32_16x16x64_i8 v[60:63], v[144:147], v[184:187], v[60:63]
	v_mfma_i32_16x16x64_i8 v[56:59], v[160:163], v[184:187], v[56:59]
	v_mfma_i32_16x16x64_i8 v[44:47], v[144:147], v[192:195], v[44:47]
	v_mfma_i32_16x16x64_i8 v[40:43], v[160:163], v[192:195], v[40:43]
	v_mfma_i32_16x16x64_i8 v[28:31], v[144:147], v[200:203], v[28:31]
	v_mfma_i32_16x16x64_i8 v[24:27], v[160:163], v[200:203], v[24:27]
	v_mfma_i32_16x16x64_i8 v[12:15], v[144:147], v[208:211], v[12:15]
	v_mfma_i32_16x16x64_i8 v[8:11], v[160:163], v[208:211], v[8:11]
	v_mfma_i32_16x16x64_i8 v[60:63], v[156:159], v[188:191], v[60:63]
	v_mfma_i32_16x16x64_i8 v[56:59], v[164:167], v[188:191], v[56:59]
	v_mfma_i32_16x16x64_i8 v[44:47], v[156:159], v[196:199], v[44:47]
	v_mfma_i32_16x16x64_i8 v[40:43], v[164:167], v[196:199], v[40:43]
	v_mfma_i32_16x16x64_i8 v[28:31], v[156:159], v[204:207], v[28:31]
	v_mfma_i32_16x16x64_i8 v[24:27], v[164:167], v[204:207], v[24:27]
	v_mfma_i32_16x16x64_i8 v[12:15], v[156:159], v[212:215], v[12:15]
	v_mfma_i32_16x16x64_i8 v[8:11], v[164:167], v[212:215], v[8:11]
	v_mfma_i32_16x16x64_i8 v[52:55], v[168:171], v[184:187], v[52:55]
	v_mfma_i32_16x16x64_i8 v[48:51], v[176:179], v[184:187], v[48:51]
	v_mfma_i32_16x16x64_i8 v[36:39], v[168:171], v[192:195], v[36:39]
	v_mfma_i32_16x16x64_i8 v[32:35], v[176:179], v[192:195], v[32:35]
	v_mfma_i32_16x16x64_i8 v[20:23], v[168:171], v[200:203], v[20:23]
	v_mfma_i32_16x16x64_i8 v[16:19], v[176:179], v[200:203], v[16:19]
	v_mfma_i32_16x16x64_i8 v[4:7], v[168:171], v[208:211], v[4:7]
	v_mfma_i32_16x16x64_i8 v[0:3], v[176:179], v[208:211], v[0:3]
	v_mfma_i32_16x16x64_i8 v[52:55], v[172:175], v[188:191], v[52:55]
	v_mfma_i32_16x16x64_i8 v[48:51], v[180:183], v[188:191], v[48:51]
	v_mfma_i32_16x16x64_i8 v[36:39], v[172:175], v[196:199], v[36:39]
	v_mfma_i32_16x16x64_i8 v[32:35], v[180:183], v[196:199], v[32:35]
	v_mfma_i32_16x16x64_i8 v[20:23], v[172:175], v[204:207], v[20:23]
	v_mfma_i32_16x16x64_i8 v[16:19], v[180:183], v[204:207], v[16:19]
	v_mfma_i32_16x16x64_i8 v[4:7], v[172:175], v[212:215], v[4:7]
	v_mfma_i32_16x16x64_i8 v[0:3], v[180:183], v[212:215], v[0:3]
	s_barrier
	ds_read_b128 v[184:187], v155 offset:32768
	ds_read_b128 v[188:191], v155 offset:33792
	ds_read_b128 v[192:195], v155 offset:34816
	ds_read_b128 v[196:199], v155 offset:35840
	ds_read_b128 v[200:203], v155 offset:36864
	ds_read_b128 v[204:207], v155 offset:37888
	ds_read_b128 v[208:211], v155 offset:38912
	ds_read_b128 v[212:215], v155 offset:39936
	s_add_i32 s62, 0, 0x18000
	s_add_i32 s63, 0, 0x1c000
	v_add_u32_e32 v164, s62, v151
	v_add_u32_e32 v180, s63, v151
	ds_read_b128 v[144:147], v164
	ds_read_b128 v[156:159], v164 offset:1024
	ds_read_b128 v[160:163], v164 offset:2048
	ds_read_b128 v[164:167], v164 offset:3072
	ds_read_b128 v[168:171], v180
	ds_read_b128 v[172:175], v180 offset:1024
	ds_read_b128 v[176:179], v180 offset:2048
	ds_read_b128 v[180:183], v180 offset:3072
	s_add_u32 s36, s36, 0x80000
	s_addc_u32 s37, s37, 0
	s_mov_b32 m0, s49
	v_lshl_add_u64 v[222:223], s[36:37], 0, v[128:129]
	global_load_lds_dwordx4 v[222:223], off
	v_lshl_add_u64 v[222:223], s[36:37], 0, v[132:133]
	s_mov_b32 m0, s50
	s_nop 0
	global_load_lds_dwordx4 v[222:223], off
	s_waitcnt vmcnt(8)
	s_waitcnt lgkmcnt(0)
	s_barrier
	s_waitcnt lgkmcnt(0)
	v_mfma_i32_16x16x64_i8 v[124:127], v[144:147], v[184:187], v[124:127]
	v_mfma_i32_16x16x64_i8 v[120:123], v[160:163], v[184:187], v[120:123]
	v_mfma_i32_16x16x64_i8 v[108:111], v[144:147], v[192:195], v[108:111]
	v_mfma_i32_16x16x64_i8 v[104:107], v[160:163], v[192:195], v[104:107]
	v_mfma_i32_16x16x64_i8 v[92:95], v[144:147], v[200:203], v[92:95]
	v_mfma_i32_16x16x64_i8 v[88:91], v[160:163], v[200:203], v[88:91]
	v_mfma_i32_16x16x64_i8 v[76:79], v[144:147], v[208:211], v[76:79]
	v_mfma_i32_16x16x64_i8 v[72:75], v[160:163], v[208:211], v[72:75]
	v_mfma_i32_16x16x64_i8 v[124:127], v[156:159], v[188:191], v[124:127]
	v_mfma_i32_16x16x64_i8 v[120:123], v[164:167], v[188:191], v[120:123]
	v_mfma_i32_16x16x64_i8 v[108:111], v[156:159], v[196:199], v[108:111]
	v_mfma_i32_16x16x64_i8 v[104:107], v[164:167], v[196:199], v[104:107]
	v_mfma_i32_16x16x64_i8 v[92:95], v[156:159], v[204:207], v[92:95]
	v_mfma_i32_16x16x64_i8 v[88:91], v[164:167], v[204:207], v[88:91]
	v_mfma_i32_16x16x64_i8 v[76:79], v[156:159], v[212:215], v[76:79]
	v_mfma_i32_16x16x64_i8 v[72:75], v[164:167], v[212:215], v[72:75]
	v_mfma_i32_16x16x64_i8 v[116:119], v[168:171], v[184:187], v[116:119]
	v_mfma_i32_16x16x64_i8 v[112:115], v[176:179], v[184:187], v[112:115]
	v_mfma_i32_16x16x64_i8 v[100:103], v[168:171], v[192:195], v[100:103]
	v_mfma_i32_16x16x64_i8 v[96:99], v[176:179], v[192:195], v[96:99]
	v_mfma_i32_16x16x64_i8 v[84:87], v[168:171], v[200:203], v[84:87]
	v_mfma_i32_16x16x64_i8 v[80:83], v[176:179], v[200:203], v[80:83]
	v_mfma_i32_16x16x64_i8 v[68:71], v[168:171], v[208:211], v[68:71]
	v_mfma_i32_16x16x64_i8 v[64:67], v[176:179], v[208:211], v[64:67]
	v_mfma_i32_16x16x64_i8 v[116:119], v[172:175], v[188:191], v[116:119]
	v_mfma_i32_16x16x64_i8 v[112:115], v[180:183], v[188:191], v[112:115]
	v_mfma_i32_16x16x64_i8 v[100:103], v[172:175], v[196:199], v[100:103]
	v_mfma_i32_16x16x64_i8 v[96:99], v[180:183], v[196:199], v[96:99]
	v_mfma_i32_16x16x64_i8 v[84:87], v[172:175], v[204:207], v[84:87]
	v_mfma_i32_16x16x64_i8 v[80:83], v[180:183], v[204:207], v[80:83]
	v_mfma_i32_16x16x64_i8 v[68:71], v[172:175], v[212:215], v[68:71]
	v_mfma_i32_16x16x64_i8 v[64:67], v[180:183], v[212:215], v[64:67]
	s_barrier
	ds_read_b128 v[184:187], v155 offset:49152
	ds_read_b128 v[188:191], v155 offset:50176
	ds_read_b128 v[192:195], v155 offset:51200
	ds_read_b128 v[196:199], v155 offset:52224
	ds_read_b128 v[200:203], v155 offset:53248
	ds_read_b128 v[204:207], v155 offset:54272
	ds_read_b128 v[208:211], v155 offset:55296
	ds_read_b128 v[212:215], v155 offset:56320
	s_add_i32 s36, s62, s40
	v_lshl_add_u64 v[148:149], v[148:149], 0, s[6:7]
	s_mov_b32 m0, s36
	s_nop 0
	global_load_lds_dwordx4 v[148:149], off
	s_add_i32 m0, s36, 0x2000
	s_add_u32 s34, s34, 0x80080
	v_lshl_add_u64 v[148:149], v[216:217], 0, s[6:7]
	s_addc_u32 s35, s35, 0
	s_add_i32 s36, s63, s40
	global_load_lds_dwordx4 v[148:149], off
	v_lshl_add_u64 v[148:149], s[34:35], 0, v[130:131]
	s_mov_b32 m0, s36
	s_nop 0
	global_load_lds_dwordx4 v[148:149], off
	v_lshl_add_u64 v[148:149], s[34:35], 0, v[134:135]
	s_add_i32 m0, s36, 0x2000
	s_nop 0
	global_load_lds_dwordx4 v[148:149], off
	v_lshl_add_u64 v[148:149], v[218:219], 0, s[6:7]
	s_mov_b32 m0, s44
	s_nop 0
	global_load_lds_dwordx4 v[148:149], off
	v_lshl_add_u64 v[148:149], v[220:221], 0, s[6:7]
	s_mov_b32 m0, s52
	s_nop 0
	global_load_lds_dwordx4 v[148:149], off
	s_waitcnt vmcnt(8)
	s_waitcnt lgkmcnt(0)
	s_barrier
	s_waitcnt lgkmcnt(0)
	v_mfma_i32_16x16x64_i8 v[60:63], v[144:147], v[184:187], v[60:63]
	v_mfma_i32_16x16x64_i8 v[56:59], v[160:163], v[184:187], v[56:59]
	v_mfma_i32_16x16x64_i8 v[44:47], v[144:147], v[192:195], v[44:47]
	v_mfma_i32_16x16x64_i8 v[40:43], v[160:163], v[192:195], v[40:43]
	v_mfma_i32_16x16x64_i8 v[28:31], v[144:147], v[200:203], v[28:31]
	v_mfma_i32_16x16x64_i8 v[24:27], v[160:163], v[200:203], v[24:27]
	v_mfma_i32_16x16x64_i8 v[12:15], v[144:147], v[208:211], v[12:15]
	v_mfma_i32_16x16x64_i8 v[8:11], v[160:163], v[208:211], v[8:11]
	v_mfma_i32_16x16x64_i8 v[60:63], v[156:159], v[188:191], v[60:63]
	v_mfma_i32_16x16x64_i8 v[56:59], v[164:167], v[188:191], v[56:59]
	v_mfma_i32_16x16x64_i8 v[44:47], v[156:159], v[196:199], v[44:47]
	v_mfma_i32_16x16x64_i8 v[40:43], v[164:167], v[196:199], v[40:43]
	v_mfma_i32_16x16x64_i8 v[28:31], v[156:159], v[204:207], v[28:31]
	v_mfma_i32_16x16x64_i8 v[24:27], v[164:167], v[204:207], v[24:27]
	v_mfma_i32_16x16x64_i8 v[12:15], v[156:159], v[212:215], v[12:15]
	v_mfma_i32_16x16x64_i8 v[8:11], v[164:167], v[212:215], v[8:11]
	v_mfma_i32_16x16x64_i8 v[52:55], v[168:171], v[184:187], v[52:55]
	v_mfma_i32_16x16x64_i8 v[48:51], v[176:179], v[184:187], v[48:51]
	v_mfma_i32_16x16x64_i8 v[36:39], v[168:171], v[192:195], v[36:39]
	v_mfma_i32_16x16x64_i8 v[32:35], v[176:179], v[192:195], v[32:35]
	v_mfma_i32_16x16x64_i8 v[20:23], v[168:171], v[200:203], v[20:23]
	v_mfma_i32_16x16x64_i8 v[16:19], v[176:179], v[200:203], v[16:19]
	v_mfma_i32_16x16x64_i8 v[4:7], v[168:171], v[208:211], v[4:7]
	v_mfma_i32_16x16x64_i8 v[0:3], v[176:179], v[208:211], v[0:3]
	v_mfma_i32_16x16x64_i8 v[52:55], v[172:175], v[188:191], v[52:55]
	v_mfma_i32_16x16x64_i8 v[48:51], v[180:183], v[188:191], v[48:51]
	v_mfma_i32_16x16x64_i8 v[36:39], v[172:175], v[196:199], v[36:39]
	v_mfma_i32_16x16x64_i8 v[32:35], v[180:183], v[196:199], v[32:35]
	v_mfma_i32_16x16x64_i8 v[20:23], v[172:175], v[204:207], v[20:23]
	v_mfma_i32_16x16x64_i8 v[16:19], v[180:183], v[204:207], v[16:19]
	v_mfma_i32_16x16x64_i8 v[4:7], v[172:175], v[212:215], v[4:7]
	v_mfma_i32_16x16x64_i8 v[0:3], v[180:183], v[212:215], v[0:3]
	s_barrier
	s_add_i32 s61, s61, 2
	s_add_u32 s59, s59, 0x100
	s_addc_u32 s60, s60, 0
	s_add_u32 s30, s30, 0x100
	s_addc_u32 s31, s31, 0
	s_cmp_gt_u32 s61, 29
	s_cbranch_scc0 .LBB0_281
	s_setprio 0
	s_and_b64 vcc, exec, s[8:9]
	s_cbranch_vccz .LBB0_284
	s_barrier

.Lsp_skip3:
.LBB0_451:
	ds_read_b128 v[112:115], v193
	ds_read_b128 v[124:127], v193 offset:1024
	ds_read_b128 v[136:139], v193 offset:2048
	ds_read_b128 v[140:143], v193 offset:3072
	ds_read_b128 v[144:147], v194
	ds_read_b128 v[148:151], v194 offset:1024
	ds_read_b128 v[168:171], v194 offset:2048
	ds_read_b128 v[172:175], v194 offset:3072
	ds_read_b128 v[176:179], v195
	ds_read_b128 v[180:183], v195 offset:1024
	ds_read_b128 v[184:187], v195 offset:2048
	ds_read_b128 v[200:203], v195 offset:3072
	ds_read_b128 v[204:207], v195 offset:4096
	ds_read_b128 v[208:211], v195 offset:5120
	ds_read_b128 v[212:215], v195 offset:6144
	ds_read_b128 v[216:219], v195 offset:7168
	s_add_u32 s34, s30, 0xfff00080
	s_addc_u32 s35, s31, -1
	s_cmp_eq_u32 s58, 60
	s_cselect_b32 s37, s21, s35
	s_cselect_b32 s36, s27, s34
	s_cselect_b32 s35, s19, s57
	s_cselect_b32 s34, s55, s56
	v_lshl_add_u64 v[188:189], s[30:31], 0, v[162:163]
	s_add_i32 m0, s29, 0xc000
	s_nop 0
	global_load_lds_dwordx4 v[188:189], off
	v_lshl_add_u64 v[188:189], s[30:31], 0, v[160:161]
	s_add_i32 m0, s29, 0xe000
	s_nop 0
	global_load_lds_dwordx4 v[188:189], off
	s_waitcnt vmcnt(8)
	s_waitcnt lgkmcnt(0)
	s_barrier
	s_waitcnt lgkmcnt(0)
	v_mfma_f32_16x16x32_bf16 v[132:135], v[112:115], v[176:179], v[132:135]
	v_mfma_f32_16x16x32_bf16 v[128:131], v[136:139], v[176:179], v[128:131]
	v_mfma_f32_16x16x32_bf16 v[108:111], v[112:115], v[184:187], v[108:111]
	v_mfma_f32_16x16x32_bf16 v[104:107], v[136:139], v[184:187], v[104:107]
	v_mfma_f32_16x16x32_bf16 v[92:95], v[112:115], v[204:207], v[92:95]
	v_mfma_f32_16x16x32_bf16 v[88:91], v[136:139], v[204:207], v[88:91]
	v_mfma_f32_16x16x32_bf16 v[76:79], v[112:115], v[212:215], v[76:79]
	v_mfma_f32_16x16x32_bf16 v[72:75], v[136:139], v[212:215], v[72:75]
	v_mfma_f32_16x16x32_bf16 v[132:135], v[124:127], v[180:183], v[132:135]
	v_mfma_f32_16x16x32_bf16 v[128:131], v[140:143], v[180:183], v[128:131]
	v_mfma_f32_16x16x32_bf16 v[108:111], v[124:127], v[200:203], v[108:111]
	v_mfma_f32_16x16x32_bf16 v[104:107], v[140:143], v[200:203], v[104:107]
	v_mfma_f32_16x16x32_bf16 v[92:95], v[124:127], v[208:211], v[92:95]
	v_mfma_f32_16x16x32_bf16 v[88:91], v[140:143], v[208:211], v[88:91]
	v_mfma_f32_16x16x32_bf16 v[76:79], v[124:127], v[216:219], v[76:79]
	v_mfma_f32_16x16x32_bf16 v[72:75], v[140:143], v[216:219], v[72:75]
	v_mfma_f32_16x16x32_bf16 v[120:123], v[144:147], v[176:179], v[120:123]
	v_mfma_f32_16x16x32_bf16 v[116:119], v[168:171], v[176:179], v[116:119]
	v_mfma_f32_16x16x32_bf16 v[100:103], v[144:147], v[184:187], v[100:103]
	v_mfma_f32_16x16x32_bf16 v[96:99], v[168:171], v[184:187], v[96:99]
	v_mfma_f32_16x16x32_bf16 v[84:87], v[144:147], v[204:207], v[84:87]
	v_mfma_f32_16x16x32_bf16 v[80:83], v[168:171], v[204:207], v[80:83]
	v_mfma_f32_16x16x32_bf16 v[68:71], v[144:147], v[212:215], v[68:71]
	v_mfma_f32_16x16x32_bf16 v[64:67], v[168:171], v[212:215], v[64:67]
	v_mfma_f32_16x16x32_bf16 v[120:123], v[148:151], v[180:183], v[120:123]
	v_mfma_f32_16x16x32_bf16 v[116:119], v[172:175], v[180:183], v[116:119]
	v_mfma_f32_16x16x32_bf16 v[100:103], v[148:151], v[200:203], v[100:103]
	v_mfma_f32_16x16x32_bf16 v[96:99], v[172:175], v[200:203], v[96:99]
	v_mfma_f32_16x16x32_bf16 v[84:87], v[148:151], v[208:211], v[84:87]
	v_mfma_f32_16x16x32_bf16 v[80:83], v[172:175], v[208:211], v[80:83]
	v_mfma_f32_16x16x32_bf16 v[68:71], v[148:151], v[216:219], v[68:71]
	v_mfma_f32_16x16x32_bf16 v[64:67], v[172:175], v[216:219], v[64:67]
	s_barrier
	ds_read_b128 v[176:179], v195 offset:16384
	ds_read_b128 v[180:183], v195 offset:17408
	ds_read_b128 v[184:187], v195 offset:18432
	ds_read_b128 v[200:203], v195 offset:19456
	ds_read_b128 v[204:207], v195 offset:20480
	ds_read_b128 v[208:211], v195 offset:21504
	ds_read_b128 v[212:215], v195 offset:22528
	ds_read_b128 v[216:219], v195 offset:23552
	s_add_i32 s59, s50, s41
	v_lshl_add_u64 v[188:189], s[34:35], 0, v[154:155]
	s_mov_b32 m0, s59
	s_nop 0
	global_load_lds_dwordx4 v[188:189], off
	s_add_i32 m0, s59, 0x2000
	s_add_u32 s60, s34, 0x100000
	v_lshl_add_u64 v[220:221], s[34:35], 0, v[158:159]
	s_addc_u32 s61, s35, 0
	s_add_i32 s59, s51, s41
	global_load_lds_dwordx4 v[220:221], off
	v_lshl_add_u64 v[222:223], s[60:61], 0, v[154:155]
	s_mov_b32 m0, s59
	v_lshl_add_u64 v[224:225], s[36:37], 0, v[156:157]
	global_load_lds_dwordx4 v[222:223], off
	v_lshl_add_u64 v[222:223], s[60:61], 0, v[158:159]
	s_add_i32 m0, s59, 0x2000
	s_nop 0
	global_load_lds_dwordx4 v[222:223], off
	v_lshl_add_u64 v[222:223], s[36:37], 0, v[152:153]
	s_mov_b32 m0, s29
	s_nop 0
	global_load_lds_dwordx4 v[222:223], off
	s_mov_b32 m0, s42
	s_nop 0
	global_load_lds_dwordx4 v[224:225], off
	s_waitcnt vmcnt(8)
	s_waitcnt lgkmcnt(0)
	s_barrier
	s_waitcnt lgkmcnt(0)
	v_mfma_f32_16x16x32_bf16 v[60:63], v[112:115], v[176:179], v[60:63]
	v_mfma_f32_16x16x32_bf16 v[56:59], v[136:139], v[176:179], v[56:59]
	v_mfma_f32_16x16x32_bf16 v[44:47], v[112:115], v[184:187], v[44:47]
	v_mfma_f32_16x16x32_bf16 v[40:43], v[136:139], v[184:187], v[40:43]
	v_mfma_f32_16x16x32_bf16 v[28:31], v[112:115], v[204:207], v[28:31]
	v_mfma_f32_16x16x32_bf16 v[24:27], v[136:139], v[204:207], v[24:27]
	v_mfma_f32_16x16x32_bf16 v[12:15], v[112:115], v[212:215], v[12:15]
	v_mfma_f32_16x16x32_bf16 v[8:11], v[136:139], v[212:215], v[8:11]
	v_mfma_f32_16x16x32_bf16 v[60:63], v[124:127], v[180:183], v[60:63]
	v_mfma_f32_16x16x32_bf16 v[56:59], v[140:143], v[180:183], v[56:59]
	v_mfma_f32_16x16x32_bf16 v[44:47], v[124:127], v[200:203], v[44:47]
	v_mfma_f32_16x16x32_bf16 v[40:43], v[140:143], v[200:203], v[40:43]
	v_mfma_f32_16x16x32_bf16 v[28:31], v[124:127], v[208:211], v[28:31]
	v_mfma_f32_16x16x32_bf16 v[24:27], v[140:143], v[208:211], v[24:27]
	v_mfma_f32_16x16x32_bf16 v[12:15], v[124:127], v[216:219], v[12:15]
	v_mfma_f32_16x16x32_bf16 v[8:11], v[140:143], v[216:219], v[8:11]
	v_mfma_f32_16x16x32_bf16 v[52:55], v[144:147], v[176:179], v[52:55]
	v_mfma_f32_16x16x32_bf16 v[48:51], v[168:171], v[176:179], v[48:51]
	v_mfma_f32_16x16x32_bf16 v[36:39], v[144:147], v[184:187], v[36:39]
	v_mfma_f32_16x16x32_bf16 v[32:35], v[168:171], v[184:187], v[32:35]
	v_mfma_f32_16x16x32_bf16 v[20:23], v[144:147], v[204:207], v[20:23]
	v_mfma_f32_16x16x32_bf16 v[16:19], v[168:171], v[204:207], v[16:19]
	v_mfma_f32_16x16x32_bf16 v[4:7], v[144:147], v[212:215], v[4:7]
	v_mfma_f32_16x16x32_bf16 v[0:3], v[168:171], v[212:215], v[0:3]
	v_mfma_f32_16x16x32_bf16 v[52:55], v[148:151], v[180:183], v[52:55]
	v_mfma_f32_16x16x32_bf16 v[48:51], v[172:175], v[180:183], v[48:51]
	v_mfma_f32_16x16x32_bf16 v[36:39], v[148:151], v[200:203], v[36:39]
	v_mfma_f32_16x16x32_bf16 v[32:35], v[172:175], v[200:203], v[32:35]
	v_mfma_f32_16x16x32_bf16 v[20:23], v[148:151], v[208:211], v[20:23]
	v_mfma_f32_16x16x32_bf16 v[16:19], v[172:175], v[208:211], v[16:19]
	v_mfma_f32_16x16x32_bf16 v[4:7], v[148:151], v[216:219], v[4:7]
	v_mfma_f32_16x16x32_bf16 v[0:3], v[172:175], v[216:219], v[0:3]
	s_barrier
	ds_read_b128 v[176:179], v195 offset:32768
	ds_read_b128 v[180:183], v195 offset:33792
	ds_read_b128 v[184:187], v195 offset:34816
	ds_read_b128 v[200:203], v195 offset:35840
	ds_read_b128 v[204:207], v195 offset:36864
	ds_read_b128 v[208:211], v195 offset:37888
	ds_read_b128 v[212:215], v195 offset:38912
	ds_read_b128 v[216:219], v195 offset:39936
	s_add_i32 s59, 0, 0x18000
	s_add_i32 s60, 0, 0x1c000
	v_add_u32_e32 v140, s59, v191
	v_add_u32_e32 v172, s60, v191
	ds_read_b128 v[112:115], v140
	ds_read_b128 v[124:127], v140 offset:1024
	ds_read_b128 v[136:139], v140 offset:2048
	ds_read_b128 v[140:143], v140 offset:3072
	ds_read_b128 v[144:147], v172
	ds_read_b128 v[148:151], v172 offset:1024
	ds_read_b128 v[168:171], v172 offset:2048
	ds_read_b128 v[172:175], v172 offset:3072
	s_add_u32 s36, s36, 0x100000
	s_addc_u32 s37, s37, 0
	s_mov_b32 m0, s43
	v_lshl_add_u64 v[226:227], s[36:37], 0, v[152:153]
	global_load_lds_dwordx4 v[226:227], off
	v_lshl_add_u64 v[226:227], s[36:37], 0, v[156:157]
	s_mov_b32 m0, s44
	s_nop 0
	global_load_lds_dwordx4 v[226:227], off
	s_waitcnt vmcnt(8)
	s_waitcnt lgkmcnt(0)
	s_barrier
	s_waitcnt lgkmcnt(0)
	v_mfma_f32_16x16x32_bf16 v[132:135], v[112:115], v[176:179], v[132:135]
	v_mfma_f32_16x16x32_bf16 v[128:131], v[136:139], v[176:179], v[128:131]
	v_mfma_f32_16x16x32_bf16 v[108:111], v[112:115], v[184:187], v[108:111]
	v_mfma_f32_16x16x32_bf16 v[104:107], v[136:139], v[184:187], v[104:107]
	v_mfma_f32_16x16x32_bf16 v[92:95], v[112:115], v[204:207], v[92:95]
	v_mfma_f32_16x16x32_bf16 v[88:91], v[136:139], v[204:207], v[88:91]
	v_mfma_f32_16x16x32_bf16 v[76:79], v[112:115], v[212:215], v[76:79]
	v_mfma_f32_16x16x32_bf16 v[72:75], v[136:139], v[212:215], v[72:75]
	v_mfma_f32_16x16x32_bf16 v[132:135], v[124:127], v[180:183], v[132:135]
	v_mfma_f32_16x16x32_bf16 v[128:131], v[140:143], v[180:183], v[128:131]
	v_mfma_f32_16x16x32_bf16 v[108:111], v[124:127], v[200:203], v[108:111]
	v_mfma_f32_16x16x32_bf16 v[104:107], v[140:143], v[200:203], v[104:107]
	v_mfma_f32_16x16x32_bf16 v[92:95], v[124:127], v[208:211], v[92:95]
	v_mfma_f32_16x16x32_bf16 v[88:91], v[140:143], v[208:211], v[88:91]
	v_mfma_f32_16x16x32_bf16 v[76:79], v[124:127], v[216:219], v[76:79]
	v_mfma_f32_16x16x32_bf16 v[72:75], v[140:143], v[216:219], v[72:75]
	v_mfma_f32_16x16x32_bf16 v[120:123], v[144:147], v[176:179], v[120:123]
	v_mfma_f32_16x16x32_bf16 v[116:119], v[168:171], v[176:179], v[116:119]
	v_mfma_f32_16x16x32_bf16 v[100:103], v[144:147], v[184:187], v[100:103]
	v_mfma_f32_16x16x32_bf16 v[96:99], v[168:171], v[184:187], v[96:99]
	v_mfma_f32_16x16x32_bf16 v[84:87], v[144:147], v[204:207], v[84:87]
	v_mfma_f32_16x16x32_bf16 v[80:83], v[168:171], v[204:207], v[80:83]
	v_mfma_f32_16x16x32_bf16 v[68:71], v[144:147], v[212:215], v[68:71]
	v_mfma_f32_16x16x32_bf16 v[64:67], v[168:171], v[212:215], v[64:67]
	v_mfma_f32_16x16x32_bf16 v[120:123], v[148:151], v[180:183], v[120:123]
	v_mfma_f32_16x16x32_bf16 v[116:119], v[172:175], v[180:183], v[116:119]
	v_mfma_f32_16x16x32_bf16 v[100:103], v[148:151], v[200:203], v[100:103]
	v_mfma_f32_16x16x32_bf16 v[96:99], v[172:175], v[200:203], v[96:99]
	v_mfma_f32_16x16x32_bf16 v[84:87], v[148:151], v[208:211], v[84:87]
	v_mfma_f32_16x16x32_bf16 v[80:83], v[172:175], v[208:211], v[80:83]
	v_mfma_f32_16x16x32_bf16 v[68:71], v[148:151], v[216:219], v[68:71]
	v_mfma_f32_16x16x32_bf16 v[64:67], v[172:175], v[216:219], v[64:67]
	s_barrier
	ds_read_b128 v[176:179], v195 offset:49152
	ds_read_b128 v[180:183], v195 offset:50176
	ds_read_b128 v[184:187], v195 offset:51200
	ds_read_b128 v[200:203], v195 offset:52224
	ds_read_b128 v[204:207], v195 offset:53248
	ds_read_b128 v[208:211], v195 offset:54272
	ds_read_b128 v[212:215], v195 offset:55296
	ds_read_b128 v[216:219], v195 offset:56320
	s_add_i32 s36, s59, s41
	v_lshl_add_u64 v[188:189], v[188:189], 0, s[14:15]
	s_mov_b32 m0, s36
	s_nop 0
	global_load_lds_dwordx4 v[188:189], off
	s_add_i32 m0, s36, 0x2000
	s_add_u32 s34, s34, 0x100080
	v_lshl_add_u64 v[188:189], v[220:221], 0, s[14:15]
	s_addc_u32 s35, s35, 0
	s_add_i32 s36, s60, s41
	global_load_lds_dwordx4 v[188:189], off
	v_lshl_add_u64 v[188:189], s[34:35], 0, v[154:155]
	s_mov_b32 m0, s36
	s_nop 0
	global_load_lds_dwordx4 v[188:189], off
	v_lshl_add_u64 v[188:189], s[34:35], 0, v[158:159]
	s_add_i32 m0, s36, 0x2000
	s_nop 0
	global_load_lds_dwordx4 v[188:189], off
	v_lshl_add_u64 v[188:189], v[222:223], 0, s[14:15]
	s_mov_b32 m0, s46
	s_nop 0
	global_load_lds_dwordx4 v[188:189], off
	v_lshl_add_u64 v[188:189], v[224:225], 0, s[14:15]
	s_mov_b32 m0, s47
	s_nop 0
	global_load_lds_dwordx4 v[188:189], off
	s_waitcnt vmcnt(8)
	s_waitcnt lgkmcnt(0)
	s_barrier
	s_waitcnt lgkmcnt(0)
	v_mfma_f32_16x16x32_bf16 v[60:63], v[112:115], v[176:179], v[60:63]
	v_mfma_f32_16x16x32_bf16 v[56:59], v[136:139], v[176:179], v[56:59]
	v_mfma_f32_16x16x32_bf16 v[44:47], v[112:115], v[184:187], v[44:47]
	v_mfma_f32_16x16x32_bf16 v[40:43], v[136:139], v[184:187], v[40:43]
	v_mfma_f32_16x16x32_bf16 v[28:31], v[112:115], v[204:207], v[28:31]
	v_mfma_f32_16x16x32_bf16 v[24:27], v[136:139], v[204:207], v[24:27]
	v_mfma_f32_16x16x32_bf16 v[12:15], v[112:115], v[212:215], v[12:15]
	v_mfma_f32_16x16x32_bf16 v[8:11], v[136:139], v[212:215], v[8:11]
	v_mfma_f32_16x16x32_bf16 v[60:63], v[124:127], v[180:183], v[60:63]
	v_mfma_f32_16x16x32_bf16 v[56:59], v[140:143], v[180:183], v[56:59]
	v_mfma_f32_16x16x32_bf16 v[44:47], v[124:127], v[200:203], v[44:47]
	v_mfma_f32_16x16x32_bf16 v[40:43], v[140:143], v[200:203], v[40:43]
	v_mfma_f32_16x16x32_bf16 v[28:31], v[124:127], v[208:211], v[28:31]
	v_mfma_f32_16x16x32_bf16 v[24:27], v[140:143], v[208:211], v[24:27]
	v_mfma_f32_16x16x32_bf16 v[12:15], v[124:127], v[216:219], v[12:15]
	v_mfma_f32_16x16x32_bf16 v[8:11], v[140:143], v[216:219], v[8:11]
	v_mfma_f32_16x16x32_bf16 v[52:55], v[144:147], v[176:179], v[52:55]
	v_mfma_f32_16x16x32_bf16 v[48:51], v[168:171], v[176:179], v[48:51]
	v_mfma_f32_16x16x32_bf16 v[36:39], v[144:147], v[184:187], v[36:39]
	v_mfma_f32_16x16x32_bf16 v[32:35], v[168:171], v[184:187], v[32:35]
	v_mfma_f32_16x16x32_bf16 v[20:23], v[144:147], v[204:207], v[20:23]
	v_mfma_f32_16x16x32_bf16 v[16:19], v[168:171], v[204:207], v[16:19]
	v_mfma_f32_16x16x32_bf16 v[4:7], v[144:147], v[212:215], v[4:7]
	v_mfma_f32_16x16x32_bf16 v[0:3], v[168:171], v[212:215], v[0:3]
	v_mfma_f32_16x16x32_bf16 v[52:55], v[148:151], v[180:183], v[52:55]
	v_mfma_f32_16x16x32_bf16 v[48:51], v[172:175], v[180:183], v[48:51]
	v_mfma_f32_16x16x32_bf16 v[36:39], v[148:151], v[200:203], v[36:39]
	v_mfma_f32_16x16x32_bf16 v[32:35], v[172:175], v[200:203], v[32:35]
	v_mfma_f32_16x16x32_bf16 v[20:23], v[148:151], v[208:211], v[20:23]
	v_mfma_f32_16x16x32_bf16 v[16:19], v[172:175], v[208:211], v[16:19]
	v_mfma_f32_16x16x32_bf16 v[4:7], v[148:151], v[216:219], v[4:7]
	v_mfma_f32_16x16x32_bf16 v[0:3], v[172:175], v[216:219], v[0:3]
	s_barrier
	s_add_i32 s58, s58, 2
	s_add_u32 s56, s56, 0x100
	s_addc_u32 s57, s57, 0
	s_add_u32 s30, s30, 0x100
	s_addc_u32 s31, s31, 0
	s_cmp_gt_u32 s58, 61
	s_cbranch_scc0 .LBB0_451
	s_setprio 0
	s_and_b64 vcc, exec, s[16:17]
	s_cbranch_vccz .LBB0_454
	s_barrier

.Lsp_skip4:
.LBB0_550:
	ds_read_b128 v[144:147], v161
	ds_read_b128 v[148:151], v161 offset:1024
	ds_read_b128 v[170:173], v161 offset:2048
	ds_read_b128 v[174:177], v161 offset:3072
	ds_read_b128 v[178:181], v163
	ds_read_b128 v[182:185], v163 offset:1024
	ds_read_b128 v[186:189], v163 offset:2048
	ds_read_b128 v[190:193], v163 offset:3072
	ds_read_b128 v[194:197], v166
	ds_read_b128 v[198:201], v166 offset:1024
	ds_read_b128 v[202:205], v166 offset:2048
	ds_read_b128 v[206:209], v166 offset:3072
	ds_read_b128 v[210:213], v166 offset:4096
	ds_read_b128 v[214:217], v166 offset:5120
	ds_read_b128 v[218:221], v166 offset:6144
	ds_read_b128 v[222:225], v166 offset:7168
	s_add_u32 s6, s4, 0xfff80080
	s_addc_u32 s7, s5, -1
	s_cmp_eq_u32 s64, 28
	s_cselect_b32 s39, s1, s7
	s_cselect_b32 s38, s31, s6
	s_cselect_b32 s7, s29, s63
	s_cselect_b32 s6, s61, s62
	v_lshl_add_u64 v[152:153], s[4:5], 0, v[138:139]
	s_add_i32 m0, s45, 0xc000
	s_nop 0
	global_load_lds_dwordx4 v[152:153], off
	v_lshl_add_u64 v[152:153], s[4:5], 0, v[136:137]
	s_add_i32 m0, s45, 0xe000
	s_nop 0
	global_load_lds_dwordx4 v[152:153], off
	s_waitcnt vmcnt(8)
	s_waitcnt lgkmcnt(0)
	s_barrier
	s_waitcnt lgkmcnt(0)
	v_mfma_i32_16x16x64_i8 v[124:127], v[144:147], v[194:197], v[124:127]
	v_mfma_i32_16x16x64_i8 v[120:123], v[170:173], v[194:197], v[120:123]
	v_mfma_i32_16x16x64_i8 v[108:111], v[144:147], v[202:205], v[108:111]
	v_mfma_i32_16x16x64_i8 v[104:107], v[170:173], v[202:205], v[104:107]
	v_mfma_i32_16x16x64_i8 v[92:95], v[144:147], v[210:213], v[92:95]
	v_mfma_i32_16x16x64_i8 v[88:91], v[170:173], v[210:213], v[88:91]
	v_mfma_i32_16x16x64_i8 v[76:79], v[144:147], v[218:221], v[76:79]
	v_mfma_i32_16x16x64_i8 v[72:75], v[170:173], v[218:221], v[72:75]
	v_mfma_i32_16x16x64_i8 v[124:127], v[148:151], v[198:201], v[124:127]
	v_mfma_i32_16x16x64_i8 v[120:123], v[174:177], v[198:201], v[120:123]
	v_mfma_i32_16x16x64_i8 v[108:111], v[148:151], v[206:209], v[108:111]
	v_mfma_i32_16x16x64_i8 v[104:107], v[174:177], v[206:209], v[104:107]
	v_mfma_i32_16x16x64_i8 v[92:95], v[148:151], v[214:217], v[92:95]
	v_mfma_i32_16x16x64_i8 v[88:91], v[174:177], v[214:217], v[88:91]
	v_mfma_i32_16x16x64_i8 v[76:79], v[148:151], v[222:225], v[76:79]
	v_mfma_i32_16x16x64_i8 v[72:75], v[174:177], v[222:225], v[72:75]
	v_mfma_i32_16x16x64_i8 v[116:119], v[178:181], v[194:197], v[116:119]
	v_mfma_i32_16x16x64_i8 v[112:115], v[186:189], v[194:197], v[112:115]
	v_mfma_i32_16x16x64_i8 v[100:103], v[178:181], v[202:205], v[100:103]
	v_mfma_i32_16x16x64_i8 v[96:99], v[186:189], v[202:205], v[96:99]
	v_mfma_i32_16x16x64_i8 v[84:87], v[178:181], v[210:213], v[84:87]
	v_mfma_i32_16x16x64_i8 v[80:83], v[186:189], v[210:213], v[80:83]
	v_mfma_i32_16x16x64_i8 v[68:71], v[178:181], v[218:221], v[68:71]
	v_mfma_i32_16x16x64_i8 v[64:67], v[186:189], v[218:221], v[64:67]
	v_mfma_i32_16x16x64_i8 v[116:119], v[182:185], v[198:201], v[116:119]
	v_mfma_i32_16x16x64_i8 v[112:115], v[190:193], v[198:201], v[112:115]
	v_mfma_i32_16x16x64_i8 v[100:103], v[182:185], v[206:209], v[100:103]
	v_mfma_i32_16x16x64_i8 v[96:99], v[190:193], v[206:209], v[96:99]
	v_mfma_i32_16x16x64_i8 v[84:87], v[182:185], v[214:217], v[84:87]
	v_mfma_i32_16x16x64_i8 v[80:83], v[190:193], v[214:217], v[80:83]
	v_mfma_i32_16x16x64_i8 v[68:71], v[182:185], v[222:225], v[68:71]
	v_mfma_i32_16x16x64_i8 v[64:67], v[190:193], v[222:225], v[64:67]
	s_barrier
	ds_read_b128 v[194:197], v166 offset:16384
	ds_read_b128 v[198:201], v166 offset:17408
	ds_read_b128 v[202:205], v166 offset:18432
	ds_read_b128 v[206:209], v166 offset:19456
	ds_read_b128 v[210:213], v166 offset:20480
	ds_read_b128 v[214:217], v166 offset:21504
	ds_read_b128 v[218:221], v166 offset:22528
	ds_read_b128 v[222:225], v166 offset:23552
	s_add_i32 s65, s53, s44
	v_lshl_add_u64 v[152:153], s[6:7], 0, v[130:131]
	s_mov_b32 m0, s65
	s_nop 0
	global_load_lds_dwordx4 v[152:153], off
	s_add_i32 m0, s65, 0x2000
	s_add_u32 s66, s6, 0x80000
	v_lshl_add_u64 v[164:165], s[6:7], 0, v[134:135]
	s_addc_u32 s67, s7, 0
	s_add_i32 s65, s54, s44
	global_load_lds_dwordx4 v[164:165], off
	v_lshl_add_u64 v[226:227], s[66:67], 0, v[130:131]
	s_mov_b32 m0, s65
	v_lshl_add_u64 v[228:229], s[38:39], 0, v[132:133]
	global_load_lds_dwordx4 v[226:227], off
	v_lshl_add_u64 v[226:227], s[66:67], 0, v[134:135]
	s_add_i32 m0, s65, 0x2000
	s_nop 0
	global_load_lds_dwordx4 v[226:227], off
	v_lshl_add_u64 v[226:227], s[38:39], 0, v[128:129]
	s_mov_b32 m0, s45
	s_nop 0
	global_load_lds_dwordx4 v[226:227], off
	s_mov_b32 m0, s46
	s_nop 0
	global_load_lds_dwordx4 v[228:229], off
	s_waitcnt vmcnt(8)
	s_waitcnt lgkmcnt(0)
	s_barrier
	s_waitcnt lgkmcnt(0)
	v_mfma_i32_16x16x64_i8 v[60:63], v[144:147], v[194:197], v[60:63]
	v_mfma_i32_16x16x64_i8 v[56:59], v[170:173], v[194:197], v[56:59]
	v_mfma_i32_16x16x64_i8 v[44:47], v[144:147], v[202:205], v[44:47]
	v_mfma_i32_16x16x64_i8 v[40:43], v[170:173], v[202:205], v[40:43]
	v_mfma_i32_16x16x64_i8 v[28:31], v[144:147], v[210:213], v[28:31]
	v_mfma_i32_16x16x64_i8 v[24:27], v[170:173], v[210:213], v[24:27]
	v_mfma_i32_16x16x64_i8 v[12:15], v[144:147], v[218:221], v[12:15]
	v_mfma_i32_16x16x64_i8 v[8:11], v[170:173], v[218:221], v[8:11]
	v_mfma_i32_16x16x64_i8 v[60:63], v[148:151], v[198:201], v[60:63]
	v_mfma_i32_16x16x64_i8 v[56:59], v[174:177], v[198:201], v[56:59]
	v_mfma_i32_16x16x64_i8 v[44:47], v[148:151], v[206:209], v[44:47]
	v_mfma_i32_16x16x64_i8 v[40:43], v[174:177], v[206:209], v[40:43]
	v_mfma_i32_16x16x64_i8 v[28:31], v[148:151], v[214:217], v[28:31]
	v_mfma_i32_16x16x64_i8 v[24:27], v[174:177], v[214:217], v[24:27]
	v_mfma_i32_16x16x64_i8 v[12:15], v[148:151], v[222:225], v[12:15]
	v_mfma_i32_16x16x64_i8 v[8:11], v[174:177], v[222:225], v[8:11]
	v_mfma_i32_16x16x64_i8 v[52:55], v[178:181], v[194:197], v[52:55]
	v_mfma_i32_16x16x64_i8 v[48:51], v[186:189], v[194:197], v[48:51]
	v_mfma_i32_16x16x64_i8 v[36:39], v[178:181], v[202:205], v[36:39]
	v_mfma_i32_16x16x64_i8 v[32:35], v[186:189], v[202:205], v[32:35]
	v_mfma_i32_16x16x64_i8 v[20:23], v[178:181], v[210:213], v[20:23]
	v_mfma_i32_16x16x64_i8 v[16:19], v[186:189], v[210:213], v[16:19]
	v_mfma_i32_16x16x64_i8 v[4:7], v[178:181], v[218:221], v[4:7]
	v_mfma_i32_16x16x64_i8 v[0:3], v[186:189], v[218:221], v[0:3]
	v_mfma_i32_16x16x64_i8 v[52:55], v[182:185], v[198:201], v[52:55]
	v_mfma_i32_16x16x64_i8 v[48:51], v[190:193], v[198:201], v[48:51]
	v_mfma_i32_16x16x64_i8 v[36:39], v[182:185], v[206:209], v[36:39]
	v_mfma_i32_16x16x64_i8 v[32:35], v[190:193], v[206:209], v[32:35]
	v_mfma_i32_16x16x64_i8 v[20:23], v[182:185], v[214:217], v[20:23]
	v_mfma_i32_16x16x64_i8 v[16:19], v[190:193], v[214:217], v[16:19]
	v_mfma_i32_16x16x64_i8 v[4:7], v[182:185], v[222:225], v[4:7]
	v_mfma_i32_16x16x64_i8 v[0:3], v[190:193], v[222:225], v[0:3]
	s_barrier
	ds_read_b128 v[194:197], v166 offset:32768
	ds_read_b128 v[198:201], v166 offset:33792
	ds_read_b128 v[202:205], v166 offset:34816
	ds_read_b128 v[206:209], v166 offset:35840
	ds_read_b128 v[210:213], v166 offset:36864
	ds_read_b128 v[214:217], v166 offset:37888
	ds_read_b128 v[218:221], v166 offset:38912
	ds_read_b128 v[222:225], v166 offset:39936
	s_add_i32 s65, 0, 0x18000
	v_add_u32_e32 v154, s65, v157
	s_add_i32 s66, 0, 0x1c000
	ds_read_b128 v[144:147], v154
	ds_read_b128 v[148:151], v154 offset:1024
	ds_read_b128 v[170:173], v154 offset:2048
	ds_read_b128 v[174:177], v154 offset:3072
	v_add_u32_e32 v154, s66, v157
	ds_read_b128 v[178:181], v154
	ds_read_b128 v[182:185], v154 offset:1024
	ds_read_b128 v[186:189], v154 offset:2048
	ds_read_b128 v[190:193], v154 offset:3072
	s_add_u32 s38, s38, 0x80000
	s_addc_u32 s39, s39, 0
	s_mov_b32 m0, s47
	v_lshl_add_u64 v[230:231], s[38:39], 0, v[128:129]
	global_load_lds_dwordx4 v[230:231], off
	v_lshl_add_u64 v[230:231], s[38:39], 0, v[132:133]
	s_mov_b32 m0, s48
	s_nop 0
	global_load_lds_dwordx4 v[230:231], off
	s_waitcnt vmcnt(8)
	s_waitcnt lgkmcnt(0)
	s_barrier
	s_waitcnt lgkmcnt(0)
	v_mfma_i32_16x16x64_i8 v[124:127], v[144:147], v[194:197], v[124:127]
	v_mfma_i32_16x16x64_i8 v[120:123], v[170:173], v[194:197], v[120:123]
	v_mfma_i32_16x16x64_i8 v[108:111], v[144:147], v[202:205], v[108:111]
	v_mfma_i32_16x16x64_i8 v[104:107], v[170:173], v[202:205], v[104:107]
	v_mfma_i32_16x16x64_i8 v[92:95], v[144:147], v[210:213], v[92:95]
	v_mfma_i32_16x16x64_i8 v[88:91], v[170:173], v[210:213], v[88:91]
	v_mfma_i32_16x16x64_i8 v[76:79], v[144:147], v[218:221], v[76:79]
	v_mfma_i32_16x16x64_i8 v[72:75], v[170:173], v[218:221], v[72:75]
	v_mfma_i32_16x16x64_i8 v[124:127], v[148:151], v[198:201], v[124:127]
	v_mfma_i32_16x16x64_i8 v[120:123], v[174:177], v[198:201], v[120:123]
	v_mfma_i32_16x16x64_i8 v[108:111], v[148:151], v[206:209], v[108:111]
	v_mfma_i32_16x16x64_i8 v[104:107], v[174:177], v[206:209], v[104:107]
	v_mfma_i32_16x16x64_i8 v[92:95], v[148:151], v[214:217], v[92:95]
	v_mfma_i32_16x16x64_i8 v[88:91], v[174:177], v[214:217], v[88:91]
	v_mfma_i32_16x16x64_i8 v[76:79], v[148:151], v[222:225], v[76:79]
	v_mfma_i32_16x16x64_i8 v[72:75], v[174:177], v[222:225], v[72:75]
	v_mfma_i32_16x16x64_i8 v[116:119], v[178:181], v[194:197], v[116:119]
	v_mfma_i32_16x16x64_i8 v[112:115], v[186:189], v[194:197], v[112:115]
	v_mfma_i32_16x16x64_i8 v[100:103], v[178:181], v[202:205], v[100:103]
	v_mfma_i32_16x16x64_i8 v[96:99], v[186:189], v[202:205], v[96:99]
	v_mfma_i32_16x16x64_i8 v[84:87], v[178:181], v[210:213], v[84:87]
	v_mfma_i32_16x16x64_i8 v[80:83], v[186:189], v[210:213], v[80:83]
	v_mfma_i32_16x16x64_i8 v[68:71], v[178:181], v[218:221], v[68:71]
	v_mfma_i32_16x16x64_i8 v[64:67], v[186:189], v[218:221], v[64:67]
	v_mfma_i32_16x16x64_i8 v[116:119], v[182:185], v[198:201], v[116:119]
	v_mfma_i32_16x16x64_i8 v[112:115], v[190:193], v[198:201], v[112:115]
	v_mfma_i32_16x16x64_i8 v[100:103], v[182:185], v[206:209], v[100:103]
	v_mfma_i32_16x16x64_i8 v[96:99], v[190:193], v[206:209], v[96:99]
	v_mfma_i32_16x16x64_i8 v[84:87], v[182:185], v[214:217], v[84:87]
	v_mfma_i32_16x16x64_i8 v[80:83], v[190:193], v[214:217], v[80:83]
	v_mfma_i32_16x16x64_i8 v[68:71], v[182:185], v[222:225], v[68:71]
	v_mfma_i32_16x16x64_i8 v[64:67], v[190:193], v[222:225], v[64:67]
	s_barrier
	ds_read_b128 v[194:197], v166 offset:49152
	ds_read_b128 v[198:201], v166 offset:50176
	ds_read_b128 v[202:205], v166 offset:51200
	ds_read_b128 v[206:209], v166 offset:52224
	ds_read_b128 v[210:213], v166 offset:53248
	ds_read_b128 v[214:217], v166 offset:54272
	ds_read_b128 v[218:221], v166 offset:55296
	ds_read_b128 v[222:225], v166 offset:56320
	s_add_i32 s38, s65, s44
	v_lshl_add_u64 v[152:153], v[152:153], 0, s[16:17]
	s_mov_b32 m0, s38
	s_nop 0
	global_load_lds_dwordx4 v[152:153], off
	s_add_i32 m0, s38, 0x2000
	s_add_u32 s6, s6, 0x80080
	v_lshl_add_u64 v[152:153], v[164:165], 0, s[16:17]
	s_addc_u32 s7, s7, 0
	s_add_i32 s38, s66, s44
	global_load_lds_dwordx4 v[152:153], off
	v_lshl_add_u64 v[152:153], s[6:7], 0, v[130:131]
	s_mov_b32 m0, s38
	s_nop 0
	global_load_lds_dwordx4 v[152:153], off
	v_lshl_add_u64 v[152:153], s[6:7], 0, v[134:135]
	s_add_i32 m0, s38, 0x2000
	s_nop 0
	global_load_lds_dwordx4 v[152:153], off
	v_lshl_add_u64 v[152:153], v[226:227], 0, s[16:17]
	s_mov_b32 m0, s50
	s_nop 0
	global_load_lds_dwordx4 v[152:153], off
	v_lshl_add_u64 v[152:153], v[228:229], 0, s[16:17]
	s_mov_b32 m0, s51
	s_nop 0
	global_load_lds_dwordx4 v[152:153], off
	s_waitcnt vmcnt(8)
	s_waitcnt lgkmcnt(0)
	s_barrier
	s_waitcnt lgkmcnt(0)
	v_mfma_i32_16x16x64_i8 v[60:63], v[144:147], v[194:197], v[60:63]
	v_mfma_i32_16x16x64_i8 v[56:59], v[170:173], v[194:197], v[56:59]
	v_mfma_i32_16x16x64_i8 v[44:47], v[144:147], v[202:205], v[44:47]
	v_mfma_i32_16x16x64_i8 v[40:43], v[170:173], v[202:205], v[40:43]
	v_mfma_i32_16x16x64_i8 v[28:31], v[144:147], v[210:213], v[28:31]
	v_mfma_i32_16x16x64_i8 v[24:27], v[170:173], v[210:213], v[24:27]
	v_mfma_i32_16x16x64_i8 v[12:15], v[144:147], v[218:221], v[12:15]
	v_mfma_i32_16x16x64_i8 v[8:11], v[170:173], v[218:221], v[8:11]
	v_mfma_i32_16x16x64_i8 v[60:63], v[148:151], v[198:201], v[60:63]
	v_mfma_i32_16x16x64_i8 v[56:59], v[174:177], v[198:201], v[56:59]
	v_mfma_i32_16x16x64_i8 v[44:47], v[148:151], v[206:209], v[44:47]
	v_mfma_i32_16x16x64_i8 v[40:43], v[174:177], v[206:209], v[40:43]
	v_mfma_i32_16x16x64_i8 v[28:31], v[148:151], v[214:217], v[28:31]
	v_mfma_i32_16x16x64_i8 v[24:27], v[174:177], v[214:217], v[24:27]
	v_mfma_i32_16x16x64_i8 v[12:15], v[148:151], v[222:225], v[12:15]
	v_mfma_i32_16x16x64_i8 v[8:11], v[174:177], v[222:225], v[8:11]
	v_mfma_i32_16x16x64_i8 v[52:55], v[178:181], v[194:197], v[52:55]
	v_mfma_i32_16x16x64_i8 v[48:51], v[186:189], v[194:197], v[48:51]
	v_mfma_i32_16x16x64_i8 v[36:39], v[178:181], v[202:205], v[36:39]
	v_mfma_i32_16x16x64_i8 v[32:35], v[186:189], v[202:205], v[32:35]
	v_mfma_i32_16x16x64_i8 v[20:23], v[178:181], v[210:213], v[20:23]
	v_mfma_i32_16x16x64_i8 v[16:19], v[186:189], v[210:213], v[16:19]
	v_mfma_i32_16x16x64_i8 v[4:7], v[178:181], v[218:221], v[4:7]
	v_mfma_i32_16x16x64_i8 v[0:3], v[186:189], v[218:221], v[0:3]
	v_mfma_i32_16x16x64_i8 v[52:55], v[182:185], v[198:201], v[52:55]
	v_mfma_i32_16x16x64_i8 v[48:51], v[190:193], v[198:201], v[48:51]
	v_mfma_i32_16x16x64_i8 v[36:39], v[182:185], v[206:209], v[36:39]
	v_mfma_i32_16x16x64_i8 v[32:35], v[190:193], v[206:209], v[32:35]
	v_mfma_i32_16x16x64_i8 v[20:23], v[182:185], v[214:217], v[20:23]
	v_mfma_i32_16x16x64_i8 v[16:19], v[190:193], v[214:217], v[16:19]
	v_mfma_i32_16x16x64_i8 v[4:7], v[182:185], v[222:225], v[4:7]
	v_mfma_i32_16x16x64_i8 v[0:3], v[190:193], v[222:225], v[0:3]
	s_barrier
	s_add_i32 s64, s64, 2
	s_add_u32 s62, s62, 0x100
	s_addc_u32 s63, s63, 0
	s_add_u32 s4, s4, 0x100
	s_addc_u32 s5, s5, 0
	s_cmp_gt_u32 s64, 29
	s_cbranch_scc0 .LBB0_550
	s_setprio 0
	s_and_b64 vcc, exec, s[18:19]
	s_cbranch_vccz .LBB0_553
	s_barrier

.Lsp_skip5:
.LBB0_635:
	ds_read_b128 v[112:115], v193
	ds_read_b128 v[124:127], v193 offset:1024
	ds_read_b128 v[136:139], v193 offset:2048
	ds_read_b128 v[140:143], v193 offset:3072
	ds_read_b128 v[144:147], v194
	ds_read_b128 v[148:151], v194 offset:1024
	ds_read_b128 v[168:171], v194 offset:2048
	ds_read_b128 v[172:175], v194 offset:3072
	ds_read_b128 v[176:179], v195
	ds_read_b128 v[180:183], v195 offset:1024
	ds_read_b128 v[184:187], v195 offset:2048
	ds_read_b128 v[200:203], v195 offset:3072
	ds_read_b128 v[204:207], v195 offset:4096
	ds_read_b128 v[208:211], v195 offset:5120
	ds_read_b128 v[212:215], v195 offset:6144
	ds_read_b128 v[216:219], v195 offset:7168
	s_add_u32 s34, s30, 0xffbf8080
	s_addc_u32 s35, s31, -1
	s_cmpk_eq_i32 s58, 0xfc
	s_cselect_b32 s37, s21, s35
	s_cselect_b32 s36, s27, s34
	s_cselect_b32 s35, s19, s57
	s_cselect_b32 s34, s55, s56
	v_lshl_add_u64 v[188:189], s[30:31], 0, v[162:163]
	s_add_i32 m0, s29, 0xc000
	s_nop 0
	global_load_lds_dwordx4 v[188:189], off
	v_lshl_add_u64 v[188:189], s[30:31], 0, v[160:161]
	s_add_i32 m0, s29, 0xe000
	s_nop 0
	global_load_lds_dwordx4 v[188:189], off
	s_waitcnt vmcnt(8)
	s_waitcnt lgkmcnt(0)
	s_barrier
	s_waitcnt lgkmcnt(0)
	v_mfma_f32_16x16x32_bf16 v[132:135], v[112:115], v[176:179], v[132:135]
	v_mfma_f32_16x16x32_bf16 v[128:131], v[136:139], v[176:179], v[128:131]
	v_mfma_f32_16x16x32_bf16 v[108:111], v[112:115], v[184:187], v[108:111]
	v_mfma_f32_16x16x32_bf16 v[104:107], v[136:139], v[184:187], v[104:107]
	v_mfma_f32_16x16x32_bf16 v[92:95], v[112:115], v[204:207], v[92:95]
	v_mfma_f32_16x16x32_bf16 v[88:91], v[136:139], v[204:207], v[88:91]
	v_mfma_f32_16x16x32_bf16 v[76:79], v[112:115], v[212:215], v[76:79]
	v_mfma_f32_16x16x32_bf16 v[72:75], v[136:139], v[212:215], v[72:75]
	v_mfma_f32_16x16x32_bf16 v[132:135], v[124:127], v[180:183], v[132:135]
	v_mfma_f32_16x16x32_bf16 v[128:131], v[140:143], v[180:183], v[128:131]
	v_mfma_f32_16x16x32_bf16 v[108:111], v[124:127], v[200:203], v[108:111]
	v_mfma_f32_16x16x32_bf16 v[104:107], v[140:143], v[200:203], v[104:107]
	v_mfma_f32_16x16x32_bf16 v[92:95], v[124:127], v[208:211], v[92:95]
	v_mfma_f32_16x16x32_bf16 v[88:91], v[140:143], v[208:211], v[88:91]
	v_mfma_f32_16x16x32_bf16 v[76:79], v[124:127], v[216:219], v[76:79]
	v_mfma_f32_16x16x32_bf16 v[72:75], v[140:143], v[216:219], v[72:75]
	v_mfma_f32_16x16x32_bf16 v[120:123], v[144:147], v[176:179], v[120:123]
	v_mfma_f32_16x16x32_bf16 v[116:119], v[168:171], v[176:179], v[116:119]
	v_mfma_f32_16x16x32_bf16 v[100:103], v[144:147], v[184:187], v[100:103]
	v_mfma_f32_16x16x32_bf16 v[96:99], v[168:171], v[184:187], v[96:99]
	v_mfma_f32_16x16x32_bf16 v[84:87], v[144:147], v[204:207], v[84:87]
	v_mfma_f32_16x16x32_bf16 v[80:83], v[168:171], v[204:207], v[80:83]
	v_mfma_f32_16x16x32_bf16 v[68:71], v[144:147], v[212:215], v[68:71]
	v_mfma_f32_16x16x32_bf16 v[64:67], v[168:171], v[212:215], v[64:67]
	v_mfma_f32_16x16x32_bf16 v[120:123], v[148:151], v[180:183], v[120:123]
	v_mfma_f32_16x16x32_bf16 v[116:119], v[172:175], v[180:183], v[116:119]
	v_mfma_f32_16x16x32_bf16 v[100:103], v[148:151], v[200:203], v[100:103]
	v_mfma_f32_16x16x32_bf16 v[96:99], v[172:175], v[200:203], v[96:99]
	v_mfma_f32_16x16x32_bf16 v[84:87], v[148:151], v[208:211], v[84:87]
	v_mfma_f32_16x16x32_bf16 v[80:83], v[172:175], v[208:211], v[80:83]
	v_mfma_f32_16x16x32_bf16 v[68:71], v[148:151], v[216:219], v[68:71]
	v_mfma_f32_16x16x32_bf16 v[64:67], v[172:175], v[216:219], v[64:67]
	s_barrier
	ds_read_b128 v[176:179], v195 offset:16384
	ds_read_b128 v[180:183], v195 offset:17408
	ds_read_b128 v[184:187], v195 offset:18432
	ds_read_b128 v[200:203], v195 offset:19456
	ds_read_b128 v[204:207], v195 offset:20480
	ds_read_b128 v[208:211], v195 offset:21504
	ds_read_b128 v[212:215], v195 offset:22528
	ds_read_b128 v[216:219], v195 offset:23552
	s_add_i32 s59, s50, s41
	v_lshl_add_u64 v[188:189], s[34:35], 0, v[154:155]
	s_mov_b32 m0, s59
	s_nop 0
	global_load_lds_dwordx4 v[188:189], off
	s_add_i32 m0, s59, 0x2000
	s_add_u32 s60, s34, 0x400000
	v_lshl_add_u64 v[220:221], s[34:35], 0, v[158:159]
	s_addc_u32 s61, s35, 0
	s_add_i32 s59, s51, s41
	global_load_lds_dwordx4 v[220:221], off
	v_lshl_add_u64 v[222:223], s[60:61], 0, v[154:155]
	s_mov_b32 m0, s59
	v_lshl_add_u64 v[224:225], s[36:37], 0, v[156:157]
	global_load_lds_dwordx4 v[222:223], off
	v_lshl_add_u64 v[222:223], s[60:61], 0, v[158:159]
	s_add_i32 m0, s59, 0x2000
	s_nop 0
	global_load_lds_dwordx4 v[222:223], off
	v_lshl_add_u64 v[222:223], s[36:37], 0, v[152:153]
	s_mov_b32 m0, s29
	s_nop 0
	global_load_lds_dwordx4 v[222:223], off
	s_mov_b32 m0, s42
	s_nop 0
	global_load_lds_dwordx4 v[224:225], off
	s_waitcnt vmcnt(8)
	s_waitcnt lgkmcnt(0)
	s_barrier
	s_waitcnt lgkmcnt(0)
	v_mfma_f32_16x16x32_bf16 v[60:63], v[112:115], v[176:179], v[60:63]
	v_mfma_f32_16x16x32_bf16 v[56:59], v[136:139], v[176:179], v[56:59]
	v_mfma_f32_16x16x32_bf16 v[44:47], v[112:115], v[184:187], v[44:47]
	v_mfma_f32_16x16x32_bf16 v[40:43], v[136:139], v[184:187], v[40:43]
	v_mfma_f32_16x16x32_bf16 v[28:31], v[112:115], v[204:207], v[28:31]
	v_mfma_f32_16x16x32_bf16 v[24:27], v[136:139], v[204:207], v[24:27]
	v_mfma_f32_16x16x32_bf16 v[12:15], v[112:115], v[212:215], v[12:15]
	v_mfma_f32_16x16x32_bf16 v[8:11], v[136:139], v[212:215], v[8:11]
	v_mfma_f32_16x16x32_bf16 v[60:63], v[124:127], v[180:183], v[60:63]
	v_mfma_f32_16x16x32_bf16 v[56:59], v[140:143], v[180:183], v[56:59]
	v_mfma_f32_16x16x32_bf16 v[44:47], v[124:127], v[200:203], v[44:47]
	v_mfma_f32_16x16x32_bf16 v[40:43], v[140:143], v[200:203], v[40:43]
	v_mfma_f32_16x16x32_bf16 v[28:31], v[124:127], v[208:211], v[28:31]
	v_mfma_f32_16x16x32_bf16 v[24:27], v[140:143], v[208:211], v[24:27]
	v_mfma_f32_16x16x32_bf16 v[12:15], v[124:127], v[216:219], v[12:15]
	v_mfma_f32_16x16x32_bf16 v[8:11], v[140:143], v[216:219], v[8:11]
	v_mfma_f32_16x16x32_bf16 v[52:55], v[144:147], v[176:179], v[52:55]
	v_mfma_f32_16x16x32_bf16 v[48:51], v[168:171], v[176:179], v[48:51]
	v_mfma_f32_16x16x32_bf16 v[36:39], v[144:147], v[184:187], v[36:39]
	v_mfma_f32_16x16x32_bf16 v[32:35], v[168:171], v[184:187], v[32:35]
	v_mfma_f32_16x16x32_bf16 v[20:23], v[144:147], v[204:207], v[20:23]
	v_mfma_f32_16x16x32_bf16 v[16:19], v[168:171], v[204:207], v[16:19]
	v_mfma_f32_16x16x32_bf16 v[4:7], v[144:147], v[212:215], v[4:7]
	v_mfma_f32_16x16x32_bf16 v[0:3], v[168:171], v[212:215], v[0:3]
	v_mfma_f32_16x16x32_bf16 v[52:55], v[148:151], v[180:183], v[52:55]
	v_mfma_f32_16x16x32_bf16 v[48:51], v[172:175], v[180:183], v[48:51]
	v_mfma_f32_16x16x32_bf16 v[36:39], v[148:151], v[200:203], v[36:39]
	v_mfma_f32_16x16x32_bf16 v[32:35], v[172:175], v[200:203], v[32:35]
	v_mfma_f32_16x16x32_bf16 v[20:23], v[148:151], v[208:211], v[20:23]
	v_mfma_f32_16x16x32_bf16 v[16:19], v[172:175], v[208:211], v[16:19]
	v_mfma_f32_16x16x32_bf16 v[4:7], v[148:151], v[216:219], v[4:7]
	v_mfma_f32_16x16x32_bf16 v[0:3], v[172:175], v[216:219], v[0:3]
	s_barrier
	ds_read_b128 v[176:179], v195 offset:32768
	ds_read_b128 v[180:183], v195 offset:33792
	ds_read_b128 v[184:187], v195 offset:34816
	ds_read_b128 v[200:203], v195 offset:35840
	ds_read_b128 v[204:207], v195 offset:36864
	ds_read_b128 v[208:211], v195 offset:37888
	ds_read_b128 v[212:215], v195 offset:38912
	ds_read_b128 v[216:219], v195 offset:39936
	s_add_i32 s59, 0, 0x18000
	s_add_i32 s60, 0, 0x1c000
	v_add_u32_e32 v140, s59, v191
	v_add_u32_e32 v172, s60, v191
	ds_read_b128 v[112:115], v140
	ds_read_b128 v[124:127], v140 offset:1024
	ds_read_b128 v[136:139], v140 offset:2048
	ds_read_b128 v[140:143], v140 offset:3072
	ds_read_b128 v[144:147], v172
	ds_read_b128 v[148:151], v172 offset:1024
	ds_read_b128 v[168:171], v172 offset:2048
	ds_read_b128 v[172:175], v172 offset:3072
	s_add_u32 s36, s36, 0x408000
	s_addc_u32 s37, s37, 0
	s_mov_b32 m0, s43
	v_lshl_add_u64 v[226:227], s[36:37], 0, v[152:153]
	global_load_lds_dwordx4 v[226:227], off
	v_lshl_add_u64 v[226:227], s[36:37], 0, v[156:157]
	s_mov_b32 m0, s44
	s_nop 0
	global_load_lds_dwordx4 v[226:227], off
	s_waitcnt vmcnt(8)
	s_waitcnt lgkmcnt(0)
	s_barrier
	s_waitcnt lgkmcnt(0)
	v_mfma_f32_16x16x32_bf16 v[132:135], v[112:115], v[176:179], v[132:135]
	v_mfma_f32_16x16x32_bf16 v[128:131], v[136:139], v[176:179], v[128:131]
	v_mfma_f32_16x16x32_bf16 v[108:111], v[112:115], v[184:187], v[108:111]
	v_mfma_f32_16x16x32_bf16 v[104:107], v[136:139], v[184:187], v[104:107]
	v_mfma_f32_16x16x32_bf16 v[92:95], v[112:115], v[204:207], v[92:95]
	v_mfma_f32_16x16x32_bf16 v[88:91], v[136:139], v[204:207], v[88:91]
	v_mfma_f32_16x16x32_bf16 v[76:79], v[112:115], v[212:215], v[76:79]
	v_mfma_f32_16x16x32_bf16 v[72:75], v[136:139], v[212:215], v[72:75]
	v_mfma_f32_16x16x32_bf16 v[132:135], v[124:127], v[180:183], v[132:135]
	v_mfma_f32_16x16x32_bf16 v[128:131], v[140:143], v[180:183], v[128:131]
	v_mfma_f32_16x16x32_bf16 v[108:111], v[124:127], v[200:203], v[108:111]
	v_mfma_f32_16x16x32_bf16 v[104:107], v[140:143], v[200:203], v[104:107]
	v_mfma_f32_16x16x32_bf16 v[92:95], v[124:127], v[208:211], v[92:95]
	v_mfma_f32_16x16x32_bf16 v[88:91], v[140:143], v[208:211], v[88:91]
	v_mfma_f32_16x16x32_bf16 v[76:79], v[124:127], v[216:219], v[76:79]
	v_mfma_f32_16x16x32_bf16 v[72:75], v[140:143], v[216:219], v[72:75]
	v_mfma_f32_16x16x32_bf16 v[120:123], v[144:147], v[176:179], v[120:123]
	v_mfma_f32_16x16x32_bf16 v[116:119], v[168:171], v[176:179], v[116:119]
	v_mfma_f32_16x16x32_bf16 v[100:103], v[144:147], v[184:187], v[100:103]
	v_mfma_f32_16x16x32_bf16 v[96:99], v[168:171], v[184:187], v[96:99]
	v_mfma_f32_16x16x32_bf16 v[84:87], v[144:147], v[204:207], v[84:87]
	v_mfma_f32_16x16x32_bf16 v[80:83], v[168:171], v[204:207], v[80:83]
	v_mfma_f32_16x16x32_bf16 v[68:71], v[144:147], v[212:215], v[68:71]
	v_mfma_f32_16x16x32_bf16 v[64:67], v[168:171], v[212:215], v[64:67]
	v_mfma_f32_16x16x32_bf16 v[120:123], v[148:151], v[180:183], v[120:123]
	v_mfma_f32_16x16x32_bf16 v[116:119], v[172:175], v[180:183], v[116:119]
	v_mfma_f32_16x16x32_bf16 v[100:103], v[148:151], v[200:203], v[100:103]
	v_mfma_f32_16x16x32_bf16 v[96:99], v[172:175], v[200:203], v[96:99]
	v_mfma_f32_16x16x32_bf16 v[84:87], v[148:151], v[208:211], v[84:87]
	v_mfma_f32_16x16x32_bf16 v[80:83], v[172:175], v[208:211], v[80:83]
	v_mfma_f32_16x16x32_bf16 v[68:71], v[148:151], v[216:219], v[68:71]
	v_mfma_f32_16x16x32_bf16 v[64:67], v[172:175], v[216:219], v[64:67]
	s_barrier
	ds_read_b128 v[176:179], v195 offset:49152
	ds_read_b128 v[180:183], v195 offset:50176
	ds_read_b128 v[184:187], v195 offset:51200
	ds_read_b128 v[200:203], v195 offset:52224
	ds_read_b128 v[204:207], v195 offset:53248
	ds_read_b128 v[208:211], v195 offset:54272
	ds_read_b128 v[212:215], v195 offset:55296
	ds_read_b128 v[216:219], v195 offset:56320
	s_add_i32 s36, s59, s41
	v_lshl_add_u64 v[188:189], v[188:189], 0, s[14:15]
	s_mov_b32 m0, s36
	s_nop 0
	global_load_lds_dwordx4 v[188:189], off
	s_add_i32 m0, s36, 0x2000
	s_add_u32 s34, s34, 0x400080
	v_lshl_add_u64 v[188:189], v[220:221], 0, s[14:15]
	s_addc_u32 s35, s35, 0
	s_add_i32 s36, s60, s41
	global_load_lds_dwordx4 v[188:189], off
	v_lshl_add_u64 v[188:189], s[34:35], 0, v[154:155]
	s_mov_b32 m0, s36
	s_nop 0
	global_load_lds_dwordx4 v[188:189], off
	v_lshl_add_u64 v[188:189], s[34:35], 0, v[158:159]
	s_add_i32 m0, s36, 0x2000
	s_nop 0
	global_load_lds_dwordx4 v[188:189], off
	v_lshl_add_u64 v[188:189], v[222:223], 0, s[14:15]
	s_mov_b32 m0, s46
	s_nop 0
	global_load_lds_dwordx4 v[188:189], off
	v_lshl_add_u64 v[188:189], v[224:225], 0, s[14:15]
	s_mov_b32 m0, s47
	s_nop 0
	global_load_lds_dwordx4 v[188:189], off
	s_waitcnt vmcnt(8)
	s_waitcnt lgkmcnt(0)
	s_barrier
	s_waitcnt lgkmcnt(0)
	v_mfma_f32_16x16x32_bf16 v[60:63], v[112:115], v[176:179], v[60:63]
	v_mfma_f32_16x16x32_bf16 v[56:59], v[136:139], v[176:179], v[56:59]
	v_mfma_f32_16x16x32_bf16 v[44:47], v[112:115], v[184:187], v[44:47]
	v_mfma_f32_16x16x32_bf16 v[40:43], v[136:139], v[184:187], v[40:43]
	v_mfma_f32_16x16x32_bf16 v[28:31], v[112:115], v[204:207], v[28:31]
	v_mfma_f32_16x16x32_bf16 v[24:27], v[136:139], v[204:207], v[24:27]
	v_mfma_f32_16x16x32_bf16 v[12:15], v[112:115], v[212:215], v[12:15]
	v_mfma_f32_16x16x32_bf16 v[8:11], v[136:139], v[212:215], v[8:11]
	v_mfma_f32_16x16x32_bf16 v[60:63], v[124:127], v[180:183], v[60:63]
	v_mfma_f32_16x16x32_bf16 v[56:59], v[140:143], v[180:183], v[56:59]
	v_mfma_f32_16x16x32_bf16 v[44:47], v[124:127], v[200:203], v[44:47]
	v_mfma_f32_16x16x32_bf16 v[40:43], v[140:143], v[200:203], v[40:43]
	v_mfma_f32_16x16x32_bf16 v[28:31], v[124:127], v[208:211], v[28:31]
	v_mfma_f32_16x16x32_bf16 v[24:27], v[140:143], v[208:211], v[24:27]
	v_mfma_f32_16x16x32_bf16 v[12:15], v[124:127], v[216:219], v[12:15]
	v_mfma_f32_16x16x32_bf16 v[8:11], v[140:143], v[216:219], v[8:11]
	v_mfma_f32_16x16x32_bf16 v[52:55], v[144:147], v[176:179], v[52:55]
	v_mfma_f32_16x16x32_bf16 v[48:51], v[168:171], v[176:179], v[48:51]
	v_mfma_f32_16x16x32_bf16 v[36:39], v[144:147], v[184:187], v[36:39]
	v_mfma_f32_16x16x32_bf16 v[32:35], v[168:171], v[184:187], v[32:35]
	v_mfma_f32_16x16x32_bf16 v[20:23], v[144:147], v[204:207], v[20:23]
	v_mfma_f32_16x16x32_bf16 v[16:19], v[168:171], v[204:207], v[16:19]
	v_mfma_f32_16x16x32_bf16 v[4:7], v[144:147], v[212:215], v[4:7]
	v_mfma_f32_16x16x32_bf16 v[0:3], v[168:171], v[212:215], v[0:3]
	v_mfma_f32_16x16x32_bf16 v[52:55], v[148:151], v[180:183], v[52:55]
	v_mfma_f32_16x16x32_bf16 v[48:51], v[172:175], v[180:183], v[48:51]
	v_mfma_f32_16x16x32_bf16 v[36:39], v[148:151], v[200:203], v[36:39]
	v_mfma_f32_16x16x32_bf16 v[32:35], v[172:175], v[200:203], v[32:35]
	v_mfma_f32_16x16x32_bf16 v[20:23], v[148:151], v[208:211], v[20:23]
	v_mfma_f32_16x16x32_bf16 v[16:19], v[172:175], v[208:211], v[16:19]
	v_mfma_f32_16x16x32_bf16 v[4:7], v[148:151], v[216:219], v[4:7]
	v_mfma_f32_16x16x32_bf16 v[0:3], v[172:175], v[216:219], v[0:3]
	s_barrier
	s_add_i32 s58, s58, 2
	s_add_u32 s56, s56, 0x100
	s_addc_u32 s57, s57, 0
	s_add_u32 s30, s30, 0x100
	s_addc_u32 s31, s31, 0
	s_cmpk_gt_u32 s58, 0xfd
	s_cbranch_scc0 .LBB0_635
	s_setprio 0
	s_and_b64 vcc, exec, s[16:17]
	s_cbranch_vccz .LBB0_638
	s_barrier

.Lsp_skip6:
.LBB0_726:
	ds_read_b128 v[144:147], v161
	ds_read_b128 v[148:151], v161 offset:1024
	ds_read_b128 v[168:171], v161 offset:2048
	ds_read_b128 v[172:175], v161 offset:3072
	ds_read_b128 v[176:179], v163
	ds_read_b128 v[180:183], v163 offset:1024
	ds_read_b128 v[184:187], v163 offset:2048
	ds_read_b128 v[188:191], v163 offset:3072
	ds_read_b128 v[192:195], v165
	ds_read_b128 v[196:199], v165 offset:1024
	ds_read_b128 v[200:203], v165 offset:2048
	ds_read_b128 v[204:207], v165 offset:3072
	ds_read_b128 v[208:211], v165 offset:4096
	ds_read_b128 v[212:215], v165 offset:5120
	ds_read_b128 v[216:219], v165 offset:6144
	ds_read_b128 v[220:223], v165 offset:7168
	s_add_u32 s6, s4, 0xfff80080
	s_addc_u32 s7, s5, -1
	s_cmp_eq_u32 s54, 28
	s_cselect_b32 s29, s1, s7
	s_cselect_b32 s28, s23, s6
	s_cselect_b32 s7, s21, s53
	s_cselect_b32 s6, s51, s52
	v_lshl_add_u64 v[152:153], s[4:5], 0, v[138:139]
	s_add_i32 m0, s38, 0xc000
	s_nop 0
	global_load_lds_dwordx4 v[152:153], off
	v_lshl_add_u64 v[152:153], s[4:5], 0, v[136:137]
	s_add_i32 m0, s38, 0xe000
	s_nop 0
	global_load_lds_dwordx4 v[152:153], off
	s_waitcnt vmcnt(8)
	s_waitcnt lgkmcnt(0)
	s_barrier
	s_waitcnt lgkmcnt(0)
	v_mfma_i32_16x16x64_i8 v[124:127], v[144:147], v[192:195], v[124:127]
	v_mfma_i32_16x16x64_i8 v[120:123], v[168:171], v[192:195], v[120:123]
	v_mfma_i32_16x16x64_i8 v[108:111], v[144:147], v[200:203], v[108:111]
	v_mfma_i32_16x16x64_i8 v[104:107], v[168:171], v[200:203], v[104:107]
	v_mfma_i32_16x16x64_i8 v[92:95], v[144:147], v[208:211], v[92:95]
	v_mfma_i32_16x16x64_i8 v[88:91], v[168:171], v[208:211], v[88:91]
	v_mfma_i32_16x16x64_i8 v[76:79], v[144:147], v[216:219], v[76:79]
	v_mfma_i32_16x16x64_i8 v[72:75], v[168:171], v[216:219], v[72:75]
	v_mfma_i32_16x16x64_i8 v[124:127], v[148:151], v[196:199], v[124:127]
	v_mfma_i32_16x16x64_i8 v[120:123], v[172:175], v[196:199], v[120:123]
	v_mfma_i32_16x16x64_i8 v[108:111], v[148:151], v[204:207], v[108:111]
	v_mfma_i32_16x16x64_i8 v[104:107], v[172:175], v[204:207], v[104:107]
	v_mfma_i32_16x16x64_i8 v[92:95], v[148:151], v[212:215], v[92:95]
	v_mfma_i32_16x16x64_i8 v[88:91], v[172:175], v[212:215], v[88:91]
	v_mfma_i32_16x16x64_i8 v[76:79], v[148:151], v[220:223], v[76:79]
	v_mfma_i32_16x16x64_i8 v[72:75], v[172:175], v[220:223], v[72:75]
	v_mfma_i32_16x16x64_i8 v[116:119], v[176:179], v[192:195], v[116:119]
	v_mfma_i32_16x16x64_i8 v[112:115], v[184:187], v[192:195], v[112:115]
	v_mfma_i32_16x16x64_i8 v[100:103], v[176:179], v[200:203], v[100:103]
	v_mfma_i32_16x16x64_i8 v[96:99], v[184:187], v[200:203], v[96:99]
	v_mfma_i32_16x16x64_i8 v[84:87], v[176:179], v[208:211], v[84:87]
	v_mfma_i32_16x16x64_i8 v[80:83], v[184:187], v[208:211], v[80:83]
	v_mfma_i32_16x16x64_i8 v[68:71], v[176:179], v[216:219], v[68:71]
	v_mfma_i32_16x16x64_i8 v[64:67], v[184:187], v[216:219], v[64:67]
	v_mfma_i32_16x16x64_i8 v[116:119], v[180:183], v[196:199], v[116:119]
	v_mfma_i32_16x16x64_i8 v[112:115], v[188:191], v[196:199], v[112:115]
	v_mfma_i32_16x16x64_i8 v[100:103], v[180:183], v[204:207], v[100:103]
	v_mfma_i32_16x16x64_i8 v[96:99], v[188:191], v[204:207], v[96:99]
	v_mfma_i32_16x16x64_i8 v[84:87], v[180:183], v[212:215], v[84:87]
	v_mfma_i32_16x16x64_i8 v[80:83], v[188:191], v[212:215], v[80:83]
	v_mfma_i32_16x16x64_i8 v[68:71], v[180:183], v[220:223], v[68:71]
	v_mfma_i32_16x16x64_i8 v[64:67], v[188:191], v[220:223], v[64:67]
	s_barrier
	ds_read_b128 v[192:195], v165 offset:16384
	ds_read_b128 v[196:199], v165 offset:17408
	ds_read_b128 v[200:203], v165 offset:18432
	ds_read_b128 v[204:207], v165 offset:19456
	ds_read_b128 v[208:211], v165 offset:20480
	ds_read_b128 v[212:215], v165 offset:21504
	ds_read_b128 v[216:219], v165 offset:22528
	ds_read_b128 v[220:223], v165 offset:23552
	s_add_i32 s55, s46, s35
	v_lshl_add_u64 v[152:153], s[6:7], 0, v[132:133]
	s_mov_b32 m0, s55
	s_nop 0
	global_load_lds_dwordx4 v[152:153], off
	s_add_i32 m0, s55, 0x2000
	s_add_u32 s56, s6, 0x80000
	v_lshl_add_u64 v[224:225], s[6:7], 0, v[128:129]
	s_addc_u32 s57, s7, 0
	s_add_i32 s55, s47, s35
	global_load_lds_dwordx4 v[224:225], off
	v_lshl_add_u64 v[226:227], s[56:57], 0, v[132:133]
	s_mov_b32 m0, s55
	v_lshl_add_u64 v[228:229], s[28:29], 0, v[130:131]
	global_load_lds_dwordx4 v[226:227], off
	v_lshl_add_u64 v[226:227], s[56:57], 0, v[128:129]
	s_add_i32 m0, s55, 0x2000
	s_nop 0
	global_load_lds_dwordx4 v[226:227], off
	v_lshl_add_u64 v[226:227], s[28:29], 0, v[134:135]
	s_mov_b32 m0, s38
	s_nop 0
	global_load_lds_dwordx4 v[226:227], off
	s_mov_b32 m0, s39
	s_nop 0
	global_load_lds_dwordx4 v[228:229], off
	s_waitcnt vmcnt(8)
	s_waitcnt lgkmcnt(0)
	s_barrier
	s_waitcnt lgkmcnt(0)
	v_mfma_i32_16x16x64_i8 v[60:63], v[144:147], v[192:195], v[60:63]
	v_mfma_i32_16x16x64_i8 v[56:59], v[168:171], v[192:195], v[56:59]
	v_mfma_i32_16x16x64_i8 v[44:47], v[144:147], v[200:203], v[44:47]
	v_mfma_i32_16x16x64_i8 v[40:43], v[168:171], v[200:203], v[40:43]
	v_mfma_i32_16x16x64_i8 v[28:31], v[144:147], v[208:211], v[28:31]
	v_mfma_i32_16x16x64_i8 v[24:27], v[168:171], v[208:211], v[24:27]
	v_mfma_i32_16x16x64_i8 v[12:15], v[144:147], v[216:219], v[12:15]
	v_mfma_i32_16x16x64_i8 v[8:11], v[168:171], v[216:219], v[8:11]
	v_mfma_i32_16x16x64_i8 v[60:63], v[148:151], v[196:199], v[60:63]
	v_mfma_i32_16x16x64_i8 v[56:59], v[172:175], v[196:199], v[56:59]
	v_mfma_i32_16x16x64_i8 v[44:47], v[148:151], v[204:207], v[44:47]
	v_mfma_i32_16x16x64_i8 v[40:43], v[172:175], v[204:207], v[40:43]
	v_mfma_i32_16x16x64_i8 v[28:31], v[148:151], v[212:215], v[28:31]
	v_mfma_i32_16x16x64_i8 v[24:27], v[172:175], v[212:215], v[24:27]
	v_mfma_i32_16x16x64_i8 v[12:15], v[148:151], v[220:223], v[12:15]
	v_mfma_i32_16x16x64_i8 v[8:11], v[172:175], v[220:223], v[8:11]
	v_mfma_i32_16x16x64_i8 v[52:55], v[176:179], v[192:195], v[52:55]
	v_mfma_i32_16x16x64_i8 v[48:51], v[184:187], v[192:195], v[48:51]
	v_mfma_i32_16x16x64_i8 v[36:39], v[176:179], v[200:203], v[36:39]
	v_mfma_i32_16x16x64_i8 v[32:35], v[184:187], v[200:203], v[32:35]
	v_mfma_i32_16x16x64_i8 v[20:23], v[176:179], v[208:211], v[20:23]
	v_mfma_i32_16x16x64_i8 v[16:19], v[184:187], v[208:211], v[16:19]
	v_mfma_i32_16x16x64_i8 v[4:7], v[176:179], v[216:219], v[4:7]
	v_mfma_i32_16x16x64_i8 v[0:3], v[184:187], v[216:219], v[0:3]
	v_mfma_i32_16x16x64_i8 v[52:55], v[180:183], v[196:199], v[52:55]
	v_mfma_i32_16x16x64_i8 v[48:51], v[188:191], v[196:199], v[48:51]
	v_mfma_i32_16x16x64_i8 v[36:39], v[180:183], v[204:207], v[36:39]
	v_mfma_i32_16x16x64_i8 v[32:35], v[188:191], v[204:207], v[32:35]
	v_mfma_i32_16x16x64_i8 v[20:23], v[180:183], v[212:215], v[20:23]
	v_mfma_i32_16x16x64_i8 v[16:19], v[188:191], v[212:215], v[16:19]
	v_mfma_i32_16x16x64_i8 v[4:7], v[180:183], v[220:223], v[4:7]
	v_mfma_i32_16x16x64_i8 v[0:3], v[188:191], v[220:223], v[0:3]
	s_barrier
	ds_read_b128 v[192:195], v165 offset:32768
	ds_read_b128 v[196:199], v165 offset:33792
	ds_read_b128 v[200:203], v165 offset:34816
	ds_read_b128 v[204:207], v165 offset:35840
	ds_read_b128 v[208:211], v165 offset:36864
	ds_read_b128 v[212:215], v165 offset:37888
	ds_read_b128 v[216:219], v165 offset:38912
	ds_read_b128 v[220:223], v165 offset:39936
	s_add_i32 s55, 0, 0x18000
	v_add_u32_e32 v154, s55, v157
	s_add_i32 s56, 0, 0x1c000
	ds_read_b128 v[144:147], v154
	ds_read_b128 v[148:151], v154 offset:1024
	ds_read_b128 v[168:171], v154 offset:2048
	ds_read_b128 v[172:175], v154 offset:3072
	v_add_u32_e32 v154, s56, v157
	ds_read_b128 v[176:179], v154
	ds_read_b128 v[180:183], v154 offset:1024
	ds_read_b128 v[184:187], v154 offset:2048
	ds_read_b128 v[188:191], v154 offset:3072
	s_add_u32 s28, s28, 0x80000
	s_addc_u32 s29, s29, 0
	s_mov_b32 m0, s40
	v_lshl_add_u64 v[230:231], s[28:29], 0, v[134:135]
	global_load_lds_dwordx4 v[230:231], off
	v_lshl_add_u64 v[230:231], s[28:29], 0, v[130:131]
	s_mov_b32 m0, s41
	s_nop 0
	global_load_lds_dwordx4 v[230:231], off
	s_waitcnt vmcnt(8)
	s_waitcnt lgkmcnt(0)
	s_barrier
	s_waitcnt lgkmcnt(0)
	v_mfma_i32_16x16x64_i8 v[124:127], v[144:147], v[192:195], v[124:127]
	v_mfma_i32_16x16x64_i8 v[120:123], v[168:171], v[192:195], v[120:123]
	v_mfma_i32_16x16x64_i8 v[108:111], v[144:147], v[200:203], v[108:111]
	v_mfma_i32_16x16x64_i8 v[104:107], v[168:171], v[200:203], v[104:107]
	v_mfma_i32_16x16x64_i8 v[92:95], v[144:147], v[208:211], v[92:95]
	v_mfma_i32_16x16x64_i8 v[88:91], v[168:171], v[208:211], v[88:91]
	v_mfma_i32_16x16x64_i8 v[76:79], v[144:147], v[216:219], v[76:79]
	v_mfma_i32_16x16x64_i8 v[72:75], v[168:171], v[216:219], v[72:75]
	v_mfma_i32_16x16x64_i8 v[124:127], v[148:151], v[196:199], v[124:127]
	v_mfma_i32_16x16x64_i8 v[120:123], v[172:175], v[196:199], v[120:123]
	v_mfma_i32_16x16x64_i8 v[108:111], v[148:151], v[204:207], v[108:111]
	v_mfma_i32_16x16x64_i8 v[104:107], v[172:175], v[204:207], v[104:107]
	v_mfma_i32_16x16x64_i8 v[92:95], v[148:151], v[212:215], v[92:95]
	v_mfma_i32_16x16x64_i8 v[88:91], v[172:175], v[212:215], v[88:91]
	v_mfma_i32_16x16x64_i8 v[76:79], v[148:151], v[220:223], v[76:79]
	v_mfma_i32_16x16x64_i8 v[72:75], v[172:175], v[220:223], v[72:75]
	v_mfma_i32_16x16x64_i8 v[116:119], v[176:179], v[192:195], v[116:119]
	v_mfma_i32_16x16x64_i8 v[112:115], v[184:187], v[192:195], v[112:115]
	v_mfma_i32_16x16x64_i8 v[100:103], v[176:179], v[200:203], v[100:103]
	v_mfma_i32_16x16x64_i8 v[96:99], v[184:187], v[200:203], v[96:99]
	v_mfma_i32_16x16x64_i8 v[84:87], v[176:179], v[208:211], v[84:87]
	v_mfma_i32_16x16x64_i8 v[80:83], v[184:187], v[208:211], v[80:83]
	v_mfma_i32_16x16x64_i8 v[68:71], v[176:179], v[216:219], v[68:71]
	v_mfma_i32_16x16x64_i8 v[64:67], v[184:187], v[216:219], v[64:67]
	v_mfma_i32_16x16x64_i8 v[116:119], v[180:183], v[196:199], v[116:119]
	v_mfma_i32_16x16x64_i8 v[112:115], v[188:191], v[196:199], v[112:115]
	v_mfma_i32_16x16x64_i8 v[100:103], v[180:183], v[204:207], v[100:103]
	v_mfma_i32_16x16x64_i8 v[96:99], v[188:191], v[204:207], v[96:99]
	v_mfma_i32_16x16x64_i8 v[84:87], v[180:183], v[212:215], v[84:87]
	v_mfma_i32_16x16x64_i8 v[80:83], v[188:191], v[212:215], v[80:83]
	v_mfma_i32_16x16x64_i8 v[68:71], v[180:183], v[220:223], v[68:71]
	v_mfma_i32_16x16x64_i8 v[64:67], v[188:191], v[220:223], v[64:67]
	s_barrier
	ds_read_b128 v[192:195], v165 offset:49152
	ds_read_b128 v[196:199], v165 offset:50176
	ds_read_b128 v[200:203], v165 offset:51200
	ds_read_b128 v[204:207], v165 offset:52224
	ds_read_b128 v[208:211], v165 offset:53248
	ds_read_b128 v[212:215], v165 offset:54272
	ds_read_b128 v[216:219], v165 offset:55296
	ds_read_b128 v[220:223], v165 offset:56320
	s_add_i32 s28, s55, s35
	v_lshl_add_u64 v[152:153], v[152:153], 0, s[16:17]
	s_mov_b32 m0, s28
	s_nop 0
	global_load_lds_dwordx4 v[152:153], off
	s_add_i32 m0, s28, 0x2000
	s_add_u32 s6, s6, 0x80080
	v_lshl_add_u64 v[152:153], v[224:225], 0, s[16:17]
	s_addc_u32 s7, s7, 0
	s_add_i32 s28, s56, s35
	global_load_lds_dwordx4 v[152:153], off
	v_lshl_add_u64 v[152:153], s[6:7], 0, v[132:133]
	s_mov_b32 m0, s28
	s_nop 0
	global_load_lds_dwordx4 v[152:153], off
	v_lshl_add_u64 v[152:153], s[6:7], 0, v[128:129]
	s_add_i32 m0, s28, 0x2000
	s_nop 0
	global_load_lds_dwordx4 v[152:153], off
	v_lshl_add_u64 v[152:153], v[226:227], 0, s[16:17]
	s_mov_b32 m0, s43
	s_nop 0
	global_load_lds_dwordx4 v[152:153], off
	v_lshl_add_u64 v[152:153], v[228:229], 0, s[16:17]
	s_mov_b32 m0, s44
	s_nop 0
	global_load_lds_dwordx4 v[152:153], off
	s_waitcnt vmcnt(8)
	s_waitcnt lgkmcnt(0)
	s_barrier
	s_waitcnt lgkmcnt(0)
	v_mfma_i32_16x16x64_i8 v[60:63], v[144:147], v[192:195], v[60:63]
	v_mfma_i32_16x16x64_i8 v[56:59], v[168:171], v[192:195], v[56:59]
	v_mfma_i32_16x16x64_i8 v[44:47], v[144:147], v[200:203], v[44:47]
	v_mfma_i32_16x16x64_i8 v[40:43], v[168:171], v[200:203], v[40:43]
	v_mfma_i32_16x16x64_i8 v[28:31], v[144:147], v[208:211], v[28:31]
	v_mfma_i32_16x16x64_i8 v[24:27], v[168:171], v[208:211], v[24:27]
	v_mfma_i32_16x16x64_i8 v[12:15], v[144:147], v[216:219], v[12:15]
	v_mfma_i32_16x16x64_i8 v[8:11], v[168:171], v[216:219], v[8:11]
	v_mfma_i32_16x16x64_i8 v[60:63], v[148:151], v[196:199], v[60:63]
	v_mfma_i32_16x16x64_i8 v[56:59], v[172:175], v[196:199], v[56:59]
	v_mfma_i32_16x16x64_i8 v[44:47], v[148:151], v[204:207], v[44:47]
	v_mfma_i32_16x16x64_i8 v[40:43], v[172:175], v[204:207], v[40:43]
	v_mfma_i32_16x16x64_i8 v[28:31], v[148:151], v[212:215], v[28:31]
	v_mfma_i32_16x16x64_i8 v[24:27], v[172:175], v[212:215], v[24:27]
	v_mfma_i32_16x16x64_i8 v[12:15], v[148:151], v[220:223], v[12:15]
	v_mfma_i32_16x16x64_i8 v[8:11], v[172:175], v[220:223], v[8:11]
	v_mfma_i32_16x16x64_i8 v[52:55], v[176:179], v[192:195], v[52:55]
	v_mfma_i32_16x16x64_i8 v[48:51], v[184:187], v[192:195], v[48:51]
	v_mfma_i32_16x16x64_i8 v[36:39], v[176:179], v[200:203], v[36:39]
	v_mfma_i32_16x16x64_i8 v[32:35], v[184:187], v[200:203], v[32:35]
	v_mfma_i32_16x16x64_i8 v[20:23], v[176:179], v[208:211], v[20:23]
	v_mfma_i32_16x16x64_i8 v[16:19], v[184:187], v[208:211], v[16:19]
	v_mfma_i32_16x16x64_i8 v[4:7], v[176:179], v[216:219], v[4:7]
	v_mfma_i32_16x16x64_i8 v[0:3], v[184:187], v[216:219], v[0:3]
	v_mfma_i32_16x16x64_i8 v[52:55], v[180:183], v[196:199], v[52:55]
	v_mfma_i32_16x16x64_i8 v[48:51], v[188:191], v[196:199], v[48:51]
	v_mfma_i32_16x16x64_i8 v[36:39], v[180:183], v[204:207], v[36:39]
	v_mfma_i32_16x16x64_i8 v[32:35], v[188:191], v[204:207], v[32:35]
	v_mfma_i32_16x16x64_i8 v[20:23], v[180:183], v[212:215], v[20:23]
	v_mfma_i32_16x16x64_i8 v[16:19], v[188:191], v[212:215], v[16:19]
	v_mfma_i32_16x16x64_i8 v[4:7], v[180:183], v[220:223], v[4:7]
	v_mfma_i32_16x16x64_i8 v[0:3], v[188:191], v[220:223], v[0:3]
	s_barrier
	s_add_i32 s54, s54, 2
	s_add_u32 s52, s52, 0x100
	s_addc_u32 s53, s53, 0
	s_add_u32 s4, s4, 0x100
	s_addc_u32 s5, s5, 0
	s_cmp_gt_u32 s54, 29
	s_cbranch_scc0 .LBB0_726
	s_setprio 0
	s_and_b64 vcc, exec, s[18:19]
	s_cbranch_vccz .LBB0_729
	s_barrier

.Lsp_skip7:
.LBB0_1255:
	ds_read_b128 v[16:19], v193
	ds_read_b128 v[20:23], v193 offset:1024
	ds_read_b128 v[24:27], v193 offset:2048
	ds_read_b128 v[28:31], v193 offset:3072
	ds_read_b128 v[0:3], v194
	ds_read_b128 v[4:7], v194 offset:1024
	ds_read_b128 v[8:11], v194 offset:2048
	ds_read_b128 v[12:15], v194 offset:3072
	ds_read_b128 v[176:179], v195
	ds_read_b128 v[180:183], v195 offset:1024
	ds_read_b128 v[200:203], v195 offset:2048
	ds_read_b128 v[204:207], v195 offset:3072
	ds_read_b128 v[208:211], v195 offset:4096
	ds_read_b128 v[212:215], v195 offset:5120
	ds_read_b128 v[216:219], v195 offset:6144
	ds_read_b128 v[220:223], v195 offset:7168
	s_waitcnt lgkmcnt(0)
	s_add_u32 s36, s34, 0xfffc0080
	s_addc_u32 s37, s35, -1
	s_cmp_eq_u32 s59, 12
	s_cselect_b32 s39, s23, s37
	s_cselect_b32 s38, s29, s36
	s_cselect_b32 s37, s21, s58
	s_cselect_b32 s36, s56, s57
	v_lshl_add_u64 v[184:185], s[34:35], 0, v[170:171]
	s_add_i32 m0, s31, 0xc000
	s_nop 0
	global_load_lds_dwordx4 v[184:185], off
	v_lshl_add_u64 v[184:185], s[34:35], 0, v[168:169]
	s_add_i32 m0, s31, 0xe000
	s_nop 0
	global_load_lds_dwordx4 v[184:185], off
	s_waitcnt vmcnt(8)
	s_waitcnt lgkmcnt(0)
	s_barrier
	s_waitcnt lgkmcnt(0)
	v_mfma_scale_f32_16x16x128_f8f6f4 v[156:159], v[16:23], v[176:183], v[156:159], v196, v196 op_sel_hi:[0,0,0]
	v_mfma_scale_f32_16x16x128_f8f6f4 v[152:155], v[24:31], v[176:183], v[152:155], v196, v196 op_sel_hi:[0,0,0]
	v_mfma_scale_f32_16x16x128_f8f6f4 v[140:143], v[16:23], v[200:207], v[140:143], v196, v196 op_sel_hi:[0,0,0]
	v_mfma_scale_f32_16x16x128_f8f6f4 v[136:139], v[24:31], v[200:207], v[136:139], v196, v196 op_sel_hi:[0,0,0]
	v_mfma_scale_f32_16x16x128_f8f6f4 v[124:127], v[16:23], v[208:215], v[124:127], v196, v196 op_sel_hi:[0,0,0]
	v_mfma_scale_f32_16x16x128_f8f6f4 v[120:123], v[24:31], v[208:215], v[120:123], v196, v196 op_sel_hi:[0,0,0]
	v_mfma_scale_f32_16x16x128_f8f6f4 v[108:111], v[16:23], v[216:223], v[108:111], v196, v196 op_sel_hi:[0,0,0]
	v_mfma_scale_f32_16x16x128_f8f6f4 v[104:107], v[24:31], v[216:223], v[104:107], v196, v196 op_sel_hi:[0,0,0]
	v_mfma_scale_f32_16x16x128_f8f6f4 v[148:151], v[0:7], v[176:183], v[148:151], v196, v196 op_sel_hi:[0,0,0]
	v_mfma_scale_f32_16x16x128_f8f6f4 v[144:147], v[8:15], v[176:183], v[144:147], v196, v196 op_sel_hi:[0,0,0]
	v_mfma_scale_f32_16x16x128_f8f6f4 v[132:135], v[0:7], v[200:207], v[132:135], v196, v196 op_sel_hi:[0,0,0]
	v_mfma_scale_f32_16x16x128_f8f6f4 v[128:131], v[8:15], v[200:207], v[128:131], v196, v196 op_sel_hi:[0,0,0]
	v_mfma_scale_f32_16x16x128_f8f6f4 v[116:119], v[0:7], v[208:215], v[116:119], v196, v196 op_sel_hi:[0,0,0]
	v_mfma_scale_f32_16x16x128_f8f6f4 v[112:115], v[8:15], v[208:215], v[112:115], v196, v196 op_sel_hi:[0,0,0]
	v_mfma_scale_f32_16x16x128_f8f6f4 v[100:103], v[0:7], v[216:223], v[100:103], v196, v196 op_sel_hi:[0,0,0]
	v_mfma_scale_f32_16x16x128_f8f6f4 v[96:99], v[8:15], v[216:223], v[96:99], v196, v196 op_sel_hi:[0,0,0]
	s_barrier
	ds_read_b128 v[200:203], v195 offset:16384
	ds_read_b128 v[204:207], v195 offset:17408
	ds_read_b128 v[208:211], v195 offset:18432
	ds_read_b128 v[212:215], v195 offset:19456
	ds_read_b128 v[216:219], v195 offset:20480
	ds_read_b128 v[220:223], v195 offset:21504
	ds_read_b128 v[224:227], v195 offset:22528
	ds_read_b128 v[228:231], v195 offset:23552
	s_add_i32 s60, s51, s42
	v_lshl_add_u64 v[176:177], s[36:37], 0, v[162:163]
	s_mov_b32 m0, s60
	s_nop 0
	global_load_lds_dwordx4 v[176:177], off
	s_add_i32 m0, s60, 0x2000
	s_add_u32 s60, s36, 0x40000
	v_lshl_add_u64 v[178:179], s[36:37], 0, v[166:167]
	s_addc_u32 s61, s37, 0
	s_add_i32 s62, s52, s42
	global_load_lds_dwordx4 v[178:179], off
	v_lshl_add_u64 v[180:181], s[60:61], 0, v[162:163]
	s_mov_b32 m0, s62
	v_lshl_add_u64 v[182:183], s[38:39], 0, v[164:165]
	global_load_lds_dwordx4 v[180:181], off
	v_lshl_add_u64 v[180:181], s[60:61], 0, v[166:167]
	s_add_i32 m0, s62, 0x2000
	s_nop 0
	global_load_lds_dwordx4 v[180:181], off
	v_lshl_add_u64 v[180:181], s[38:39], 0, v[160:161]
	s_mov_b32 m0, s31
	s_nop 0
	global_load_lds_dwordx4 v[180:181], off
	s_mov_b32 m0, s43
	s_nop 0
	global_load_lds_dwordx4 v[182:183], off
	s_waitcnt vmcnt(8)
	s_waitcnt lgkmcnt(0)
	s_barrier
	s_waitcnt lgkmcnt(0)
	v_mfma_scale_f32_16x16x128_f8f6f4 v[92:95], v[16:23], v[200:207], v[92:95], v196, v196 op_sel_hi:[0,0,0]
	v_mfma_scale_f32_16x16x128_f8f6f4 v[88:91], v[24:31], v[200:207], v[88:91], v196, v196 op_sel_hi:[0,0,0]
	v_mfma_scale_f32_16x16x128_f8f6f4 v[76:79], v[16:23], v[208:215], v[76:79], v196, v196 op_sel_hi:[0,0,0]
	v_mfma_scale_f32_16x16x128_f8f6f4 v[72:75], v[24:31], v[208:215], v[72:75], v196, v196 op_sel_hi:[0,0,0]
	v_mfma_scale_f32_16x16x128_f8f6f4 v[60:63], v[16:23], v[216:223], v[60:63], v196, v196 op_sel_hi:[0,0,0]
	v_mfma_scale_f32_16x16x128_f8f6f4 v[56:59], v[24:31], v[216:223], v[56:59], v196, v196 op_sel_hi:[0,0,0]
	v_mfma_scale_f32_16x16x128_f8f6f4 v[44:47], v[16:23], v[224:231], v[44:47], v196, v196 op_sel_hi:[0,0,0]
	v_mfma_scale_f32_16x16x128_f8f6f4 v[40:43], v[24:31], v[224:231], v[40:43], v196, v196 op_sel_hi:[0,0,0]
	v_mfma_scale_f32_16x16x128_f8f6f4 v[84:87], v[0:7], v[200:207], v[84:87], v196, v196 op_sel_hi:[0,0,0]
	v_mfma_scale_f32_16x16x128_f8f6f4 v[80:83], v[8:15], v[200:207], v[80:83], v196, v196 op_sel_hi:[0,0,0]
	v_mfma_scale_f32_16x16x128_f8f6f4 v[68:71], v[0:7], v[208:215], v[68:71], v196, v196 op_sel_hi:[0,0,0]
	v_mfma_scale_f32_16x16x128_f8f6f4 v[64:67], v[8:15], v[208:215], v[64:67], v196, v196 op_sel_hi:[0,0,0]
	v_mfma_scale_f32_16x16x128_f8f6f4 v[52:55], v[0:7], v[216:223], v[52:55], v196, v196 op_sel_hi:[0,0,0]
	v_mfma_scale_f32_16x16x128_f8f6f4 v[48:51], v[8:15], v[216:223], v[48:51], v196, v196 op_sel_hi:[0,0,0]
	v_mfma_scale_f32_16x16x128_f8f6f4 v[36:39], v[0:7], v[224:231], v[36:39], v196, v196 op_sel_hi:[0,0,0]
	v_mfma_scale_f32_16x16x128_f8f6f4 v[32:35], v[8:15], v[224:231], v[32:35], v196, v196 op_sel_hi:[0,0,0]
	s_barrier
	ds_read_b128 v[200:203], v195 offset:32768
	ds_read_b128 v[204:207], v195 offset:33792
	ds_read_b128 v[208:211], v195 offset:34816
	ds_read_b128 v[212:215], v195 offset:35840
	ds_read_b128 v[216:219], v195 offset:36864
	ds_read_b128 v[220:223], v195 offset:37888
	ds_read_b128 v[224:227], v195 offset:38912
	ds_read_b128 v[228:231], v195 offset:39936
	s_add_i32 s60, 0, 0x18000
	s_add_i32 s61, 0, 0x1c000
	v_add_u32_e32 v12, s60, v191
	v_add_u32_e32 v28, s61, v191
	ds_read_b128 v[0:3], v12
	ds_read_b128 v[4:7], v12 offset:1024
	ds_read_b128 v[8:11], v12 offset:2048
	ds_read_b128 v[12:15], v12 offset:3072
	ds_read_b128 v[16:19], v28
	ds_read_b128 v[20:23], v28 offset:1024
	ds_read_b128 v[24:27], v28 offset:2048
	ds_read_b128 v[28:31], v28 offset:3072
	s_add_u32 s38, s38, 0x40000
	s_addc_u32 s39, s39, 0
	s_mov_b32 m0, s44
	v_lshl_add_u64 v[184:185], s[38:39], 0, v[160:161]
	global_load_lds_dwordx4 v[184:185], off
	v_lshl_add_u64 v[184:185], s[38:39], 0, v[164:165]
	s_mov_b32 m0, s45
	s_nop 0
	global_load_lds_dwordx4 v[184:185], off
	s_waitcnt vmcnt(8)
	s_waitcnt lgkmcnt(0)
	s_barrier
	s_waitcnt lgkmcnt(0)
	v_mfma_scale_f32_16x16x128_f8f6f4 v[156:159], v[0:7], v[200:207], v[156:159], v196, v196 op_sel_hi:[0,0,0]
	v_mfma_scale_f32_16x16x128_f8f6f4 v[152:155], v[8:15], v[200:207], v[152:155], v196, v196 op_sel_hi:[0,0,0]
	v_mfma_scale_f32_16x16x128_f8f6f4 v[140:143], v[0:7], v[208:215], v[140:143], v196, v196 op_sel_hi:[0,0,0]
	v_mfma_scale_f32_16x16x128_f8f6f4 v[136:139], v[8:15], v[208:215], v[136:139], v196, v196 op_sel_hi:[0,0,0]
	v_mfma_scale_f32_16x16x128_f8f6f4 v[124:127], v[0:7], v[216:223], v[124:127], v196, v196 op_sel_hi:[0,0,0]
	v_mfma_scale_f32_16x16x128_f8f6f4 v[120:123], v[8:15], v[216:223], v[120:123], v196, v196 op_sel_hi:[0,0,0]
	v_mfma_scale_f32_16x16x128_f8f6f4 v[108:111], v[0:7], v[224:231], v[108:111], v196, v196 op_sel_hi:[0,0,0]
	v_mfma_scale_f32_16x16x128_f8f6f4 v[104:107], v[8:15], v[224:231], v[104:107], v196, v196 op_sel_hi:[0,0,0]
	v_mfma_scale_f32_16x16x128_f8f6f4 v[148:151], v[16:23], v[200:207], v[148:151], v196, v196 op_sel_hi:[0,0,0]
	v_mfma_scale_f32_16x16x128_f8f6f4 v[144:147], v[24:31], v[200:207], v[144:147], v196, v196 op_sel_hi:[0,0,0]
	v_mfma_scale_f32_16x16x128_f8f6f4 v[132:135], v[16:23], v[208:215], v[132:135], v196, v196 op_sel_hi:[0,0,0]
	v_mfma_scale_f32_16x16x128_f8f6f4 v[128:131], v[24:31], v[208:215], v[128:131], v196, v196 op_sel_hi:[0,0,0]
	v_mfma_scale_f32_16x16x128_f8f6f4 v[116:119], v[16:23], v[216:223], v[116:119], v196, v196 op_sel_hi:[0,0,0]
	v_mfma_scale_f32_16x16x128_f8f6f4 v[112:115], v[24:31], v[216:223], v[112:115], v196, v196 op_sel_hi:[0,0,0]
	v_mfma_scale_f32_16x16x128_f8f6f4 v[100:103], v[16:23], v[224:231], v[100:103], v196, v196 op_sel_hi:[0,0,0]
	v_mfma_scale_f32_16x16x128_f8f6f4 v[96:99], v[24:31], v[224:231], v[96:99], v196, v196 op_sel_hi:[0,0,0]
	s_barrier
	ds_read_b128 v[200:203], v195 offset:49152
	ds_read_b128 v[204:207], v195 offset:50176
	ds_read_b128 v[208:211], v195 offset:51200
	ds_read_b128 v[212:215], v195 offset:52224
	ds_read_b128 v[216:219], v195 offset:53248
	ds_read_b128 v[220:223], v195 offset:54272
	ds_read_b128 v[224:227], v195 offset:55296
	ds_read_b128 v[228:231], v195 offset:56320
	s_add_i32 s38, s60, s42
	v_lshl_add_u64 v[176:177], v[176:177], 0, s[14:15]
	s_mov_b32 m0, s38
	s_nop 0
	global_load_lds_dwordx4 v[176:177], off
	s_add_i32 m0, s38, 0x2000
	s_add_u32 s36, s36, 0x40080
	v_lshl_add_u64 v[176:177], v[178:179], 0, s[14:15]
	s_addc_u32 s37, s37, 0
	s_add_i32 s38, s61, s42
	global_load_lds_dwordx4 v[176:177], off
	v_lshl_add_u64 v[176:177], s[36:37], 0, v[162:163]
	s_mov_b32 m0, s38
	s_nop 0
	global_load_lds_dwordx4 v[176:177], off
	v_lshl_add_u64 v[176:177], s[36:37], 0, v[166:167]
	s_add_i32 m0, s38, 0x2000
	s_nop 0
	global_load_lds_dwordx4 v[176:177], off
	v_lshl_add_u64 v[176:177], v[180:181], 0, s[14:15]
	s_mov_b32 m0, s47
	s_nop 0
	global_load_lds_dwordx4 v[176:177], off
	v_lshl_add_u64 v[176:177], v[182:183], 0, s[14:15]
	s_mov_b32 m0, s48
	s_nop 0
	global_load_lds_dwordx4 v[176:177], off
	s_waitcnt vmcnt(8)
	s_waitcnt lgkmcnt(0)
	s_barrier
	s_waitcnt lgkmcnt(0)
	v_mfma_scale_f32_16x16x128_f8f6f4 v[92:95], v[0:7], v[200:207], v[92:95], v196, v196 op_sel_hi:[0,0,0]
	v_mfma_scale_f32_16x16x128_f8f6f4 v[88:91], v[8:15], v[200:207], v[88:91], v196, v196 op_sel_hi:[0,0,0]
	v_mfma_scale_f32_16x16x128_f8f6f4 v[76:79], v[0:7], v[208:215], v[76:79], v196, v196 op_sel_hi:[0,0,0]
	v_mfma_scale_f32_16x16x128_f8f6f4 v[72:75], v[8:15], v[208:215], v[72:75], v196, v196 op_sel_hi:[0,0,0]
	v_mfma_scale_f32_16x16x128_f8f6f4 v[60:63], v[0:7], v[216:223], v[60:63], v196, v196 op_sel_hi:[0,0,0]
	v_mfma_scale_f32_16x16x128_f8f6f4 v[56:59], v[8:15], v[216:223], v[56:59], v196, v196 op_sel_hi:[0,0,0]
	v_mfma_scale_f32_16x16x128_f8f6f4 v[44:47], v[0:7], v[224:231], v[44:47], v196, v196 op_sel_hi:[0,0,0]
	v_mfma_scale_f32_16x16x128_f8f6f4 v[40:43], v[8:15], v[224:231], v[40:43], v196, v196 op_sel_hi:[0,0,0]
	v_mfma_scale_f32_16x16x128_f8f6f4 v[84:87], v[16:23], v[200:207], v[84:87], v196, v196 op_sel_hi:[0,0,0]
	v_mfma_scale_f32_16x16x128_f8f6f4 v[80:83], v[24:31], v[200:207], v[80:83], v196, v196 op_sel_hi:[0,0,0]
	v_mfma_scale_f32_16x16x128_f8f6f4 v[68:71], v[16:23], v[208:215], v[68:71], v196, v196 op_sel_hi:[0,0,0]
	v_mfma_scale_f32_16x16x128_f8f6f4 v[64:67], v[24:31], v[208:215], v[64:67], v196, v196 op_sel_hi:[0,0,0]
	v_mfma_scale_f32_16x16x128_f8f6f4 v[52:55], v[16:23], v[216:223], v[52:55], v196, v196 op_sel_hi:[0,0,0]
	v_mfma_scale_f32_16x16x128_f8f6f4 v[48:51], v[24:31], v[216:223], v[48:51], v196, v196 op_sel_hi:[0,0,0]
	v_mfma_scale_f32_16x16x128_f8f6f4 v[36:39], v[16:23], v[224:231], v[36:39], v196, v196 op_sel_hi:[0,0,0]
	v_mfma_scale_f32_16x16x128_f8f6f4 v[32:35], v[24:31], v[224:231], v[32:35], v196, v196 op_sel_hi:[0,0,0]
	s_barrier
	s_add_i32 s59, s59, 2
	s_add_u32 s57, s57, 0x100
	s_addc_u32 s58, s58, 0
	s_add_u32 s34, s34, 0x100
	s_addc_u32 s35, s35, 0
	s_cmp_gt_u32 s59, 13
	s_cbranch_scc0 .LBB0_1255
	s_setprio 0
	s_and_b64 vcc, exec, s[16:17]
	s_cbranch_vccz .LBB0_1258
	s_barrier

.Lsp_skip8:
.LBB0_1356:
	ds_read_b128 v[144:147], v180
	ds_read_b128 v[148:151], v180 offset:1024
	ds_read_b128 v[152:155], v180 offset:2048
	ds_read_b128 v[156:159], v180 offset:3072
	ds_read_b128 v[160:163], v181
	ds_read_b128 v[164:167], v181 offset:1024
	ds_read_b128 v[168:171], v181 offset:2048
	ds_read_b128 v[172:175], v181 offset:3072
	ds_read_b128 v[186:189], v182
	ds_read_b128 v[190:193], v182 offset:1024
	ds_read_b128 v[194:197], v182 offset:2048
	ds_read_b128 v[198:201], v182 offset:3072
	ds_read_b128 v[202:205], v182 offset:4096
	ds_read_b128 v[206:209], v182 offset:5120
	ds_read_b128 v[210:213], v182 offset:6144
	ds_read_b128 v[214:217], v182 offset:7168
	s_add_u32 s34, s30, 0xfff80080
	s_addc_u32 s35, s31, -1
	s_cmp_eq_u32 s58, 28
	s_cselect_b32 s37, s1, s35
	s_cselect_b32 s36, s23, s34
	s_cselect_b32 s35, s21, s57
	s_cselect_b32 s34, s29, s33
	v_lshl_add_u64 v[218:219], s[30:31], 0, v[138:139]
	s_add_i32 m0, s43, 0xc000
	s_nop 0
	global_load_lds_dwordx4 v[218:219], off
	v_lshl_add_u64 v[218:219], s[30:31], 0, v[136:137]
	s_add_i32 m0, s43, 0xe000
	s_nop 0
	global_load_lds_dwordx4 v[218:219], off
	s_waitcnt vmcnt(8)
	s_waitcnt lgkmcnt(0)
	s_barrier
	s_waitcnt lgkmcnt(0)
	v_mfma_i32_16x16x64_i8 v[124:127], v[144:147], v[186:189], v[124:127]
	v_mfma_i32_16x16x64_i8 v[120:123], v[152:155], v[186:189], v[120:123]
	v_mfma_i32_16x16x64_i8 v[108:111], v[144:147], v[194:197], v[108:111]
	v_mfma_i32_16x16x64_i8 v[104:107], v[152:155], v[194:197], v[104:107]
	v_mfma_i32_16x16x64_i8 v[92:95], v[144:147], v[202:205], v[92:95]
	v_mfma_i32_16x16x64_i8 v[88:91], v[152:155], v[202:205], v[88:91]
	v_mfma_i32_16x16x64_i8 v[76:79], v[144:147], v[210:213], v[76:79]
	v_mfma_i32_16x16x64_i8 v[72:75], v[152:155], v[210:213], v[72:75]
	v_mfma_i32_16x16x64_i8 v[124:127], v[148:151], v[190:193], v[124:127]
	v_mfma_i32_16x16x64_i8 v[120:123], v[156:159], v[190:193], v[120:123]
	v_mfma_i32_16x16x64_i8 v[108:111], v[148:151], v[198:201], v[108:111]
	v_mfma_i32_16x16x64_i8 v[104:107], v[156:159], v[198:201], v[104:107]
	v_mfma_i32_16x16x64_i8 v[92:95], v[148:151], v[206:209], v[92:95]
	v_mfma_i32_16x16x64_i8 v[88:91], v[156:159], v[206:209], v[88:91]
	v_mfma_i32_16x16x64_i8 v[76:79], v[148:151], v[214:217], v[76:79]
	v_mfma_i32_16x16x64_i8 v[72:75], v[156:159], v[214:217], v[72:75]
	v_mfma_i32_16x16x64_i8 v[116:119], v[160:163], v[186:189], v[116:119]
	v_mfma_i32_16x16x64_i8 v[112:115], v[168:171], v[186:189], v[112:115]
	v_mfma_i32_16x16x64_i8 v[100:103], v[160:163], v[194:197], v[100:103]
	v_mfma_i32_16x16x64_i8 v[96:99], v[168:171], v[194:197], v[96:99]
	v_mfma_i32_16x16x64_i8 v[84:87], v[160:163], v[202:205], v[84:87]
	v_mfma_i32_16x16x64_i8 v[80:83], v[168:171], v[202:205], v[80:83]
	v_mfma_i32_16x16x64_i8 v[68:71], v[160:163], v[210:213], v[68:71]
	v_mfma_i32_16x16x64_i8 v[64:67], v[168:171], v[210:213], v[64:67]
	v_mfma_i32_16x16x64_i8 v[116:119], v[164:167], v[190:193], v[116:119]
	v_mfma_i32_16x16x64_i8 v[112:115], v[172:175], v[190:193], v[112:115]
	v_mfma_i32_16x16x64_i8 v[100:103], v[164:167], v[198:201], v[100:103]
	v_mfma_i32_16x16x64_i8 v[96:99], v[172:175], v[198:201], v[96:99]
	v_mfma_i32_16x16x64_i8 v[84:87], v[164:167], v[206:209], v[84:87]
	v_mfma_i32_16x16x64_i8 v[80:83], v[172:175], v[206:209], v[80:83]
	v_mfma_i32_16x16x64_i8 v[68:71], v[164:167], v[214:217], v[68:71]
	v_mfma_i32_16x16x64_i8 v[64:67], v[172:175], v[214:217], v[64:67]
	s_barrier
	ds_read_b128 v[186:189], v182 offset:16384
	ds_read_b128 v[190:193], v182 offset:17408
	ds_read_b128 v[194:197], v182 offset:18432
	ds_read_b128 v[198:201], v182 offset:19456
	ds_read_b128 v[202:205], v182 offset:20480
	ds_read_b128 v[206:209], v182 offset:21504
	ds_read_b128 v[210:213], v182 offset:22528
	ds_read_b128 v[214:217], v182 offset:23552
	s_add_i32 s59, s52, s42
	v_lshl_add_u64 v[218:219], s[34:35], 0, v[130:131]
	s_mov_b32 m0, s59
	s_nop 0
	global_load_lds_dwordx4 v[218:219], off
	s_add_i32 m0, s59, 0x2000
	s_add_u32 s60, s34, 0x80000
	v_lshl_add_u64 v[220:221], s[34:35], 0, v[134:135]
	s_addc_u32 s61, s35, 0
	s_add_i32 s59, s53, s42
	global_load_lds_dwordx4 v[220:221], off
	v_lshl_add_u64 v[222:223], s[60:61], 0, v[130:131]
	s_mov_b32 m0, s59
	v_lshl_add_u64 v[224:225], s[36:37], 0, v[132:133]
	global_load_lds_dwordx4 v[222:223], off
	v_lshl_add_u64 v[222:223], s[60:61], 0, v[134:135]
	s_add_i32 m0, s59, 0x2000
	s_nop 0
	global_load_lds_dwordx4 v[222:223], off
	v_lshl_add_u64 v[222:223], s[36:37], 0, v[128:129]
	s_mov_b32 m0, s43
	s_nop 0
	global_load_lds_dwordx4 v[222:223], off
	s_mov_b32 m0, s44
	s_nop 0
	global_load_lds_dwordx4 v[224:225], off
	s_waitcnt vmcnt(8)
	s_waitcnt lgkmcnt(0)
	s_barrier
	s_waitcnt lgkmcnt(0)
	v_mfma_i32_16x16x64_i8 v[60:63], v[144:147], v[186:189], v[60:63]
	v_mfma_i32_16x16x64_i8 v[56:59], v[152:155], v[186:189], v[56:59]
	v_mfma_i32_16x16x64_i8 v[44:47], v[144:147], v[194:197], v[44:47]
	v_mfma_i32_16x16x64_i8 v[40:43], v[152:155], v[194:197], v[40:43]
	v_mfma_i32_16x16x64_i8 v[28:31], v[144:147], v[202:205], v[28:31]
	v_mfma_i32_16x16x64_i8 v[24:27], v[152:155], v[202:205], v[24:27]
	v_mfma_i32_16x16x64_i8 v[12:15], v[144:147], v[210:213], v[12:15]
	v_mfma_i32_16x16x64_i8 v[8:11], v[152:155], v[210:213], v[8:11]
	v_mfma_i32_16x16x64_i8 v[60:63], v[148:151], v[190:193], v[60:63]
	v_mfma_i32_16x16x64_i8 v[56:59], v[156:159], v[190:193], v[56:59]
	v_mfma_i32_16x16x64_i8 v[44:47], v[148:151], v[198:201], v[44:47]
	v_mfma_i32_16x16x64_i8 v[40:43], v[156:159], v[198:201], v[40:43]
	v_mfma_i32_16x16x64_i8 v[28:31], v[148:151], v[206:209], v[28:31]
	v_mfma_i32_16x16x64_i8 v[24:27], v[156:159], v[206:209], v[24:27]
	v_mfma_i32_16x16x64_i8 v[12:15], v[148:151], v[214:217], v[12:15]
	v_mfma_i32_16x16x64_i8 v[8:11], v[156:159], v[214:217], v[8:11]
	v_mfma_i32_16x16x64_i8 v[52:55], v[160:163], v[186:189], v[52:55]
	v_mfma_i32_16x16x64_i8 v[48:51], v[168:171], v[186:189], v[48:51]
	v_mfma_i32_16x16x64_i8 v[36:39], v[160:163], v[194:197], v[36:39]
	v_mfma_i32_16x16x64_i8 v[32:35], v[168:171], v[194:197], v[32:35]
	v_mfma_i32_16x16x64_i8 v[20:23], v[160:163], v[202:205], v[20:23]
	v_mfma_i32_16x16x64_i8 v[16:19], v[168:171], v[202:205], v[16:19]
	v_mfma_i32_16x16x64_i8 v[4:7], v[160:163], v[210:213], v[4:7]
	v_mfma_i32_16x16x64_i8 v[0:3], v[168:171], v[210:213], v[0:3]
	v_mfma_i32_16x16x64_i8 v[52:55], v[164:167], v[190:193], v[52:55]
	v_mfma_i32_16x16x64_i8 v[48:51], v[172:175], v[190:193], v[48:51]
	v_mfma_i32_16x16x64_i8 v[36:39], v[164:167], v[198:201], v[36:39]
	v_mfma_i32_16x16x64_i8 v[32:35], v[172:175], v[198:201], v[32:35]
	v_mfma_i32_16x16x64_i8 v[20:23], v[164:167], v[206:209], v[20:23]
	v_mfma_i32_16x16x64_i8 v[16:19], v[172:175], v[206:209], v[16:19]
	v_mfma_i32_16x16x64_i8 v[4:7], v[164:167], v[214:217], v[4:7]
	v_mfma_i32_16x16x64_i8 v[0:3], v[172:175], v[214:217], v[0:3]
	s_barrier
	ds_read_b128 v[186:189], v182 offset:32768
	ds_read_b128 v[190:193], v182 offset:33792
	ds_read_b128 v[194:197], v182 offset:34816
	ds_read_b128 v[198:201], v182 offset:35840
	ds_read_b128 v[202:205], v182 offset:36864
	ds_read_b128 v[206:209], v182 offset:37888
	ds_read_b128 v[210:213], v182 offset:38912
	ds_read_b128 v[214:217], v182 offset:39936
	s_add_i32 s59, 0, 0x18000
	s_add_i32 s60, 0, 0x1c000
	v_add_u32_e32 v156, s59, v178
	v_add_u32_e32 v172, s60, v178
	ds_read_b128 v[144:147], v156
	ds_read_b128 v[148:151], v156 offset:1024
	ds_read_b128 v[152:155], v156 offset:2048
	ds_read_b128 v[156:159], v156 offset:3072
	ds_read_b128 v[160:163], v172
	ds_read_b128 v[164:167], v172 offset:1024
	ds_read_b128 v[168:171], v172 offset:2048
	ds_read_b128 v[172:175], v172 offset:3072
	s_add_u32 s36, s36, 0x80000
	s_addc_u32 s37, s37, 0
	s_mov_b32 m0, s45
	v_lshl_add_u64 v[226:227], s[36:37], 0, v[128:129]
	global_load_lds_dwordx4 v[226:227], off
	v_lshl_add_u64 v[226:227], s[36:37], 0, v[132:133]
	s_mov_b32 m0, s46
	s_nop 0
	global_load_lds_dwordx4 v[226:227], off
	s_waitcnt vmcnt(8)
	s_waitcnt lgkmcnt(0)
	s_barrier
	s_waitcnt lgkmcnt(0)
	v_mfma_i32_16x16x64_i8 v[124:127], v[144:147], v[186:189], v[124:127]
	v_mfma_i32_16x16x64_i8 v[120:123], v[152:155], v[186:189], v[120:123]
	v_mfma_i32_16x16x64_i8 v[108:111], v[144:147], v[194:197], v[108:111]
	v_mfma_i32_16x16x64_i8 v[104:107], v[152:155], v[194:197], v[104:107]
	v_mfma_i32_16x16x64_i8 v[92:95], v[144:147], v[202:205], v[92:95]
	v_mfma_i32_16x16x64_i8 v[88:91], v[152:155], v[202:205], v[88:91]
	v_mfma_i32_16x16x64_i8 v[76:79], v[144:147], v[210:213], v[76:79]
	v_mfma_i32_16x16x64_i8 v[72:75], v[152:155], v[210:213], v[72:75]
	v_mfma_i32_16x16x64_i8 v[124:127], v[148:151], v[190:193], v[124:127]
	v_mfma_i32_16x16x64_i8 v[120:123], v[156:159], v[190:193], v[120:123]
	v_mfma_i32_16x16x64_i8 v[108:111], v[148:151], v[198:201], v[108:111]
	v_mfma_i32_16x16x64_i8 v[104:107], v[156:159], v[198:201], v[104:107]
	v_mfma_i32_16x16x64_i8 v[92:95], v[148:151], v[206:209], v[92:95]
	v_mfma_i32_16x16x64_i8 v[88:91], v[156:159], v[206:209], v[88:91]
	v_mfma_i32_16x16x64_i8 v[76:79], v[148:151], v[214:217], v[76:79]
	v_mfma_i32_16x16x64_i8 v[72:75], v[156:159], v[214:217], v[72:75]
	v_mfma_i32_16x16x64_i8 v[116:119], v[160:163], v[186:189], v[116:119]
	v_mfma_i32_16x16x64_i8 v[112:115], v[168:171], v[186:189], v[112:115]
	v_mfma_i32_16x16x64_i8 v[100:103], v[160:163], v[194:197], v[100:103]
	v_mfma_i32_16x16x64_i8 v[96:99], v[168:171], v[194:197], v[96:99]
	v_mfma_i32_16x16x64_i8 v[84:87], v[160:163], v[202:205], v[84:87]
	v_mfma_i32_16x16x64_i8 v[80:83], v[168:171], v[202:205], v[80:83]
	v_mfma_i32_16x16x64_i8 v[68:71], v[160:163], v[210:213], v[68:71]
	v_mfma_i32_16x16x64_i8 v[64:67], v[168:171], v[210:213], v[64:67]
	v_mfma_i32_16x16x64_i8 v[116:119], v[164:167], v[190:193], v[116:119]
	v_mfma_i32_16x16x64_i8 v[112:115], v[172:175], v[190:193], v[112:115]
	v_mfma_i32_16x16x64_i8 v[100:103], v[164:167], v[198:201], v[100:103]
	v_mfma_i32_16x16x64_i8 v[96:99], v[172:175], v[198:201], v[96:99]
	v_mfma_i32_16x16x64_i8 v[84:87], v[164:167], v[206:209], v[84:87]
	v_mfma_i32_16x16x64_i8 v[80:83], v[172:175], v[206:209], v[80:83]
	v_mfma_i32_16x16x64_i8 v[68:71], v[164:167], v[214:217], v[68:71]
	v_mfma_i32_16x16x64_i8 v[64:67], v[172:175], v[214:217], v[64:67]
	s_barrier
	ds_read_b128 v[186:189], v182 offset:49152
	ds_read_b128 v[190:193], v182 offset:50176
	ds_read_b128 v[194:197], v182 offset:51200
	ds_read_b128 v[198:201], v182 offset:52224
	ds_read_b128 v[202:205], v182 offset:53248
	ds_read_b128 v[206:209], v182 offset:54272
	ds_read_b128 v[210:213], v182 offset:55296
	ds_read_b128 v[214:217], v182 offset:56320
	s_add_i32 s36, s59, s42
	v_lshl_add_u64 v[218:219], v[218:219], 0, s[16:17]
	s_mov_b32 m0, s36
	s_nop 0
	global_load_lds_dwordx4 v[218:219], off
	s_add_i32 m0, s36, 0x2000
	s_add_u32 s34, s34, 0x80080
	v_lshl_add_u64 v[218:219], v[220:221], 0, s[16:17]
	s_addc_u32 s35, s35, 0
	s_add_i32 s36, s60, s42
	global_load_lds_dwordx4 v[218:219], off
	v_lshl_add_u64 v[218:219], s[34:35], 0, v[130:131]
	s_mov_b32 m0, s36
	s_nop 0
	global_load_lds_dwordx4 v[218:219], off
	v_lshl_add_u64 v[218:219], s[34:35], 0, v[134:135]
	s_add_i32 m0, s36, 0x2000
	s_nop 0
	global_load_lds_dwordx4 v[218:219], off
	v_lshl_add_u64 v[218:219], v[222:223], 0, s[16:17]
	s_mov_b32 m0, s48
	s_nop 0
	global_load_lds_dwordx4 v[218:219], off
	v_lshl_add_u64 v[218:219], v[224:225], 0, s[16:17]
	s_mov_b32 m0, s49
	s_nop 0
	global_load_lds_dwordx4 v[218:219], off
	s_waitcnt vmcnt(8)
	s_waitcnt lgkmcnt(0)
	s_barrier
	s_waitcnt lgkmcnt(0)
	v_mfma_i32_16x16x64_i8 v[60:63], v[144:147], v[186:189], v[60:63]
	v_mfma_i32_16x16x64_i8 v[56:59], v[152:155], v[186:189], v[56:59]
	v_mfma_i32_16x16x64_i8 v[44:47], v[144:147], v[194:197], v[44:47]
	v_mfma_i32_16x16x64_i8 v[40:43], v[152:155], v[194:197], v[40:43]
	v_mfma_i32_16x16x64_i8 v[28:31], v[144:147], v[202:205], v[28:31]
	v_mfma_i32_16x16x64_i8 v[24:27], v[152:155], v[202:205], v[24:27]
	v_mfma_i32_16x16x64_i8 v[12:15], v[144:147], v[210:213], v[12:15]
	v_mfma_i32_16x16x64_i8 v[8:11], v[152:155], v[210:213], v[8:11]
	v_mfma_i32_16x16x64_i8 v[60:63], v[148:151], v[190:193], v[60:63]
	v_mfma_i32_16x16x64_i8 v[56:59], v[156:159], v[190:193], v[56:59]
	v_mfma_i32_16x16x64_i8 v[44:47], v[148:151], v[198:201], v[44:47]
	v_mfma_i32_16x16x64_i8 v[40:43], v[156:159], v[198:201], v[40:43]
	v_mfma_i32_16x16x64_i8 v[28:31], v[148:151], v[206:209], v[28:31]
	v_mfma_i32_16x16x64_i8 v[24:27], v[156:159], v[206:209], v[24:27]
	v_mfma_i32_16x16x64_i8 v[12:15], v[148:151], v[214:217], v[12:15]
	v_mfma_i32_16x16x64_i8 v[8:11], v[156:159], v[214:217], v[8:11]
	v_mfma_i32_16x16x64_i8 v[52:55], v[160:163], v[186:189], v[52:55]
	v_mfma_i32_16x16x64_i8 v[48:51], v[168:171], v[186:189], v[48:51]
	v_mfma_i32_16x16x64_i8 v[36:39], v[160:163], v[194:197], v[36:39]
	v_mfma_i32_16x16x64_i8 v[32:35], v[168:171], v[194:197], v[32:35]
	v_mfma_i32_16x16x64_i8 v[20:23], v[160:163], v[202:205], v[20:23]
	v_mfma_i32_16x16x64_i8 v[16:19], v[168:171], v[202:205], v[16:19]
	v_mfma_i32_16x16x64_i8 v[4:7], v[160:163], v[210:213], v[4:7]
	v_mfma_i32_16x16x64_i8 v[0:3], v[168:171], v[210:213], v[0:3]
	v_mfma_i32_16x16x64_i8 v[52:55], v[164:167], v[190:193], v[52:55]
	v_mfma_i32_16x16x64_i8 v[48:51], v[172:175], v[190:193], v[48:51]
	v_mfma_i32_16x16x64_i8 v[36:39], v[164:167], v[198:201], v[36:39]
	v_mfma_i32_16x16x64_i8 v[32:35], v[172:175], v[198:201], v[32:35]
	v_mfma_i32_16x16x64_i8 v[20:23], v[164:167], v[206:209], v[20:23]
	v_mfma_i32_16x16x64_i8 v[16:19], v[172:175], v[206:209], v[16:19]
	v_mfma_i32_16x16x64_i8 v[4:7], v[164:167], v[214:217], v[4:7]
	v_mfma_i32_16x16x64_i8 v[0:3], v[172:175], v[214:217], v[0:3]
	s_barrier
	s_add_i32 s58, s58, 2
	s_add_u32 s33, s33, 0x100
	s_addc_u32 s57, s57, 0
	s_add_u32 s30, s30, 0x100
	s_addc_u32 s31, s31, 0
	s_cmp_gt_u32 s58, 29
	s_cbranch_scc0 .LBB0_1356
	s_setprio 0
	s_and_b64 vcc, exec, s[18:19]
	s_cbranch_vccz .LBB0_1359
	s_barrier

.Lsp_skip9:
.LBB0_1841:
	ds_read_b128 v[186:189], v183
	ds_read_b128 v[190:193], v183 offset:1024
	ds_read_b128 v[194:197], v183 offset:2048
	ds_read_b128 v[198:201], v183 offset:3072
	ds_read_b128 v[202:205], v183 offset:4096
	ds_read_b128 v[206:209], v183 offset:5120
	ds_read_b128 v[210:213], v183 offset:6144
	ds_read_b128 v[214:217], v183 offset:7168
	v_add_u32_e32 v140, s47, v181
	v_add_u32_e32 v174, s48, v181
	ds_read_b128 v[124:127], v140
	ds_read_b128 v[132:135], v140 offset:1024
	ds_read_b128 v[136:139], v140 offset:2048
	ds_read_b128 v[140:143], v140 offset:3072
	ds_read_b128 v[162:165], v174
	ds_read_b128 v[166:169], v174 offset:1024
	ds_read_b128 v[170:173], v174 offset:2048
	ds_read_b128 v[174:177], v174 offset:3072
	s_add_u32 s30, s28, 0xffe00080
	s_addc_u32 s31, s29, -1
	s_cmpk_eq_i32 s53, 0x7c
	s_cselect_b32 s35, s19, s31
	s_cselect_b32 s34, s25, s30
	s_cselect_b32 s31, s17, s52
	s_cselect_b32 s30, s50, s51
	v_lshl_add_u64 v[178:179], s[28:29], 0, v[156:157]
	s_add_i32 m0, s27, 0xc000
	s_nop 0
	global_load_lds_dwordx4 v[178:179], off
	v_lshl_add_u64 v[178:179], s[28:29], 0, v[154:155]
	s_add_i32 m0, s27, 0xe000
	s_nop 0
	global_load_lds_dwordx4 v[178:179], off
	s_waitcnt vmcnt(8)
	s_waitcnt lgkmcnt(0)
	s_barrier
	s_waitcnt lgkmcnt(0)
	v_mfma_i32_16x16x64_i8 v[116:119], v[124:127], v[186:189], v[116:119]
	v_mfma_i32_16x16x64_i8 v[104:107], v[136:139], v[186:189], v[104:107]
	v_mfma_i32_16x16x64_i8 v[112:115], v[124:127], v[194:197], v[112:115]
	v_mfma_i32_16x16x64_i8 v[108:111], v[136:139], v[194:197], v[108:111]
	v_mfma_i32_16x16x64_i8 v[92:95], v[124:127], v[202:205], v[92:95]
	v_mfma_i32_16x16x64_i8 v[88:91], v[136:139], v[202:205], v[88:91]
	v_mfma_i32_16x16x64_i8 v[76:79], v[124:127], v[210:213], v[76:79]
	v_mfma_i32_16x16x64_i8 v[72:75], v[136:139], v[210:213], v[72:75]
	v_mfma_i32_16x16x64_i8 v[116:119], v[132:135], v[190:193], v[116:119]
	v_mfma_i32_16x16x64_i8 v[104:107], v[140:143], v[190:193], v[104:107]
	v_mfma_i32_16x16x64_i8 v[112:115], v[132:135], v[198:201], v[112:115]
	v_mfma_i32_16x16x64_i8 v[108:111], v[140:143], v[198:201], v[108:111]
	v_mfma_i32_16x16x64_i8 v[92:95], v[132:135], v[206:209], v[92:95]
	v_mfma_i32_16x16x64_i8 v[88:91], v[140:143], v[206:209], v[88:91]
	v_mfma_i32_16x16x64_i8 v[76:79], v[132:135], v[214:217], v[76:79]
	v_mfma_i32_16x16x64_i8 v[72:75], v[140:143], v[214:217], v[72:75]
	v_mfma_i32_16x16x64_i8 v[128:131], v[162:165], v[186:189], v[128:131]
	v_mfma_i32_16x16x64_i8 v[120:123], v[170:173], v[186:189], v[120:123]
	v_mfma_i32_16x16x64_i8 v[100:103], v[162:165], v[194:197], v[100:103]
	v_mfma_i32_16x16x64_i8 v[96:99], v[170:173], v[194:197], v[96:99]
	v_mfma_i32_16x16x64_i8 v[84:87], v[162:165], v[202:205], v[84:87]
	v_mfma_i32_16x16x64_i8 v[80:83], v[170:173], v[202:205], v[80:83]
	v_mfma_i32_16x16x64_i8 v[68:71], v[162:165], v[210:213], v[68:71]
	v_mfma_i32_16x16x64_i8 v[64:67], v[170:173], v[210:213], v[64:67]
	v_mfma_i32_16x16x64_i8 v[128:131], v[166:169], v[190:193], v[128:131]
	v_mfma_i32_16x16x64_i8 v[120:123], v[174:177], v[190:193], v[120:123]
	v_mfma_i32_16x16x64_i8 v[100:103], v[166:169], v[198:201], v[100:103]
	v_mfma_i32_16x16x64_i8 v[96:99], v[174:177], v[198:201], v[96:99]
	v_mfma_i32_16x16x64_i8 v[84:87], v[166:169], v[206:209], v[84:87]
	v_mfma_i32_16x16x64_i8 v[80:83], v[174:177], v[206:209], v[80:83]
	v_mfma_i32_16x16x64_i8 v[68:71], v[166:169], v[214:217], v[68:71]
	v_mfma_i32_16x16x64_i8 v[64:67], v[174:177], v[214:217], v[64:67]
	s_barrier
	ds_read_b128 v[186:189], v183 offset:16384
	ds_read_b128 v[190:193], v183 offset:17408
	ds_read_b128 v[194:197], v183 offset:18432
	ds_read_b128 v[198:201], v183 offset:19456
	ds_read_b128 v[202:205], v183 offset:20480
	ds_read_b128 v[206:209], v183 offset:21504
	ds_read_b128 v[210:213], v183 offset:22528
	ds_read_b128 v[214:217], v183 offset:23552
	s_add_i32 s54, s47, s38
	v_lshl_add_u64 v[178:179], s[30:31], 0, v[146:147]
	s_mov_b32 m0, s54
	s_nop 0
	global_load_lds_dwordx4 v[178:179], off
	s_add_i32 m0, s54, 0x2000
	s_add_u32 s54, s30, 0x200000
	v_lshl_add_u64 v[218:219], s[30:31], 0, v[150:151]
	s_addc_u32 s55, s31, 0
	s_add_i32 s56, s48, s38
	global_load_lds_dwordx4 v[218:219], off
	v_lshl_add_u64 v[220:221], s[54:55], 0, v[146:147]
	s_mov_b32 m0, s56
	v_lshl_add_u64 v[222:223], s[34:35], 0, v[148:149]
	global_load_lds_dwordx4 v[220:221], off
	v_lshl_add_u64 v[220:221], s[54:55], 0, v[150:151]
	s_add_i32 m0, s56, 0x2000
	s_nop 0
	global_load_lds_dwordx4 v[220:221], off
	v_lshl_add_u64 v[220:221], s[34:35], 0, v[144:145]
	s_mov_b32 m0, s27
	s_nop 0
	global_load_lds_dwordx4 v[220:221], off
	s_mov_b32 m0, s39
	s_nop 0
	global_load_lds_dwordx4 v[222:223], off
	s_waitcnt vmcnt(8)
	s_waitcnt lgkmcnt(0)
	s_barrier
	s_waitcnt lgkmcnt(0)
	v_mfma_i32_16x16x64_i8 v[60:63], v[124:127], v[186:189], v[60:63]
	v_mfma_i32_16x16x64_i8 v[56:59], v[136:139], v[186:189], v[56:59]
	v_mfma_i32_16x16x64_i8 v[44:47], v[124:127], v[194:197], v[44:47]
	v_mfma_i32_16x16x64_i8 v[40:43], v[136:139], v[194:197], v[40:43]
	v_mfma_i32_16x16x64_i8 v[28:31], v[124:127], v[202:205], v[28:31]
	v_mfma_i32_16x16x64_i8 v[24:27], v[136:139], v[202:205], v[24:27]
	v_mfma_i32_16x16x64_i8 v[12:15], v[124:127], v[210:213], v[12:15]
	v_mfma_i32_16x16x64_i8 v[8:11], v[136:139], v[210:213], v[8:11]
	v_mfma_i32_16x16x64_i8 v[60:63], v[132:135], v[190:193], v[60:63]
	v_mfma_i32_16x16x64_i8 v[56:59], v[140:143], v[190:193], v[56:59]
	v_mfma_i32_16x16x64_i8 v[44:47], v[132:135], v[198:201], v[44:47]
	v_mfma_i32_16x16x64_i8 v[40:43], v[140:143], v[198:201], v[40:43]
	v_mfma_i32_16x16x64_i8 v[28:31], v[132:135], v[206:209], v[28:31]
	v_mfma_i32_16x16x64_i8 v[24:27], v[140:143], v[206:209], v[24:27]
	v_mfma_i32_16x16x64_i8 v[12:15], v[132:135], v[214:217], v[12:15]
	v_mfma_i32_16x16x64_i8 v[8:11], v[140:143], v[214:217], v[8:11]
	v_mfma_i32_16x16x64_i8 v[52:55], v[162:165], v[186:189], v[52:55]
	v_mfma_i32_16x16x64_i8 v[48:51], v[170:173], v[186:189], v[48:51]
	v_mfma_i32_16x16x64_i8 v[36:39], v[162:165], v[194:197], v[36:39]
	v_mfma_i32_16x16x64_i8 v[32:35], v[170:173], v[194:197], v[32:35]
	v_mfma_i32_16x16x64_i8 v[20:23], v[162:165], v[202:205], v[20:23]
	v_mfma_i32_16x16x64_i8 v[16:19], v[170:173], v[202:205], v[16:19]
	v_mfma_i32_16x16x64_i8 v[4:7], v[162:165], v[210:213], v[4:7]
	v_mfma_i32_16x16x64_i8 v[0:3], v[170:173], v[210:213], v[0:3]
	v_mfma_i32_16x16x64_i8 v[52:55], v[166:169], v[190:193], v[52:55]
	v_mfma_i32_16x16x64_i8 v[48:51], v[174:177], v[190:193], v[48:51]
	v_mfma_i32_16x16x64_i8 v[36:39], v[166:169], v[198:201], v[36:39]
	v_mfma_i32_16x16x64_i8 v[32:35], v[174:177], v[198:201], v[32:35]
	v_mfma_i32_16x16x64_i8 v[20:23], v[166:169], v[206:209], v[20:23]
	v_mfma_i32_16x16x64_i8 v[16:19], v[174:177], v[206:209], v[16:19]
	v_mfma_i32_16x16x64_i8 v[4:7], v[166:169], v[214:217], v[4:7]
	v_mfma_i32_16x16x64_i8 v[0:3], v[174:177], v[214:217], v[0:3]
	s_barrier
	ds_read_b128 v[186:189], v183 offset:32768
	ds_read_b128 v[190:193], v183 offset:33792
	ds_read_b128 v[194:197], v183 offset:34816
	ds_read_b128 v[198:201], v183 offset:35840
	ds_read_b128 v[202:205], v183 offset:36864
	ds_read_b128 v[206:209], v183 offset:37888
	ds_read_b128 v[210:213], v183 offset:38912
	ds_read_b128 v[214:217], v183 offset:39936
	s_add_i32 s54, 0, 0x18000
	s_add_i32 s55, 0, 0x1c000
	v_add_u32_e32 v140, s54, v181
	v_add_u32_e32 v174, s55, v181
	ds_read_b128 v[124:127], v140
	ds_read_b128 v[132:135], v140 offset:1024
	ds_read_b128 v[136:139], v140 offset:2048
	ds_read_b128 v[140:143], v140 offset:3072
	ds_read_b128 v[162:165], v174
	ds_read_b128 v[166:169], v174 offset:1024
	ds_read_b128 v[170:173], v174 offset:2048
	ds_read_b128 v[174:177], v174 offset:3072
	s_add_u32 s34, s34, 0x200000
	s_addc_u32 s35, s35, 0
	s_mov_b32 m0, s40
	v_lshl_add_u64 v[224:225], s[34:35], 0, v[144:145]
	global_load_lds_dwordx4 v[224:225], off
	v_lshl_add_u64 v[224:225], s[34:35], 0, v[148:149]
	s_mov_b32 m0, s41
	s_nop 0
	global_load_lds_dwordx4 v[224:225], off
	s_waitcnt vmcnt(8)
	s_waitcnt lgkmcnt(0)
	s_barrier
	s_waitcnt lgkmcnt(0)
	v_mfma_i32_16x16x64_i8 v[116:119], v[124:127], v[186:189], v[116:119]
	v_mfma_i32_16x16x64_i8 v[104:107], v[136:139], v[186:189], v[104:107]
	v_mfma_i32_16x16x64_i8 v[112:115], v[124:127], v[194:197], v[112:115]
	v_mfma_i32_16x16x64_i8 v[108:111], v[136:139], v[194:197], v[108:111]
	v_mfma_i32_16x16x64_i8 v[92:95], v[124:127], v[202:205], v[92:95]
	v_mfma_i32_16x16x64_i8 v[88:91], v[136:139], v[202:205], v[88:91]
	v_mfma_i32_16x16x64_i8 v[76:79], v[124:127], v[210:213], v[76:79]
	v_mfma_i32_16x16x64_i8 v[72:75], v[136:139], v[210:213], v[72:75]
	v_mfma_i32_16x16x64_i8 v[116:119], v[132:135], v[190:193], v[116:119]
	v_mfma_i32_16x16x64_i8 v[104:107], v[140:143], v[190:193], v[104:107]
	v_mfma_i32_16x16x64_i8 v[112:115], v[132:135], v[198:201], v[112:115]
	v_mfma_i32_16x16x64_i8 v[108:111], v[140:143], v[198:201], v[108:111]
	v_mfma_i32_16x16x64_i8 v[92:95], v[132:135], v[206:209], v[92:95]
	v_mfma_i32_16x16x64_i8 v[88:91], v[140:143], v[206:209], v[88:91]
	v_mfma_i32_16x16x64_i8 v[76:79], v[132:135], v[214:217], v[76:79]
	v_mfma_i32_16x16x64_i8 v[72:75], v[140:143], v[214:217], v[72:75]
	v_mfma_i32_16x16x64_i8 v[128:131], v[162:165], v[186:189], v[128:131]
	v_mfma_i32_16x16x64_i8 v[120:123], v[170:173], v[186:189], v[120:123]
	v_mfma_i32_16x16x64_i8 v[100:103], v[162:165], v[194:197], v[100:103]
	v_mfma_i32_16x16x64_i8 v[96:99], v[170:173], v[194:197], v[96:99]
	v_mfma_i32_16x16x64_i8 v[84:87], v[162:165], v[202:205], v[84:87]
	v_mfma_i32_16x16x64_i8 v[80:83], v[170:173], v[202:205], v[80:83]
	v_mfma_i32_16x16x64_i8 v[68:71], v[162:165], v[210:213], v[68:71]
	v_mfma_i32_16x16x64_i8 v[64:67], v[170:173], v[210:213], v[64:67]
	v_mfma_i32_16x16x64_i8 v[128:131], v[166:169], v[190:193], v[128:131]
	v_mfma_i32_16x16x64_i8 v[120:123], v[174:177], v[190:193], v[120:123]
	v_mfma_i32_16x16x64_i8 v[100:103], v[166:169], v[198:201], v[100:103]
	v_mfma_i32_16x16x64_i8 v[96:99], v[174:177], v[198:201], v[96:99]
	v_mfma_i32_16x16x64_i8 v[84:87], v[166:169], v[206:209], v[84:87]
	v_mfma_i32_16x16x64_i8 v[80:83], v[174:177], v[206:209], v[80:83]
	v_mfma_i32_16x16x64_i8 v[68:71], v[166:169], v[214:217], v[68:71]
	v_mfma_i32_16x16x64_i8 v[64:67], v[174:177], v[214:217], v[64:67]
	s_barrier
	ds_read_b128 v[186:189], v183 offset:49152
	ds_read_b128 v[190:193], v183 offset:50176
	ds_read_b128 v[194:197], v183 offset:51200
	ds_read_b128 v[198:201], v183 offset:52224
	ds_read_b128 v[202:205], v183 offset:53248
	ds_read_b128 v[206:209], v183 offset:54272
	ds_read_b128 v[210:213], v183 offset:55296
	ds_read_b128 v[214:217], v183 offset:56320
	s_add_i32 s34, s54, s38
	v_lshl_add_u64 v[178:179], v[178:179], 0, s[10:11]
	s_mov_b32 m0, s34
	s_nop 0
	global_load_lds_dwordx4 v[178:179], off
	s_add_i32 m0, s34, 0x2000
	s_add_u32 s30, s30, 0x200080
	v_lshl_add_u64 v[178:179], v[218:219], 0, s[10:11]
	s_addc_u32 s31, s31, 0
	s_add_i32 s34, s55, s38
	global_load_lds_dwordx4 v[178:179], off
	v_lshl_add_u64 v[178:179], s[30:31], 0, v[146:147]
	s_mov_b32 m0, s34
	s_nop 0
	global_load_lds_dwordx4 v[178:179], off
	v_lshl_add_u64 v[178:179], s[30:31], 0, v[150:151]
	s_add_i32 m0, s34, 0x2000
	s_nop 0
	global_load_lds_dwordx4 v[178:179], off
	v_lshl_add_u64 v[178:179], v[220:221], 0, s[10:11]
	s_mov_b32 m0, s43
	s_nop 0
	global_load_lds_dwordx4 v[178:179], off
	v_lshl_add_u64 v[178:179], v[222:223], 0, s[10:11]
	s_mov_b32 m0, s44
	s_nop 0
	global_load_lds_dwordx4 v[178:179], off
	s_waitcnt vmcnt(8)
	s_waitcnt lgkmcnt(0)
	s_barrier
	s_waitcnt lgkmcnt(0)
	v_mfma_i32_16x16x64_i8 v[60:63], v[124:127], v[186:189], v[60:63]
	v_mfma_i32_16x16x64_i8 v[56:59], v[136:139], v[186:189], v[56:59]
	v_mfma_i32_16x16x64_i8 v[44:47], v[124:127], v[194:197], v[44:47]
	v_mfma_i32_16x16x64_i8 v[40:43], v[136:139], v[194:197], v[40:43]
	v_mfma_i32_16x16x64_i8 v[28:31], v[124:127], v[202:205], v[28:31]
	v_mfma_i32_16x16x64_i8 v[24:27], v[136:139], v[202:205], v[24:27]
	v_mfma_i32_16x16x64_i8 v[12:15], v[124:127], v[210:213], v[12:15]
	v_mfma_i32_16x16x64_i8 v[8:11], v[136:139], v[210:213], v[8:11]
	v_mfma_i32_16x16x64_i8 v[60:63], v[132:135], v[190:193], v[60:63]
	v_mfma_i32_16x16x64_i8 v[56:59], v[140:143], v[190:193], v[56:59]
	v_mfma_i32_16x16x64_i8 v[44:47], v[132:135], v[198:201], v[44:47]
	v_mfma_i32_16x16x64_i8 v[40:43], v[140:143], v[198:201], v[40:43]
	v_mfma_i32_16x16x64_i8 v[28:31], v[132:135], v[206:209], v[28:31]
	v_mfma_i32_16x16x64_i8 v[24:27], v[140:143], v[206:209], v[24:27]
	v_mfma_i32_16x16x64_i8 v[12:15], v[132:135], v[214:217], v[12:15]
	v_mfma_i32_16x16x64_i8 v[8:11], v[140:143], v[214:217], v[8:11]
	v_mfma_i32_16x16x64_i8 v[52:55], v[162:165], v[186:189], v[52:55]
	v_mfma_i32_16x16x64_i8 v[48:51], v[170:173], v[186:189], v[48:51]
	v_mfma_i32_16x16x64_i8 v[36:39], v[162:165], v[194:197], v[36:39]
	v_mfma_i32_16x16x64_i8 v[32:35], v[170:173], v[194:197], v[32:35]
	v_mfma_i32_16x16x64_i8 v[20:23], v[162:165], v[202:205], v[20:23]
	v_mfma_i32_16x16x64_i8 v[16:19], v[170:173], v[202:205], v[16:19]
	v_mfma_i32_16x16x64_i8 v[4:7], v[162:165], v[210:213], v[4:7]
	v_mfma_i32_16x16x64_i8 v[0:3], v[170:173], v[210:213], v[0:3]
	v_mfma_i32_16x16x64_i8 v[52:55], v[166:169], v[190:193], v[52:55]
	v_mfma_i32_16x16x64_i8 v[48:51], v[174:177], v[190:193], v[48:51]
	v_mfma_i32_16x16x64_i8 v[36:39], v[166:169], v[198:201], v[36:39]
	v_mfma_i32_16x16x64_i8 v[32:35], v[174:177], v[198:201], v[32:35]
	v_mfma_i32_16x16x64_i8 v[20:23], v[166:169], v[206:209], v[20:23]
	v_mfma_i32_16x16x64_i8 v[16:19], v[174:177], v[206:209], v[16:19]
	v_mfma_i32_16x16x64_i8 v[4:7], v[166:169], v[214:217], v[4:7]
	v_mfma_i32_16x16x64_i8 v[0:3], v[174:177], v[214:217], v[0:3]
	s_barrier
	s_add_i32 s53, s53, 2
	s_add_u32 s51, s51, 0x100
	s_addc_u32 s52, s52, 0
	s_add_u32 s28, s28, 0x100
	s_addc_u32 s29, s29, 0
	s_cmpk_gt_u32 s53, 0x7d
	s_cbranch_scc0 .LBB0_1841
	s_setprio 0
	s_and_b64 vcc, exec, s[12:13]
	s_cbranch_vccz .LBB0_1844
	s_barrier
